# peel first K-loop trip in all 5 GEMM phases (first MFMA per accumulator takes C=0) and drop the 128 per-unit zero-init v_movs
# speedup vs baseline: 1.0110x; 1.0110x over previous
.LBB0_22:
	ds_read2_b32 v[8:9], v13 offset1:8
	ds_read2_b32 v[28:29], v13 offset0:66 offset1:74
	ds_read2_b32 v[32:33], v13 offset0:33 offset1:41
	ds_read2_b32 v[36:37], v13 offset0:99 offset1:107
	ds_read2_b32 v[38:39], v13 offset0:132 offset1:140
	ds_read2_b32 v[40:41], v13 offset0:198 offset1:206
	ds_read2_b32 v[42:43], v13 offset0:165 offset1:173
	ds_read2_b32 v[44:45], v13 offset0:231 offset1:239
	s_lshl_b32 s20, s24, 6
	s_and_b32 s24, s58, 0x60
	s_and_b32 s20, s20, 0xffffff00
	s_or_b32 s21, s24, s21
	s_waitcnt lgkmcnt(5)
	v_mov_b32_e32 v26, v32
	s_waitcnt lgkmcnt(4)
	v_mov_b32_e32 v27, v36
	s_waitcnt lgkmcnt(3)
	v_mov_b32_e32 v46, v38
	s_waitcnt lgkmcnt(2)
	v_mov_b32_e32 v47, v40
	s_or_b32 s24, s21, s20
	v_mov_b32_e32 v24, v8
	v_mov_b32_e32 v25, v28
	v_pk_mul_f32 v[26:27], v[4:5], v[26:27]
	v_pk_mul_f32 v[46:47], v[2:3], v[46:47]
	s_waitcnt lgkmcnt(1)
	v_mov_b32_e32 v48, v42
	s_waitcnt lgkmcnt(0)
	v_mov_b32_e32 v49, v44
	s_and_b64 s[20:21], s[48:49], exec
	v_pk_mul_f32 v[24:25], v[6:7], v[24:25]
	v_pk_mul_f32 v[48:49], v[20:21], v[48:49]
	v_bfe_u32 v28, v27, 16, 1
	s_movk_i32 s31, 0x7fff
	v_bfe_u32 v38, v47, 16, 1
	s_cselect_b32 s20, s58, s24
	s_lshl_b64 s[24:25], s[56:57], 1
	v_bfe_u32 v8, v49, 16, 1
	v_bfe_u32 v32, v26, 16, 1
	v_add3_u32 v28, v27, v28, s31
	v_bfe_u32 v27, v25, 16, 1
	v_bfe_u32 v36, v46, 16, 1
	v_add3_u32 v38, v47, v38, s31
	s_add_u32 s24, s50, s24
	v_bfe_u32 v23, v48, 16, 1
	v_add3_u32 v32, v26, v32, s31
	v_add3_u32 v8, v49, v8, s31
	v_bfe_u32 v26, v24, 16, 1
	v_add3_u32 v36, v46, v36, s31
	v_add3_u32 v25, v25, v27, s31
	v_lshrrev_b32_e32 v27, 16, v38
	s_mov_b32 s33, 0xffff0000
	s_addc_u32 s25, s51, s25
	v_add3_u32 v23, v48, v23, s31
	v_add3_u32 v24, v24, v26, s31
	v_lshrrev_b32_e32 v26, 16, v36
	v_and_or_b32 v27, v8, s33, v27
	v_or_b32_e32 v8, s20, v11
	s_ashr_i32 s21, s20, 31
	v_lshl_add_u64 v[30:31], s[24:25], 0, v[34:35]
	v_lshrrev_b32_e32 v25, 16, v25
	v_and_or_b32 v26, v23, s33, v26
	v_mul_lo_u32 v23, s47, v8
	v_mad_u64_u32 v[46:47], s[24:25], s46, v8, 0
	s_mul_i32 s30, s46, s21
	v_lshrrev_b32_e32 v24, 16, v24
	v_and_or_b32 v25, v28, s33, v25
	v_add3_u32 v47, v47, s30, v23
	v_mov_b32_e32 v28, v9
	v_mov_b32_e32 v44, v43
	v_and_or_b32 v24, v32, s33, v24
	v_lshl_add_u64 v[46:47], v[46:47], 1, v[30:31]
	v_pk_mul_f32 v[8:9], v[6:7], v[28:29]
	v_mov_b32_e32 v36, v33
	v_pk_mul_f32 v[28:29], v[20:21], v[44:45]
	global_store_dwordx4 v[46:47], v[24:27], off
	v_mov_b32_e32 v40, v39
	v_bfe_u32 v23, v29, 16, 1
	v_pk_mul_f32 v[24:25], v[4:5], v[36:37]
	v_pk_mul_f32 v[26:27], v[2:3], v[40:41]
	v_bfe_u32 v32, v28, 16, 1
	v_bfe_u32 v36, v24, 16, 1
	v_add3_u32 v23, v29, v23, s31
	v_bfe_u32 v29, v8, 16, 1
	v_add3_u32 v24, v24, v36, s31
	v_add3_u32 v28, v28, v32, s31
	v_bfe_u32 v32, v9, 16, 1
	v_bfe_u32 v36, v27, 16, 1
	v_add3_u32 v8, v8, v29, s31
	v_bfe_u32 v33, v25, 16, 1
	v_add3_u32 v27, v27, v36, s31
	v_add3_u32 v9, v9, v32, s31
	v_lshrrev_b32_e32 v8, 16, v8
	v_add3_u32 v25, v25, v33, s31
	v_bfe_u32 v33, v26, 16, 1
	v_lshrrev_b32_e32 v9, 16, v9
	v_lshrrev_b32_e32 v27, 16, v27
	v_and_or_b32 v24, v24, s33, v8
	v_or_b32_e32 v8, s20, v15
	v_add3_u32 v26, v26, v33, s31
	v_and_or_b32 v27, v23, s33, v27
	v_and_or_b32 v25, v25, s33, v9
	v_mul_lo_u32 v23, s47, v8
	v_mad_u64_u32 v[8:9], s[24:25], s46, v8, 0
	v_lshrrev_b32_e32 v26, 16, v26
	v_add3_u32 v9, v9, s30, v23
	v_and_or_b32 v26, v28, s33, v26
	v_lshl_add_u64 v[8:9], v[8:9], 1, v[30:31]
	ds_read2_b32 v[28:29], v13 offset0:16 offset1:24
	ds_read2_b32 v[32:33], v13 offset0:82 offset1:90
	global_store_dwordx4 v[8:9], v[24:27], off
	ds_read2_b32 v[8:9], v13 offset0:49 offset1:57
	ds_read2_b32 v[36:37], v13 offset0:115 offset1:123
	ds_read2_b32 v[38:39], v13 offset0:148 offset1:156
	ds_read2_b32 v[40:41], v13 offset0:214 offset1:222
	ds_read2_b32 v[42:43], v13 offset0:181 offset1:189
	ds_read2_b32 v[44:45], v13 offset0:247 offset1:255
	s_waitcnt lgkmcnt(7)
	v_mov_b32_e32 v24, v28
	s_waitcnt lgkmcnt(5)
	v_mov_b32_e32 v26, v8
	s_waitcnt lgkmcnt(4)
	v_mov_b32_e32 v27, v36
	s_waitcnt lgkmcnt(3)
	v_mov_b32_e32 v46, v38
	s_waitcnt lgkmcnt(2)
	v_mov_b32_e32 v47, v40
	v_mov_b32_e32 v25, v32
	v_pk_mul_f32 v[26:27], v[4:5], v[26:27]
	v_pk_mul_f32 v[46:47], v[2:3], v[46:47]
	s_waitcnt lgkmcnt(1)
	v_mov_b32_e32 v48, v42
	s_waitcnt lgkmcnt(0)
	v_mov_b32_e32 v49, v44
	v_pk_mul_f32 v[24:25], v[6:7], v[24:25]
	v_pk_mul_f32 v[48:49], v[20:21], v[48:49]
	v_bfe_u32 v28, v27, 16, 1
	v_bfe_u32 v38, v47, 16, 1
	v_bfe_u32 v8, v49, 16, 1
	v_bfe_u32 v32, v26, 16, 1
	v_add3_u32 v28, v27, v28, s31
	v_bfe_u32 v27, v25, 16, 1
	v_bfe_u32 v36, v46, 16, 1
	v_add3_u32 v38, v47, v38, s31
	v_bfe_u32 v23, v48, 16, 1
	v_add3_u32 v32, v26, v32, s31
	v_add3_u32 v8, v49, v8, s31
	v_bfe_u32 v26, v24, 16, 1
	v_add3_u32 v36, v46, v36, s31
	v_add3_u32 v25, v25, v27, s31
	v_lshrrev_b32_e32 v27, 16, v38
	v_add3_u32 v23, v48, v23, s31
	v_add3_u32 v24, v24, v26, s31
	v_lshrrev_b32_e32 v26, 16, v36
	v_and_or_b32 v27, v8, s33, v27
	v_or_b32_e32 v8, s20, v17
	v_and_or_b32 v26, v23, s33, v26
	v_mul_lo_u32 v23, s47, v8
	v_mad_u64_u32 v[46:47], s[24:25], s46, v8, 0
	v_lshrrev_b32_e32 v24, 16, v24
	v_lshrrev_b32_e32 v25, 16, v25
	v_add3_u32 v47, v47, s30, v23
	v_mov_b32_e32 v36, v9
	v_mov_b32_e32 v44, v43
	v_and_or_b32 v25, v28, s33, v25
	v_and_or_b32 v24, v32, s33, v24
	v_lshl_add_u64 v[46:47], v[46:47], 1, v[30:31]
	v_mov_b32_e32 v32, v29
	v_pk_mul_f32 v[4:5], v[4:5], v[36:37]
	v_mov_b32_e32 v40, v39
	v_pk_mul_f32 v[8:9], v[20:21], v[44:45]
	global_store_dwordx4 v[46:47], v[24:27], off
	v_pk_mul_f32 v[6:7], v[6:7], v[32:33]
	v_pk_mul_f32 v[2:3], v[2:3], v[40:41]
	v_bfe_u32 v20, v9, 16, 1
	v_bfe_u32 v21, v8, 16, 1
	v_bfe_u32 v23, v5, 16, 1
	v_bfe_u32 v24, v4, 16, 1
	v_add3_u32 v24, v4, v24, s31
	v_add3_u32 v23, v5, v23, s31
	v_add3_u32 v4, v8, v21, s31
	v_add3_u32 v5, v9, v20, s31
	v_bfe_u32 v8, v6, 16, 1
	v_bfe_u32 v20, v2, 16, 1
	v_bfe_u32 v9, v7, 16, 1
	v_bfe_u32 v21, v3, 16, 1
	v_add3_u32 v2, v2, v20, s31
	v_add3_u32 v6, v6, v8, s31
	v_add3_u32 v3, v3, v21, s31
	v_add3_u32 v7, v7, v9, s31
	v_lshrrev_b32_e32 v6, 16, v6
	v_lshrrev_b32_e32 v2, 16, v2
	v_lshrrev_b32_e32 v7, 16, v7
	v_lshrrev_b32_e32 v3, 16, v3
	v_and_or_b32 v4, v4, s33, v2
	v_and_or_b32 v2, v24, s33, v6
	v_or_b32_e32 v6, s20, v22
	v_and_or_b32 v5, v5, s33, v3
	v_and_or_b32 v3, v23, s33, v7
	v_mul_lo_u32 v8, s47, v6
	v_mad_u64_u32 v[6:7], s[20:21], s46, v6, 0
	v_add3_u32 v7, v7, s30, v8
	v_lshl_add_u64 v[6:7], v[6:7], 1, v[30:31]
	global_store_dwordx4 v[6:7], v[2:5], off
	s_waitcnt lgkmcnt(0)
	v_readlane_b32 s52, v255, 28
	s_add_i32 s13, s13, s78
	v_readlane_b32 s30, v255, 32
	v_readlane_b32 s53, v255, 29
	s_cmp_lt_i32 s13, 0x8200
	v_readlane_b32 s31, v255, 33
	v_readlane_b32 s54, v255, 30
	v_readlane_b32 s55, v255, 31
	s_cbranch_scc0 .LBB0_58

.LBB0_161:
	s_ashr_i32 s23, s22, 31
	s_lshl_b64 s[8:9], s[22:23], 20
	v_readlane_b32 s20, v254, 38
	v_readlane_b32 s21, v254, 39
	s_add_u32 s8, s20, s8
	s_addc_u32 s9, s21, s9
	s_and_b64 s[20:21], s[40:41], exec
	s_cselect_b32 s13, s9, s43
	s_cselect_b32 s20, s8, s42
	s_ashr_i32 s19, s18, 31
	s_lshl_b64 s[28:29], s[18:19], 20
	v_readlane_b32 s30, v254, 22
	v_readlane_b32 s31, v254, 23
	s_add_u32 s28, s30, s28
	s_addc_u32 s29, s31, s29
	s_and_b64 s[30:31], s[40:41], exec
	s_cselect_b32 s19, s29, s45
	s_cselect_b32 s21, s28, s44
	s_add_u32 s42, s42, 0x80080
	s_addc_u32 s43, s43, 0
	s_add_u32 s23, s44, 0x100
	s_addc_u32 s25, s45, 0
	s_mov_b32 s30, -2
	v_readlane_b32 s52, v255, 20
	v_readlane_b32 s53, v255, 21
	v_readlane_b32 s72, v255, 22
	v_readlane_b32 s73, v255, 23
	s_mov_b64 s[74:75], 0x80
	s_add_u32 s31, s42, 0xfff80080
	s_addc_u32 s44, s43, -1
	s_add_i32 s47, 0, 0x10000
	s_cmp_eq_u32 s30, 28
	v_add_u32_e32 v34, s47, v1
	s_cselect_b32 s49, s13, s44
	s_cselect_b32 s48, s20, s31
	v_add_u32_e32 v140, s47, v141
	ds_read_b128 v[144:147], v34
	ds_read_b128 v[148:151], v140
	v_add_u32_e32 v34, s52, v1
	s_cselect_b32 s45, s19, s25
	s_cselect_b32 s44, s21, s23
	s_add_i32 s31, 0, 0x14000
	v_add_u32_e32 v140, s52, v141
	ds_read_b128 v[152:155], v34
	ds_read_b128 v[156:159], v140
	v_add_u32_e32 v34, s31, v1
	v_add_u32_e32 v140, s31, v141
	ds_read_b128 v[160:163], v34
	ds_read_b128 v[164:167], v140
	v_add_u32_e32 v34, s53, v1
	v_add_u32_e32 v140, s53, v141
	ds_read_b128 v[168:171], v34
	ds_read_b128 v[172:175], v140
	v_lshl_add_u64 v[212:213], s[42:43], 0, v[138:139]
	s_add_i32 m0, s34, 0xc000
	ds_read_b128 v[176:179], v142
	ds_read_b128 v[184:187], v142 offset:2048
	ds_read_b128 v[188:191], v143
	ds_read_b128 v[192:195], v143 offset:2048
	ds_read_b128 v[196:199], v142 offset:4096
	ds_read_b128 v[200:203], v142 offset:6144
	ds_read_b128 v[204:207], v143 offset:4096
	ds_read_b128 v[208:211], v143 offset:6144
	global_load_lds_dwordx4 v[212:213], off
	v_lshl_add_u64 v[212:213], s[42:43], 0, v[134:135]
	s_add_i32 m0, s34, 0xe000
	s_nop 0
	global_load_lds_dwordx4 v[212:213], off
	s_waitcnt vmcnt(8)
	s_waitcnt lgkmcnt(0)
	s_barrier
	s_setprio 1
	s_waitcnt lgkmcnt(0)
	v_mfma_f32_16x16x32_bf16 v[128:131], v[144:147], v[176:179], 0
	v_mfma_f32_16x16x32_bf16 v[124:127], v[152:155], v[176:179], 0
	v_mfma_f32_16x16x32_bf16 v[112:115], v[144:147], v[184:187], 0
	v_mfma_f32_16x16x32_bf16 v[108:111], v[152:155], v[184:187], 0
	v_mfma_f32_16x16x32_bf16 v[96:99], v[144:147], v[196:199], 0
	v_mfma_f32_16x16x32_bf16 v[92:95], v[152:155], v[196:199], 0
	v_mfma_f32_16x16x32_bf16 v[80:83], v[144:147], v[200:203], 0
	v_mfma_f32_16x16x32_bf16 v[76:79], v[152:155], v[200:203], 0
	v_mfma_f32_16x16x32_bf16 v[128:131], v[148:151], v[188:191], v[128:131]
	v_mfma_f32_16x16x32_bf16 v[124:127], v[156:159], v[188:191], v[124:127]
	v_mfma_f32_16x16x32_bf16 v[112:115], v[148:151], v[192:195], v[112:115]
	v_mfma_f32_16x16x32_bf16 v[108:111], v[156:159], v[192:195], v[108:111]
	v_mfma_f32_16x16x32_bf16 v[96:99], v[148:151], v[204:207], v[96:99]
	v_mfma_f32_16x16x32_bf16 v[92:95], v[156:159], v[204:207], v[92:95]
	v_mfma_f32_16x16x32_bf16 v[80:83], v[148:151], v[208:211], v[80:83]
	v_mfma_f32_16x16x32_bf16 v[76:79], v[156:159], v[208:211], v[76:79]
	s_setprio 0
	s_setprio 1
	v_mfma_f32_16x16x32_bf16 v[120:123], v[160:163], v[176:179], 0
	v_mfma_f32_16x16x32_bf16 v[116:119], v[168:171], v[176:179], 0
	v_mfma_f32_16x16x32_bf16 v[104:107], v[160:163], v[184:187], 0
	v_mfma_f32_16x16x32_bf16 v[100:103], v[168:171], v[184:187], 0
	v_mfma_f32_16x16x32_bf16 v[88:91], v[160:163], v[196:199], 0
	v_mfma_f32_16x16x32_bf16 v[84:87], v[168:171], v[196:199], 0
	v_mfma_f32_16x16x32_bf16 v[72:75], v[160:163], v[200:203], 0
	v_mfma_f32_16x16x32_bf16 v[68:71], v[168:171], v[200:203], 0
	v_mfma_f32_16x16x32_bf16 v[120:123], v[164:167], v[188:191], v[120:123]
	v_mfma_f32_16x16x32_bf16 v[116:119], v[172:175], v[188:191], v[116:119]
	v_mfma_f32_16x16x32_bf16 v[104:107], v[164:167], v[192:195], v[104:107]
	v_mfma_f32_16x16x32_bf16 v[100:103], v[172:175], v[192:195], v[100:103]
	v_mfma_f32_16x16x32_bf16 v[88:91], v[164:167], v[204:207], v[88:91]
	v_mfma_f32_16x16x32_bf16 v[84:87], v[172:175], v[204:207], v[84:87]
	v_mfma_f32_16x16x32_bf16 v[72:75], v[164:167], v[208:211], v[72:75]
	v_mfma_f32_16x16x32_bf16 v[68:71], v[172:175], v[208:211], v[68:71]
	s_setprio 0
	s_barrier
	s_add_i32 s47, s47, s33
	v_lshl_add_u64 v[212:213], s[44:45], 0, v[136:137]
	s_mov_b32 m0, s47
	ds_read_b128 v[176:179], v142 offset:16384
	ds_read_b128 v[184:187], v142 offset:18432
	ds_read_b128 v[188:191], v143 offset:16384
	ds_read_b128 v[192:195], v143 offset:18432
	ds_read_b128 v[196:199], v142 offset:20480
	ds_read_b128 v[200:203], v142 offset:22528
	ds_read_b128 v[204:207], v143 offset:20480
	ds_read_b128 v[208:211], v143 offset:22528
	global_load_lds_dwordx4 v[212:213], off
	s_add_i32 m0, s47, 0x2000
	s_add_u32 s50, s44, 0x80000
	v_lshl_add_u64 v[224:225], s[44:45], 0, v[132:133]
	s_addc_u32 s51, s45, 0
	s_add_i32 s31, s31, s33
	global_load_lds_dwordx4 v[224:225], off
	v_lshl_add_u64 v[226:227], s[50:51], 0, v[136:137]
	s_mov_b32 m0, s31
	v_lshl_add_u64 v[228:229], s[48:49], 0, v[134:135]
	global_load_lds_dwordx4 v[226:227], off
	v_lshl_add_u64 v[226:227], s[50:51], 0, v[132:133]
	s_add_i32 m0, s31, 0x2000
	s_nop 0
	global_load_lds_dwordx4 v[226:227], off
	v_lshl_add_u64 v[226:227], s[48:49], 0, v[138:139]
	s_mov_b32 m0, s34
	s_nop 0
	global_load_lds_dwordx4 v[226:227], off
	s_mov_b32 m0, s35
	s_nop 0
	global_load_lds_dwordx4 v[228:229], off
	s_waitcnt vmcnt(8)
	s_waitcnt lgkmcnt(0)
	s_barrier
	s_setprio 1
	s_waitcnt lgkmcnt(0)
	v_mfma_f32_16x16x32_bf16 v[64:67], v[144:147], v[176:179], 0
	v_mfma_f32_16x16x32_bf16 v[60:63], v[152:155], v[176:179], 0
	v_mfma_f32_16x16x32_bf16 v[48:51], v[144:147], v[184:187], 0
	v_mfma_f32_16x16x32_bf16 v[44:47], v[152:155], v[184:187], 0
	v_mfma_f32_16x16x32_bf16 v[30:33], v[144:147], v[196:199], 0
	v_mfma_f32_16x16x32_bf16 v[26:29], v[152:155], v[196:199], 0
	v_mfma_f32_16x16x32_bf16 v[14:17], v[144:147], v[200:203], 0
	v_mfma_f32_16x16x32_bf16 v[10:13], v[152:155], v[200:203], 0
	v_mfma_f32_16x16x32_bf16 v[64:67], v[148:151], v[188:191], v[64:67]
	v_mfma_f32_16x16x32_bf16 v[60:63], v[156:159], v[188:191], v[60:63]
	v_mfma_f32_16x16x32_bf16 v[48:51], v[148:151], v[192:195], v[48:51]
	v_mfma_f32_16x16x32_bf16 v[44:47], v[156:159], v[192:195], v[44:47]
	v_mfma_f32_16x16x32_bf16 v[30:33], v[148:151], v[204:207], v[30:33]
	v_mfma_f32_16x16x32_bf16 v[26:29], v[156:159], v[204:207], v[26:29]
	v_mfma_f32_16x16x32_bf16 v[14:17], v[148:151], v[208:211], v[14:17]
	v_mfma_f32_16x16x32_bf16 v[10:13], v[156:159], v[208:211], v[10:13]
	s_setprio 0
	s_setprio 1
	v_mfma_f32_16x16x32_bf16 v[56:59], v[160:163], v[176:179], 0
	v_mfma_f32_16x16x32_bf16 v[52:55], v[168:171], v[176:179], 0
	v_mfma_f32_16x16x32_bf16 v[40:43], v[160:163], v[184:187], 0
	v_mfma_f32_16x16x32_bf16 v[36:39], v[168:171], v[184:187], 0
	v_mfma_f32_16x16x32_bf16 v[22:25], v[160:163], v[196:199], 0
	v_mfma_f32_16x16x32_bf16 v[18:21], v[168:171], v[196:199], 0
	v_mfma_f32_16x16x32_bf16 v[6:9], v[160:163], v[200:203], 0
	v_mfma_f32_16x16x32_bf16 v[2:5], v[168:171], v[200:203], 0
	v_mfma_f32_16x16x32_bf16 v[56:59], v[164:167], v[188:191], v[56:59]
	v_mfma_f32_16x16x32_bf16 v[52:55], v[172:175], v[188:191], v[52:55]
	v_mfma_f32_16x16x32_bf16 v[40:43], v[164:167], v[192:195], v[40:43]
	v_mfma_f32_16x16x32_bf16 v[36:39], v[172:175], v[192:195], v[36:39]
	v_mfma_f32_16x16x32_bf16 v[22:25], v[164:167], v[204:207], v[22:25]
	v_mfma_f32_16x16x32_bf16 v[18:21], v[172:175], v[204:207], v[18:21]
	v_mfma_f32_16x16x32_bf16 v[6:9], v[164:167], v[208:211], v[6:9]
	v_mfma_f32_16x16x32_bf16 v[2:5], v[172:175], v[208:211], v[2:5]
	s_setprio 0
	s_barrier
	s_add_i32 s31, 0, 0x18000
	v_add_u32_e32 v34, s31, v1
	v_add_u32_e32 v140, s31, v141
	ds_read_b128 v[144:147], v34
	ds_read_b128 v[148:151], v140
	v_add_u32_e32 v34, s72, v1
	s_add_i32 s47, 0, 0x1c000
	v_add_u32_e32 v140, s72, v141
	ds_read_b128 v[152:155], v34
	ds_read_b128 v[156:159], v140
	v_add_u32_e32 v34, s47, v1
	v_add_u32_e32 v140, s47, v141
	ds_read_b128 v[160:163], v34
	ds_read_b128 v[164:167], v140
	v_add_u32_e32 v34, s73, v1
	v_add_u32_e32 v140, s73, v141
	ds_read_b128 v[168:171], v34
	ds_read_b128 v[172:175], v140
	s_add_u32 s48, s48, 0x80000
	s_addc_u32 s49, s49, 0
	s_mov_b32 m0, s54
	v_lshl_add_u64 v[230:231], s[48:49], 0, v[138:139]
	ds_read_b128 v[176:179], v142 offset:32768
	ds_read_b128 v[184:187], v142 offset:34816
	ds_read_b128 v[188:191], v143 offset:32768
	ds_read_b128 v[192:195], v143 offset:34816
	ds_read_b128 v[196:199], v142 offset:36864
	ds_read_b128 v[200:203], v142 offset:38912
	ds_read_b128 v[204:207], v143 offset:36864
	ds_read_b128 v[208:211], v143 offset:38912
	global_load_lds_dwordx4 v[230:231], off
	v_lshl_add_u64 v[230:231], s[48:49], 0, v[134:135]
	s_mov_b32 m0, s55
	s_nop 0
	global_load_lds_dwordx4 v[230:231], off
	s_waitcnt vmcnt(8)
	s_waitcnt lgkmcnt(0)
	s_barrier
	s_setprio 1
	s_waitcnt lgkmcnt(0)
	v_mfma_f32_16x16x32_bf16 v[128:131], v[144:147], v[176:179], v[128:131]
	v_mfma_f32_16x16x32_bf16 v[124:127], v[152:155], v[176:179], v[124:127]
	v_mfma_f32_16x16x32_bf16 v[112:115], v[144:147], v[184:187], v[112:115]
	v_mfma_f32_16x16x32_bf16 v[108:111], v[152:155], v[184:187], v[108:111]
	v_mfma_f32_16x16x32_bf16 v[96:99], v[144:147], v[196:199], v[96:99]
	v_mfma_f32_16x16x32_bf16 v[92:95], v[152:155], v[196:199], v[92:95]
	v_mfma_f32_16x16x32_bf16 v[80:83], v[144:147], v[200:203], v[80:83]
	v_mfma_f32_16x16x32_bf16 v[76:79], v[152:155], v[200:203], v[76:79]
	v_mfma_f32_16x16x32_bf16 v[128:131], v[148:151], v[188:191], v[128:131]
	v_mfma_f32_16x16x32_bf16 v[124:127], v[156:159], v[188:191], v[124:127]
	v_mfma_f32_16x16x32_bf16 v[112:115], v[148:151], v[192:195], v[112:115]
	v_mfma_f32_16x16x32_bf16 v[108:111], v[156:159], v[192:195], v[108:111]
	v_mfma_f32_16x16x32_bf16 v[96:99], v[148:151], v[204:207], v[96:99]
	v_mfma_f32_16x16x32_bf16 v[92:95], v[156:159], v[204:207], v[92:95]
	v_mfma_f32_16x16x32_bf16 v[80:83], v[148:151], v[208:211], v[80:83]
	v_mfma_f32_16x16x32_bf16 v[76:79], v[156:159], v[208:211], v[76:79]
	s_setprio 0
	s_setprio 1
	v_mfma_f32_16x16x32_bf16 v[120:123], v[160:163], v[176:179], v[120:123]
	v_mfma_f32_16x16x32_bf16 v[116:119], v[168:171], v[176:179], v[116:119]
	v_mfma_f32_16x16x32_bf16 v[104:107], v[160:163], v[184:187], v[104:107]
	v_mfma_f32_16x16x32_bf16 v[100:103], v[168:171], v[184:187], v[100:103]
	v_mfma_f32_16x16x32_bf16 v[88:91], v[160:163], v[196:199], v[88:91]
	v_mfma_f32_16x16x32_bf16 v[84:87], v[168:171], v[196:199], v[84:87]
	v_mfma_f32_16x16x32_bf16 v[72:75], v[160:163], v[200:203], v[72:75]
	v_mfma_f32_16x16x32_bf16 v[68:71], v[168:171], v[200:203], v[68:71]
	v_mfma_f32_16x16x32_bf16 v[120:123], v[164:167], v[188:191], v[120:123]
	v_mfma_f32_16x16x32_bf16 v[116:119], v[172:175], v[188:191], v[116:119]
	v_mfma_f32_16x16x32_bf16 v[104:107], v[164:167], v[192:195], v[104:107]
	v_mfma_f32_16x16x32_bf16 v[100:103], v[172:175], v[192:195], v[100:103]
	v_mfma_f32_16x16x32_bf16 v[88:91], v[164:167], v[204:207], v[88:91]
	v_mfma_f32_16x16x32_bf16 v[84:87], v[172:175], v[204:207], v[84:87]
	v_mfma_f32_16x16x32_bf16 v[72:75], v[164:167], v[208:211], v[72:75]
	v_mfma_f32_16x16x32_bf16 v[68:71], v[172:175], v[208:211], v[68:71]
	s_setprio 0
	s_barrier
	s_add_i32 s31, s31, s33
	v_lshl_add_u64 v[212:213], v[212:213], 0, s[74:75]
	s_mov_b32 m0, s31
	ds_read_b128 v[176:179], v142 offset:49152
	ds_read_b128 v[184:187], v142 offset:51200
	ds_read_b128 v[188:191], v143 offset:49152
	ds_read_b128 v[192:195], v143 offset:51200
	ds_read_b128 v[196:199], v142 offset:53248
	ds_read_b128 v[200:203], v142 offset:55296
	ds_read_b128 v[204:207], v143 offset:53248
	ds_read_b128 v[208:211], v143 offset:55296
	global_load_lds_dwordx4 v[212:213], off
	s_add_i32 m0, s31, 0x2000
	s_add_u32 s44, s44, 0x80080
	v_lshl_add_u64 v[212:213], v[224:225], 0, s[74:75]
	s_addc_u32 s45, s45, 0
	s_add_i32 s31, s47, s33
	global_load_lds_dwordx4 v[212:213], off
	v_lshl_add_u64 v[212:213], s[44:45], 0, v[136:137]
	s_mov_b32 m0, s31
	s_nop 0
	global_load_lds_dwordx4 v[212:213], off
	v_lshl_add_u64 v[212:213], s[44:45], 0, v[132:133]
	s_add_i32 m0, s31, 0x2000
	s_nop 0
	global_load_lds_dwordx4 v[212:213], off
	v_lshl_add_u64 v[212:213], v[226:227], 0, s[74:75]
	s_mov_b32 m0, s56
	s_nop 0
	global_load_lds_dwordx4 v[212:213], off
	v_lshl_add_u64 v[212:213], v[228:229], 0, s[74:75]
	s_mov_b32 m0, s57
	s_nop 0
	global_load_lds_dwordx4 v[212:213], off
	s_waitcnt vmcnt(8)
	s_waitcnt lgkmcnt(0)
	s_barrier
	s_setprio 1
	s_waitcnt lgkmcnt(0)
	v_mfma_f32_16x16x32_bf16 v[64:67], v[144:147], v[176:179], v[64:67]
	v_mfma_f32_16x16x32_bf16 v[60:63], v[152:155], v[176:179], v[60:63]
	v_mfma_f32_16x16x32_bf16 v[48:51], v[144:147], v[184:187], v[48:51]
	v_mfma_f32_16x16x32_bf16 v[44:47], v[152:155], v[184:187], v[44:47]
	v_mfma_f32_16x16x32_bf16 v[30:33], v[144:147], v[196:199], v[30:33]
	v_mfma_f32_16x16x32_bf16 v[26:29], v[152:155], v[196:199], v[26:29]
	v_mfma_f32_16x16x32_bf16 v[14:17], v[144:147], v[200:203], v[14:17]
	v_mfma_f32_16x16x32_bf16 v[10:13], v[152:155], v[200:203], v[10:13]
	v_mfma_f32_16x16x32_bf16 v[64:67], v[148:151], v[188:191], v[64:67]
	v_mfma_f32_16x16x32_bf16 v[60:63], v[156:159], v[188:191], v[60:63]
	v_mfma_f32_16x16x32_bf16 v[48:51], v[148:151], v[192:195], v[48:51]
	v_mfma_f32_16x16x32_bf16 v[44:47], v[156:159], v[192:195], v[44:47]
	v_mfma_f32_16x16x32_bf16 v[30:33], v[148:151], v[204:207], v[30:33]
	v_mfma_f32_16x16x32_bf16 v[26:29], v[156:159], v[204:207], v[26:29]
	v_mfma_f32_16x16x32_bf16 v[14:17], v[148:151], v[208:211], v[14:17]
	v_mfma_f32_16x16x32_bf16 v[10:13], v[156:159], v[208:211], v[10:13]
	s_setprio 0
	s_setprio 1
	v_mfma_f32_16x16x32_bf16 v[56:59], v[160:163], v[176:179], v[56:59]
	v_mfma_f32_16x16x32_bf16 v[52:55], v[168:171], v[176:179], v[52:55]
	v_mfma_f32_16x16x32_bf16 v[40:43], v[160:163], v[184:187], v[40:43]
	v_mfma_f32_16x16x32_bf16 v[36:39], v[168:171], v[184:187], v[36:39]
	v_mfma_f32_16x16x32_bf16 v[22:25], v[160:163], v[196:199], v[22:25]
	v_mfma_f32_16x16x32_bf16 v[18:21], v[168:171], v[196:199], v[18:21]
	v_mfma_f32_16x16x32_bf16 v[6:9], v[160:163], v[200:203], v[6:9]
	v_mfma_f32_16x16x32_bf16 v[2:5], v[168:171], v[200:203], v[2:5]
	v_mfma_f32_16x16x32_bf16 v[56:59], v[164:167], v[188:191], v[56:59]
	v_mfma_f32_16x16x32_bf16 v[52:55], v[172:175], v[188:191], v[52:55]
	v_mfma_f32_16x16x32_bf16 v[40:43], v[164:167], v[192:195], v[40:43]
	v_mfma_f32_16x16x32_bf16 v[36:39], v[172:175], v[192:195], v[36:39]
	v_mfma_f32_16x16x32_bf16 v[22:25], v[164:167], v[204:207], v[22:25]
	v_mfma_f32_16x16x32_bf16 v[18:21], v[172:175], v[204:207], v[18:21]
	v_mfma_f32_16x16x32_bf16 v[6:9], v[164:167], v[208:211], v[6:9]
	v_mfma_f32_16x16x32_bf16 v[2:5], v[172:175], v[208:211], v[2:5]
	s_setprio 0
	s_barrier
	s_add_i32 s30, s30, 2
	s_add_u32 s42, s42, 0x100
	s_addc_u32 s43, s43, 0
	s_add_u32 s23, s23, 0x100
	s_addc_u32 s25, s25, 0
	s_cmp_gt_u32 s30, 29
	s_cbranch_scc1 .Lpeel_done_P1

.Lpeel_done_P1:
	s_and_b64 vcc, exec, s[10:11]
	s_cbranch_vccz .LBB0_165
	s_barrier

.LBB0_202:
	s_ashr_i32 s49, s48, 31
	s_lshl_b64 s[20:21], s[48:49], 23
	v_readlane_b32 s30, v254, 52
	v_readlane_b32 s31, v254, 53
	s_add_u32 s20, s30, s20
	s_addc_u32 s21, s31, s21
	s_lshl_b32 s13, s46, 8
	v_and_b32_e32 v151, 63, v144
	s_add_i32 s13, s13, s58
	v_bfe_u32 v144, v144, 2, 4
	v_or_b32_e32 v152, s13, v144
	v_lshlrev_b32_e32 v144, 6, v148
	s_movk_i32 s13, 0xfc
	v_pk_mul_f32 v[128:129], v[128:129], v[34:35] op_sel_hi:[1,0]
	v_bitop3_b32 v144, v144, s13, v151 bitop3:0xc8
	v_pk_mul_f32 v[130:131], v[130:131], v[34:35] op_sel_hi:[1,0]
	v_pk_mul_f32 v[126:127], v[126:127], v[34:35] op_sel_hi:[1,0]
	v_pk_mul_f32 v[124:125], v[124:125], v[34:35] op_sel_hi:[1,0]
	v_cvt_pk_bf16_f32 v34, v128, v129
	v_cvt_pk_bf16_f32 v128, v130, v131
	v_ashrrev_i32_e32 v153, 31, v152
	v_cvt_pk_bf16_f32 v124, v124, v125
	v_cvt_pk_bf16_f32 v125, v126, v127
	ds_bpermute_b32 v126, v144, v34
	ds_bpermute_b32 v127, v144, v128
	ds_bpermute_b32 v128, v144, v124
	ds_bpermute_b32 v129, v144, v125
	v_lshlrev_b64 v[152:153], 8, v[152:153]
	v_lshl_add_u64 v[152:153], s[20:21], 0, v[152:153]
	v_lshlrev_b32_e32 v34, 4, v148
	v_lshl_add_u64 v[124:125], v[152:153], 0, s[92:93]
	v_and_b32_e32 v34, 48, v34
	v_lshl_add_u64 v[124:125], v[124:125], 0, v[34:35]
	s_cmp_lg_u32 s12, 0
	v_bfrev_b32_e32 v34, 60
	s_waitcnt lgkmcnt(0)
	global_store_dwordx4 v[124:125], v[126:129], off
	s_cselect_b64 s[52:53], -1, 0
	s_cmp_eq_u32 s12, 0
	v_cndmask_b32_e64 v126, v34, v220, s[42:43]
	s_cbranch_scc1 .LBB0_204
	s_add_i32 s12, 0, 0x20400
	v_add_u32_e32 v34, s12, v149
	ds_read_b128 v[128:131], v34 offset:16
	s_waitcnt lgkmcnt(0)
	v_mov_b32_e32 v148, v129
	v_mov_b32_e32 v149, v130
	v_mov_b32_e32 v129, v131
	v_pk_add_f32 v[128:129], v[148:149], v[128:129]
	s_nop 0
	v_cndmask_b32_e64 v34, v129, v128, s[38:39]
	v_add_f32_e32 v127, v128, v129
	v_cndmask_b32_e64 v34, v127, v34, s[42:43]
	v_mul_f32_e32 v34, v150, v34
	v_fmaak_f32 v34, v126, v34, 0x358637bd
	v_rsq_f32_e32 v34, v34
	s_nop 0
	v_mul_f32_e32 v140, v140, v34
.LBB0_204:
	v_pk_mul_f32 v[120:121], v[120:121], v[140:141] op_sel_hi:[1,0]
	v_pk_mul_f32 v[118:119], v[118:119], v[140:141] op_sel_hi:[1,0]
	v_pk_mul_f32 v[122:123], v[122:123], v[140:141] op_sel_hi:[1,0]
	v_pk_mul_f32 v[116:117], v[116:117], v[140:141] op_sel_hi:[1,0]
	v_cvt_pk_bf16_f32 v34, v120, v121
	v_cvt_pk_bf16_f32 v120, v122, v123
	s_nop 0
	v_cvt_pk_bf16_f32 v121, v116, v117
	v_cvt_pk_bf16_f32 v119, v118, v119
	ds_bpermute_b32 v116, v144, v34
	ds_bpermute_b32 v117, v144, v120
	ds_bpermute_b32 v118, v144, v121
	ds_bpermute_b32 v119, v144, v119
	ds_read_b32 v34, v146 offset:64
	v_add_co_u32_e32 v120, vcc, 0x800000, v124
	s_nop 1
	v_addc_co_u32_e32 v121, vcc, 0, v125, vcc
	s_waitcnt lgkmcnt(0)
	global_store_dwordx4 v[120:121], v[116:119], off
	s_andn2_b64 vcc, exec, s[50:51]
	s_nop 0
	v_cndmask_b32_e64 v116, 0, 1, s[50:51]
	v_lshlrev_b32_e32 v117, 5, v147
	v_mul_f32_e32 v118, v34, v34
	v_cmp_ne_u32_e64 s[46:47], 1, v116
	v_mov_b32_e32 v116, v34
	s_cbranch_vccnz .LBB0_206
	s_add_i32 s12, 0, 0x20400
	v_add_u32_e32 v116, s12, v117
	ds_read_b128 v[120:123], v116 offset:512
	s_waitcnt lgkmcnt(0)
	v_mov_b32_e32 v128, v121
	v_mov_b32_e32 v129, v122
	v_mov_b32_e32 v121, v123
	v_pk_add_f32 v[120:121], v[128:129], v[120:121]
	s_nop 0
	v_cndmask_b32_e64 v116, v121, v120, s[38:39]
	v_add_f32_e32 v119, v120, v121
	v_cndmask_b32_e64 v116, v119, v116, s[44:45]
	v_mul_f32_e32 v116, v118, v116
	v_fmaak_f32 v116, v145, v116, 0x358637bd
	v_rsq_f32_e32 v116, v116
	s_nop 0
	v_mul_f32_e32 v116, v34, v116
.LBB0_206:
	v_pk_mul_f32 v[114:115], v[114:115], v[116:117] op_sel_hi:[1,0]
	v_pk_mul_f32 v[112:113], v[112:113], v[116:117] op_sel_hi:[1,0]
	v_pk_mul_f32 v[110:111], v[110:111], v[116:117] op_sel_hi:[1,0]
	v_pk_mul_f32 v[108:109], v[108:109], v[116:117] op_sel_hi:[1,0]
	v_cvt_pk_bf16_f32 v112, v112, v113
	v_cvt_pk_bf16_f32 v113, v114, v115
	s_nop 0
	v_cvt_pk_bf16_f32 v114, v108, v109
	v_cvt_pk_bf16_f32 v111, v110, v111
	ds_bpermute_b32 v108, v144, v112
	ds_bpermute_b32 v109, v144, v113
	ds_bpermute_b32 v110, v144, v114
	ds_bpermute_b32 v111, v144, v111
	v_add_co_u32_e32 v112, vcc, 0x1000, v124
	v_cndmask_b32_e64 v114, 0, 1, s[52:53]
	s_nop 0
	v_addc_co_u32_e32 v113, vcc, 0, v125, vcc
	v_cmp_ne_u32_e64 s[48:49], 1, v114
	s_andn2_b64 vcc, exec, s[52:53]
	s_waitcnt lgkmcnt(0)
	global_store_dwordx4 v[112:113], v[108:111], off
	s_cbranch_vccnz .LBB0_208
	s_add_i32 s12, 0, 0x20400
	v_add_u32_e32 v108, s12, v117
	ds_read_b128 v[108:111], v108 offset:528
	s_waitcnt lgkmcnt(0)
	v_mov_b32_e32 v112, v109
	v_mov_b32_e32 v113, v110
	v_mov_b32_e32 v109, v111
	v_pk_add_f32 v[108:109], v[112:113], v[108:109]
	s_nop 0
	v_cndmask_b32_e64 v110, v109, v108, s[38:39]
	v_add_f32_e32 v108, v108, v109
	v_cndmask_b32_e64 v108, v108, v110, s[42:43]
	v_mul_f32_e32 v108, v118, v108
	v_fmaak_f32 v108, v126, v108, 0x358637bd
	v_rsq_f32_e32 v108, v108
	s_nop 0
	v_mul_f32_e32 v34, v34, v108
.LBB0_208:
	v_pk_mul_f32 v[104:105], v[104:105], v[34:35] op_sel_hi:[1,0]
	v_pk_mul_f32 v[102:103], v[102:103], v[34:35] op_sel_hi:[1,0]
	v_pk_mul_f32 v[106:107], v[106:107], v[34:35] op_sel_hi:[1,0]
	v_pk_mul_f32 v[100:101], v[100:101], v[34:35] op_sel_hi:[1,0]
	v_cvt_pk_bf16_f32 v34, v104, v105
	v_cvt_pk_bf16_f32 v104, v106, v107
	s_nop 0
	v_cvt_pk_bf16_f32 v105, v100, v101
	v_cvt_pk_bf16_f32 v103, v102, v103
	ds_bpermute_b32 v100, v144, v34
	ds_bpermute_b32 v101, v144, v104
	ds_bpermute_b32 v102, v144, v105
	ds_bpermute_b32 v103, v144, v103
	ds_read_b32 v34, v146 offset:128
	v_add_co_u32_e32 v104, vcc, 0x801000, v124
	s_nop 1
	v_addc_co_u32_e32 v105, vcc, 0, v125, vcc
	s_waitcnt lgkmcnt(0)
	global_store_dwordx4 v[104:105], v[100:103], off
	s_and_b64 vcc, exec, s[46:47]
	s_nop 0
	v_mul_f32_e32 v101, v34, v34
	v_mov_b32_e32 v100, v34
	s_cbranch_vccnz .LBB0_210
	s_add_i32 s12, 0, 0x20400
	v_add_u32_e32 v100, s12, v117
	ds_read_b128 v[102:105], v100 offset:1024
	s_waitcnt lgkmcnt(0)
	v_mov_b32_e32 v106, v103
	v_mov_b32_e32 v107, v104
	v_mov_b32_e32 v103, v105
	v_pk_add_f32 v[102:103], v[106:107], v[102:103]
	s_nop 0
	v_cndmask_b32_e64 v100, v103, v102, s[38:39]
	v_add_f32_e32 v102, v102, v103
	v_cndmask_b32_e64 v100, v102, v100, s[44:45]
	v_mul_f32_e32 v100, v101, v100
	v_fmaak_f32 v100, v145, v100, 0x358637bd
	v_rsq_f32_e32 v100, v100
	s_nop 0
	v_mul_f32_e32 v100, v34, v100
.LBB0_210:
	v_pk_mul_f32 v[98:99], v[98:99], v[100:101] op_sel_hi:[1,0]
	v_pk_mul_f32 v[96:97], v[96:97], v[100:101] op_sel_hi:[1,0]
	v_pk_mul_f32 v[94:95], v[94:95], v[100:101] op_sel_hi:[1,0]
	v_pk_mul_f32 v[92:93], v[92:93], v[100:101] op_sel_hi:[1,0]
	v_cvt_pk_bf16_f32 v96, v96, v97
	v_cvt_pk_bf16_f32 v97, v98, v99
	s_nop 0
	v_cvt_pk_bf16_f32 v98, v92, v93
	v_cvt_pk_bf16_f32 v95, v94, v95
	ds_bpermute_b32 v92, v144, v96
	ds_bpermute_b32 v93, v144, v97
	ds_bpermute_b32 v94, v144, v98
	ds_bpermute_b32 v95, v144, v95
	v_add_co_u32_e32 v96, vcc, 0x2000, v124
	s_nop 1
	v_addc_co_u32_e32 v97, vcc, 0, v125, vcc
	s_and_b64 vcc, exec, s[48:49]
	s_waitcnt lgkmcnt(0)
	global_store_dwordx4 v[96:97], v[92:95], off
	s_cbranch_vccnz .LBB0_212
	s_add_i32 s12, 0, 0x20400
	v_add_u32_e32 v92, s12, v117
	ds_read_b128 v[92:95], v92 offset:1040
	s_waitcnt lgkmcnt(0)
	v_mov_b32_e32 v96, v93
	v_mov_b32_e32 v97, v94
	v_mov_b32_e32 v93, v95
	v_pk_add_f32 v[92:93], v[96:97], v[92:93]
	s_nop 0
	v_cndmask_b32_e64 v94, v93, v92, s[38:39]
	v_add_f32_e32 v92, v92, v93
	v_cndmask_b32_e64 v92, v92, v94, s[42:43]
	v_mul_f32_e32 v92, v101, v92
	v_fmaak_f32 v92, v126, v92, 0x358637bd
	v_rsq_f32_e32 v92, v92
	s_nop 0
	v_mul_f32_e32 v34, v34, v92
.LBB0_212:
	v_pk_mul_f32 v[88:89], v[88:89], v[34:35] op_sel_hi:[1,0]
	v_pk_mul_f32 v[86:87], v[86:87], v[34:35] op_sel_hi:[1,0]
	v_pk_mul_f32 v[90:91], v[90:91], v[34:35] op_sel_hi:[1,0]
	v_pk_mul_f32 v[84:85], v[84:85], v[34:35] op_sel_hi:[1,0]
	v_cvt_pk_bf16_f32 v34, v88, v89
	v_cvt_pk_bf16_f32 v88, v90, v91
	s_nop 0
	v_cvt_pk_bf16_f32 v89, v84, v85
	v_cvt_pk_bf16_f32 v87, v86, v87
	ds_bpermute_b32 v84, v144, v34
	ds_bpermute_b32 v85, v144, v88
	ds_bpermute_b32 v86, v144, v89
	ds_bpermute_b32 v87, v144, v87
	ds_read_b32 v34, v146 offset:192
	v_add_co_u32_e32 v88, vcc, 0x802000, v124
	s_nop 1
	v_addc_co_u32_e32 v89, vcc, 0, v125, vcc
	s_waitcnt lgkmcnt(0)
	global_store_dwordx4 v[88:89], v[84:87], off
	s_and_b64 vcc, exec, s[46:47]
	s_nop 0
	v_mul_f32_e32 v85, v34, v34
	v_mov_b32_e32 v84, v34
	s_cbranch_vccnz .LBB0_214
	s_add_i32 s12, 0, 0x20400
	v_add_u32_e32 v84, s12, v117
	ds_read_b128 v[86:89], v84 offset:1536
	s_waitcnt lgkmcnt(0)
	v_mov_b32_e32 v90, v87
	v_mov_b32_e32 v91, v88
	v_mov_b32_e32 v87, v89
	v_pk_add_f32 v[86:87], v[90:91], v[86:87]
	s_nop 0
	v_cndmask_b32_e64 v84, v87, v86, s[38:39]
	v_add_f32_e32 v86, v86, v87
	v_cndmask_b32_e64 v84, v86, v84, s[44:45]
	v_mul_f32_e32 v84, v85, v84
	v_fmaak_f32 v84, v145, v84, 0x358637bd
	v_rsq_f32_e32 v84, v84
	s_nop 0
	v_mul_f32_e32 v84, v34, v84
.LBB0_214:
	v_pk_mul_f32 v[82:83], v[82:83], v[84:85] op_sel_hi:[1,0]
	v_pk_mul_f32 v[80:81], v[80:81], v[84:85] op_sel_hi:[1,0]
	v_pk_mul_f32 v[78:79], v[78:79], v[84:85] op_sel_hi:[1,0]
	v_pk_mul_f32 v[76:77], v[76:77], v[84:85] op_sel_hi:[1,0]
	v_cvt_pk_bf16_f32 v80, v80, v81
	v_cvt_pk_bf16_f32 v81, v82, v83
	s_nop 0
	v_cvt_pk_bf16_f32 v82, v76, v77
	v_cvt_pk_bf16_f32 v79, v78, v79
	ds_bpermute_b32 v76, v144, v80
	ds_bpermute_b32 v77, v144, v81
	ds_bpermute_b32 v78, v144, v82
	ds_bpermute_b32 v79, v144, v79
	v_add_co_u32_e32 v80, vcc, 0x3000, v124
	s_nop 1
	v_addc_co_u32_e32 v81, vcc, 0, v125, vcc
	s_and_b64 vcc, exec, s[48:49]
	s_waitcnt lgkmcnt(0)
	global_store_dwordx4 v[80:81], v[76:79], off
	s_cbranch_vccnz .LBB0_216
	s_add_i32 s12, 0, 0x20400
	v_add_u32_e32 v76, s12, v117
	ds_read_b128 v[76:79], v76 offset:1552
	s_waitcnt lgkmcnt(0)
	v_mov_b32_e32 v80, v77
	v_mov_b32_e32 v81, v78
	v_mov_b32_e32 v77, v79
	v_pk_add_f32 v[76:77], v[80:81], v[76:77]
	s_nop 0
	v_cndmask_b32_e64 v78, v77, v76, s[38:39]
	v_add_f32_e32 v76, v76, v77
	v_cndmask_b32_e64 v76, v76, v78, s[42:43]
	v_mul_f32_e32 v76, v85, v76
	v_fmaak_f32 v76, v126, v76, 0x358637bd
	v_rsq_f32_e32 v76, v76
	s_nop 0
	v_mul_f32_e32 v34, v34, v76
.LBB0_216:
	v_pk_mul_f32 v[72:73], v[72:73], v[34:35] op_sel_hi:[1,0]
	v_pk_mul_f32 v[70:71], v[70:71], v[34:35] op_sel_hi:[1,0]
	v_pk_mul_f32 v[74:75], v[74:75], v[34:35] op_sel_hi:[1,0]
	v_pk_mul_f32 v[68:69], v[68:69], v[34:35] op_sel_hi:[1,0]
	v_cvt_pk_bf16_f32 v34, v72, v73
	v_cvt_pk_bf16_f32 v72, v74, v75
	s_nop 0
	v_cvt_pk_bf16_f32 v73, v68, v69
	v_cvt_pk_bf16_f32 v71, v70, v71
	ds_bpermute_b32 v68, v144, v34
	ds_bpermute_b32 v69, v144, v72
	ds_bpermute_b32 v70, v144, v73
	ds_bpermute_b32 v71, v144, v71
	ds_read_b32 v34, v146 offset:512
	v_add_co_u32_e32 v72, vcc, 0x803000, v124
	s_nop 1
	v_addc_co_u32_e32 v73, vcc, 0, v125, vcc
	s_waitcnt lgkmcnt(0)
	global_store_dwordx4 v[72:73], v[68:71], off
	s_and_b64 vcc, exec, s[46:47]
	s_nop 0
	v_mul_f32_e32 v69, v34, v34
	v_mov_b32_e32 v68, v34
	s_cbranch_vccnz .LBB0_218
	s_add_i32 s12, 0, 0x20400
	v_add_u32_e32 v68, s12, v117
	ds_read_b128 v[70:73], v68 offset:4096
	s_waitcnt lgkmcnt(0)
	v_mov_b32_e32 v74, v71
	v_mov_b32_e32 v75, v72
	v_mov_b32_e32 v71, v73
	v_pk_add_f32 v[70:71], v[74:75], v[70:71]
	s_nop 0
	v_cndmask_b32_e64 v68, v71, v70, s[38:39]
	v_add_f32_e32 v70, v70, v71
	v_cndmask_b32_e64 v68, v70, v68, s[44:45]
	v_mul_f32_e32 v68, v69, v68
	v_fmaak_f32 v68, v145, v68, 0x358637bd
	v_rsq_f32_e32 v68, v68
	s_nop 0
	v_mul_f32_e32 v68, v34, v68
.LBB0_218:
	v_pk_mul_f32 v[66:67], v[66:67], v[68:69] op_sel_hi:[1,0]
	v_pk_mul_f32 v[64:65], v[64:65], v[68:69] op_sel_hi:[1,0]
	v_pk_mul_f32 v[62:63], v[62:63], v[68:69] op_sel_hi:[1,0]
	v_pk_mul_f32 v[60:61], v[60:61], v[68:69] op_sel_hi:[1,0]
	v_cvt_pk_bf16_f32 v64, v64, v65
	v_cvt_pk_bf16_f32 v65, v66, v67
	s_nop 0
	v_cvt_pk_bf16_f32 v66, v60, v61
	v_cvt_pk_bf16_f32 v63, v62, v63
	ds_bpermute_b32 v60, v144, v64
	ds_bpermute_b32 v61, v144, v65
	ds_bpermute_b32 v62, v144, v66
	ds_bpermute_b32 v63, v144, v63
	v_add_co_u32_e32 v64, vcc, 0x8000, v124
	s_nop 1
	v_addc_co_u32_e32 v65, vcc, 0, v125, vcc
	s_and_b64 vcc, exec, s[48:49]
	s_waitcnt lgkmcnt(0)
	global_store_dwordx4 v[64:65], v[60:63], off
	s_cbranch_vccnz .LBB0_220
	s_add_i32 s12, 0, 0x20400
	v_add_u32_e32 v60, s12, v117
	ds_read_b128 v[60:63], v60 offset:4112
	s_waitcnt lgkmcnt(0)
	v_mov_b32_e32 v64, v61
	v_mov_b32_e32 v65, v62
	v_mov_b32_e32 v61, v63
	v_pk_add_f32 v[60:61], v[64:65], v[60:61]
	s_nop 0
	v_cndmask_b32_e64 v62, v61, v60, s[38:39]
	v_add_f32_e32 v60, v60, v61
	v_cndmask_b32_e64 v60, v60, v62, s[42:43]
	v_mul_f32_e32 v60, v69, v60
	v_fmaak_f32 v60, v126, v60, 0x358637bd
	v_rsq_f32_e32 v60, v60
	s_nop 0
	v_mul_f32_e32 v34, v34, v60
.LBB0_220:
	v_pk_mul_f32 v[56:57], v[56:57], v[34:35] op_sel_hi:[1,0]
	v_pk_mul_f32 v[54:55], v[54:55], v[34:35] op_sel_hi:[1,0]
	v_pk_mul_f32 v[58:59], v[58:59], v[34:35] op_sel_hi:[1,0]
	v_pk_mul_f32 v[52:53], v[52:53], v[34:35] op_sel_hi:[1,0]
	v_cvt_pk_bf16_f32 v34, v56, v57
	v_cvt_pk_bf16_f32 v56, v58, v59
	s_nop 0
	v_cvt_pk_bf16_f32 v57, v52, v53
	v_cvt_pk_bf16_f32 v55, v54, v55
	ds_bpermute_b32 v52, v144, v34
	ds_bpermute_b32 v53, v144, v56
	ds_bpermute_b32 v54, v144, v57
	ds_bpermute_b32 v55, v144, v55
	ds_read_b32 v34, v146 offset:576
	v_add_co_u32_e32 v56, vcc, 0x808000, v124
	s_nop 1
	v_addc_co_u32_e32 v57, vcc, 0, v125, vcc
	s_waitcnt lgkmcnt(0)
	global_store_dwordx4 v[56:57], v[52:55], off
	s_and_b64 vcc, exec, s[46:47]
	s_nop 0
	v_mul_f32_e32 v53, v34, v34
	v_mov_b32_e32 v52, v34
	s_cbranch_vccnz .LBB0_222
	s_add_i32 s12, 0, 0x20400
	v_add_u32_e32 v52, s12, v117
	ds_read_b128 v[54:57], v52 offset:4608
	s_waitcnt lgkmcnt(0)
	v_mov_b32_e32 v58, v55
	v_mov_b32_e32 v59, v56
	v_mov_b32_e32 v55, v57
	v_pk_add_f32 v[54:55], v[58:59], v[54:55]
	s_nop 0
	v_cndmask_b32_e64 v52, v55, v54, s[38:39]
	v_add_f32_e32 v54, v54, v55
	v_cndmask_b32_e64 v52, v54, v52, s[44:45]
	v_mul_f32_e32 v52, v53, v52
	v_fmaak_f32 v52, v145, v52, 0x358637bd
	v_rsq_f32_e32 v52, v52
	s_nop 0
	v_mul_f32_e32 v52, v34, v52
.LBB0_222:
	v_pk_mul_f32 v[50:51], v[50:51], v[52:53] op_sel_hi:[1,0]
	v_pk_mul_f32 v[48:49], v[48:49], v[52:53] op_sel_hi:[1,0]
	v_pk_mul_f32 v[46:47], v[46:47], v[52:53] op_sel_hi:[1,0]
	v_pk_mul_f32 v[44:45], v[44:45], v[52:53] op_sel_hi:[1,0]
	v_cvt_pk_bf16_f32 v48, v48, v49
	v_cvt_pk_bf16_f32 v49, v50, v51
	s_nop 0
	v_cvt_pk_bf16_f32 v50, v44, v45
	v_cvt_pk_bf16_f32 v47, v46, v47
	ds_bpermute_b32 v44, v144, v48
	ds_bpermute_b32 v45, v144, v49
	ds_bpermute_b32 v46, v144, v50
	ds_bpermute_b32 v47, v144, v47
	v_add_co_u32_e32 v48, vcc, 0x9000, v124
	s_nop 1
	v_addc_co_u32_e32 v49, vcc, 0, v125, vcc
	s_and_b64 vcc, exec, s[48:49]
	s_waitcnt lgkmcnt(0)
	global_store_dwordx4 v[48:49], v[44:47], off
	s_cbranch_vccnz .LBB0_224
	s_add_i32 s12, 0, 0x20400
	v_add_u32_e32 v44, s12, v117
	ds_read_b128 v[44:47], v44 offset:4624
	s_waitcnt lgkmcnt(0)
	v_mov_b32_e32 v48, v45
	v_mov_b32_e32 v49, v46
	v_mov_b32_e32 v45, v47
	v_pk_add_f32 v[44:45], v[48:49], v[44:45]
	s_nop 0
	v_cndmask_b32_e64 v46, v45, v44, s[38:39]
	v_add_f32_e32 v44, v44, v45
	v_cndmask_b32_e64 v44, v44, v46, s[42:43]
	v_mul_f32_e32 v44, v53, v44
	v_fmaak_f32 v44, v126, v44, 0x358637bd
	v_rsq_f32_e32 v44, v44
	s_nop 0
	v_mul_f32_e32 v34, v34, v44
.LBB0_224:
	v_pk_mul_f32 v[40:41], v[40:41], v[34:35] op_sel_hi:[1,0]
	v_pk_mul_f32 v[38:39], v[38:39], v[34:35] op_sel_hi:[1,0]
	v_pk_mul_f32 v[42:43], v[42:43], v[34:35] op_sel_hi:[1,0]
	v_pk_mul_f32 v[36:37], v[36:37], v[34:35] op_sel_hi:[1,0]
	v_cvt_pk_bf16_f32 v34, v40, v41
	v_cvt_pk_bf16_f32 v40, v42, v43
	s_nop 0
	v_cvt_pk_bf16_f32 v41, v36, v37
	v_cvt_pk_bf16_f32 v39, v38, v39
	ds_bpermute_b32 v36, v144, v34
	ds_bpermute_b32 v37, v144, v40
	ds_bpermute_b32 v38, v144, v41
	ds_bpermute_b32 v39, v144, v39
	ds_read_b32 v34, v146 offset:640
	v_add_co_u32_e32 v40, vcc, 0x809000, v124
	s_nop 1
	v_addc_co_u32_e32 v41, vcc, 0, v125, vcc
	s_waitcnt lgkmcnt(0)
	global_store_dwordx4 v[40:41], v[36:39], off
	s_and_b64 vcc, exec, s[46:47]
	s_nop 0
	v_mul_f32_e32 v37, v34, v34
	v_mov_b32_e32 v36, v34
	s_cbranch_vccnz .LBB0_226
	s_add_i32 s12, 0, 0x20400
	v_add_u32_e32 v36, s12, v117
	ds_read_b128 v[38:41], v36 offset:5120
	s_waitcnt lgkmcnt(0)
	v_mov_b32_e32 v42, v39
	v_mov_b32_e32 v43, v40
	v_mov_b32_e32 v39, v41
	v_pk_add_f32 v[38:39], v[42:43], v[38:39]
	s_nop 0
	v_cndmask_b32_e64 v36, v39, v38, s[38:39]
	v_add_f32_e32 v38, v38, v39
	v_cndmask_b32_e64 v36, v38, v36, s[44:45]
	v_mul_f32_e32 v36, v37, v36
	v_fmaak_f32 v36, v145, v36, 0x358637bd
	v_rsq_f32_e32 v36, v36
	s_nop 0
	v_mul_f32_e32 v36, v34, v36
.LBB0_226:
	v_pk_mul_f32 v[32:33], v[32:33], v[36:37] op_sel_hi:[1,0]
	v_pk_mul_f32 v[30:31], v[30:31], v[36:37] op_sel_hi:[1,0]
	v_pk_mul_f32 v[28:29], v[28:29], v[36:37] op_sel_hi:[1,0]
	v_pk_mul_f32 v[26:27], v[26:27], v[36:37] op_sel_hi:[1,0]
	v_cvt_pk_bf16_f32 v30, v30, v31
	v_cvt_pk_bf16_f32 v31, v32, v33
	s_nop 0
	v_cvt_pk_bf16_f32 v32, v26, v27
	v_cvt_pk_bf16_f32 v29, v28, v29
	ds_bpermute_b32 v26, v144, v30
	ds_bpermute_b32 v27, v144, v31
	ds_bpermute_b32 v28, v144, v32
	ds_bpermute_b32 v29, v144, v29
	v_add_co_u32_e32 v30, vcc, 0xa000, v124
	s_nop 1
	v_addc_co_u32_e32 v31, vcc, 0, v125, vcc
	s_and_b64 vcc, exec, s[48:49]
	s_waitcnt lgkmcnt(0)
	global_store_dwordx4 v[30:31], v[26:29], off
	s_cbranch_vccnz .LBB0_228
	s_add_i32 s12, 0, 0x20400
	v_add_u32_e32 v26, s12, v117
	ds_read_b128 v[26:29], v26 offset:5136
	s_waitcnt lgkmcnt(0)
	v_mov_b32_e32 v30, v27
	v_mov_b32_e32 v31, v28
	v_mov_b32_e32 v27, v29
	v_pk_add_f32 v[26:27], v[30:31], v[26:27]
	s_nop 0
	v_cndmask_b32_e64 v28, v27, v26, s[38:39]
	v_add_f32_e32 v26, v26, v27
	v_cndmask_b32_e64 v26, v26, v28, s[42:43]
	v_mul_f32_e32 v26, v37, v26
	v_fmaak_f32 v26, v126, v26, 0x358637bd
	v_rsq_f32_e32 v26, v26
	s_nop 0
	v_mul_f32_e32 v34, v34, v26
.LBB0_228:
	v_pk_mul_f32 v[22:23], v[22:23], v[34:35] op_sel_hi:[1,0]
	v_pk_mul_f32 v[18:19], v[18:19], v[34:35] op_sel_hi:[1,0]
	v_pk_mul_f32 v[24:25], v[24:25], v[34:35] op_sel_hi:[1,0]
	v_pk_mul_f32 v[20:21], v[20:21], v[34:35] op_sel_hi:[1,0]
	v_cvt_pk_bf16_f32 v22, v22, v23
	v_cvt_pk_bf16_f32 v23, v24, v25
	v_cvt_pk_bf16_f32 v18, v18, v19
	v_add_co_u32_e32 v24, vcc, 0x80a000, v124
	v_cvt_pk_bf16_f32 v19, v20, v21
	ds_bpermute_b32 v20, v144, v22
	ds_bpermute_b32 v21, v144, v23
	ds_bpermute_b32 v22, v144, v18
	ds_bpermute_b32 v23, v144, v19
	ds_read_b32 v18, v146 offset:704
	v_addc_co_u32_e32 v25, vcc, 0, v125, vcc
	s_and_b64 vcc, exec, s[46:47]
	s_waitcnt lgkmcnt(0)
	global_store_dwordx4 v[24:25], v[20:23], off
	v_mul_f32_e32 v19, v18, v18
	s_nop 0
	v_mov_b32_e32 v20, v18
	s_cbranch_vccnz .LBB0_230
	s_add_i32 s12, 0, 0x20400
	v_add_u32_e32 v20, s12, v117
	ds_read_b128 v[20:23], v20 offset:5632
	s_waitcnt lgkmcnt(0)
	v_mov_b32_e32 v24, v21
	v_mov_b32_e32 v25, v22
	v_mov_b32_e32 v21, v23
	v_pk_add_f32 v[20:21], v[24:25], v[20:21]
	s_nop 0
	v_cndmask_b32_e64 v22, v21, v20, s[38:39]
	v_add_f32_e32 v20, v20, v21
	v_cndmask_b32_e64 v20, v20, v22, s[44:45]
	v_mul_f32_e32 v20, v19, v20
	v_fmaak_f32 v20, v145, v20, 0x358637bd
	v_rsq_f32_e32 v20, v20
	s_nop 0
	v_mul_f32_e32 v20, v18, v20
.LBB0_230:
	v_pk_mul_f32 v[16:17], v[16:17], v[20:21] op_sel_hi:[1,0]
	v_pk_mul_f32 v[14:15], v[14:15], v[20:21] op_sel_hi:[1,0]
	v_pk_mul_f32 v[12:13], v[12:13], v[20:21] op_sel_hi:[1,0]
	v_pk_mul_f32 v[10:11], v[10:11], v[20:21] op_sel_hi:[1,0]
	v_cvt_pk_bf16_f32 v14, v14, v15
	v_cvt_pk_bf16_f32 v15, v16, v17
	s_nop 0
	v_cvt_pk_bf16_f32 v16, v10, v11
	v_cvt_pk_bf16_f32 v13, v12, v13
	ds_bpermute_b32 v10, v144, v14
	ds_bpermute_b32 v11, v144, v15
	ds_bpermute_b32 v12, v144, v16
	ds_bpermute_b32 v13, v144, v13
	v_add_co_u32_e32 v14, vcc, 0xb000, v124
	s_nop 1
	v_addc_co_u32_e32 v15, vcc, 0, v125, vcc
	s_and_b64 vcc, exec, s[48:49]
	s_waitcnt lgkmcnt(0)
	global_store_dwordx4 v[14:15], v[10:13], off
	s_cbranch_vccnz .LBB0_232
	s_add_i32 s12, 0, 0x20400
	v_add_u32_e32 v10, s12, v117
	ds_read_b128 v[10:13], v10 offset:5648
	s_waitcnt lgkmcnt(0)
	v_mov_b32_e32 v14, v11
	v_mov_b32_e32 v15, v12
	v_mov_b32_e32 v11, v13
	v_pk_add_f32 v[10:11], v[14:15], v[10:11]
	s_nop 0
	v_cndmask_b32_e64 v12, v11, v10, s[38:39]
	v_add_f32_e32 v10, v10, v11
	v_cndmask_b32_e64 v10, v10, v12, s[42:43]
	v_mul_f32_e32 v10, v19, v10
	v_fmaak_f32 v10, v126, v10, 0x358637bd
	v_rsq_f32_e32 v10, v10
	s_nop 0
	v_mul_f32_e32 v18, v18, v10
.LBB0_232:
	v_pk_mul_f32 v[8:9], v[8:9], v[18:19] op_sel_hi:[1,0]
	v_pk_mul_f32 v[6:7], v[6:7], v[18:19] op_sel_hi:[1,0]
	v_pk_mul_f32 v[4:5], v[4:5], v[18:19] op_sel_hi:[1,0]
	v_pk_mul_f32 v[2:3], v[2:3], v[18:19] op_sel_hi:[1,0]
	v_cvt_pk_bf16_f32 v6, v6, v7
	v_cvt_pk_bf16_f32 v7, v8, v9
	s_nop 0
	v_cvt_pk_bf16_f32 v8, v2, v3
	v_cvt_pk_bf16_f32 v5, v4, v5
	ds_bpermute_b32 v2, v144, v6
	ds_bpermute_b32 v3, v144, v7
	ds_bpermute_b32 v4, v144, v8
	ds_bpermute_b32 v5, v144, v5
	v_add_co_u32_e32 v6, vcc, 0x80b000, v124
	s_nop 1
	v_addc_co_u32_e32 v7, vcc, 0, v125, vcc
	s_andn2_b64 vcc, exec, s[40:41]
	s_mov_b64 s[40:41], -1
	s_waitcnt lgkmcnt(0)
	global_store_dwordx4 v[6:7], v[2:5], off
	s_cbranch_vccnz .LBB0_156
	s_andn2_b64 vcc, exec, s[4:5]
	s_cbranch_vccnz .LBB0_155
	s_barrier
	s_branch .LBB0_155

.LBB0_907:
	s_and_b32 s9, 1, s12
	s_cmp_gt_i32 s12, 1
	s_cselect_b32 s24, 10, 12
	s_cmp_eq_u32 s9, 1
	s_cselect_b64 s[18:19], -1, 0
	s_and_b64 s[20:21], s[18:19], exec
	s_cselect_b32 s9, s24, 32
	s_add_i32 s20, s9, -2
	s_add_u32 s22, s22, 0x80080
	s_addc_u32 s23, s23, 0
	s_add_u32 s21, s28, 0x100
	s_addc_u32 s24, s29, 0
	s_mov_b32 s25, 0
	s_waitcnt vmcnt(0)
	v_readlane_b32 s43, v255, 20
	v_readlane_b32 s45, v255, 21
	v_readlane_b32 s66, v255, 22
	v_readlane_b32 s67, v255, 23
	s_mov_b64 s[68:69], 0x80
	s_add_i32 s30, s25, 2
	s_add_u32 s28, s22, 0xfff80080
	s_addc_u32 s29, s23, -1
	s_add_i32 s31, 0, 0x10000
	s_cmp_eq_u32 s20, s25
	s_cselect_b32 s41, s47, s29
	s_cselect_b32 s40, s46, s28
	s_cselect_b32 s29, s49, s24
	s_cselect_b32 s28, s48, s21
	s_add_i32 s25, 0, 0x14000
	v_add_u32_e32 v132, s31, v1
	v_add_u32_e32 v136, s31, v204
	v_add_u32_e32 v140, s43, v1
	v_add_u32_e32 v144, s43, v204
	v_add_u32_e32 v148, s25, v1
	v_add_u32_e32 v152, s25, v204
	v_add_u32_e32 v156, s45, v1
	v_add_u32_e32 v160, s45, v204
	ds_read_b128 v[132:135], v132
	ds_read_b128 v[136:139], v136
	ds_read_b128 v[140:143], v140
	ds_read_b128 v[144:147], v144
	ds_read_b128 v[148:151], v148
	ds_read_b128 v[152:155], v152
	ds_read_b128 v[156:159], v156
	ds_read_b128 v[160:163], v160
	v_lshl_add_u64 v[180:181], s[22:23], 0, v[188:189]
	s_add_i32 m0, s50, 0xc000
	ds_read_b128 v[164:167], v205
	ds_read_b128 v[168:171], v205 offset:2048
	ds_read_b128 v[172:175], v206
	ds_read_b128 v[176:179], v206 offset:2048
	ds_read_b128 v[190:193], v205 offset:4096
	ds_read_b128 v[194:197], v205 offset:6144
	ds_read_b128 v[198:201], v206 offset:4096
	ds_read_b128 v[232:235], v206 offset:6144
	global_load_lds_dwordx4 v[180:181], off
	v_lshl_add_u64 v[180:181], s[22:23], 0, v[186:187]
	s_add_i32 m0, s50, 0xe000
	s_nop 0
	global_load_lds_dwordx4 v[180:181], off
	s_waitcnt vmcnt(8)
	s_waitcnt lgkmcnt(0)
	s_barrier
	s_setprio 1
	s_waitcnt lgkmcnt(0)
	v_mfma_f32_16x16x32_bf16 v[68:71], v[132:135], v[164:167], 0
	v_mfma_f32_16x16x32_bf16 v[72:75], v[140:143], v[164:167], 0
	v_mfma_f32_16x16x32_bf16 v[84:87], v[132:135], v[168:171], 0
	v_mfma_f32_16x16x32_bf16 v[88:91], v[140:143], v[168:171], 0
	v_mfma_f32_16x16x32_bf16 v[100:103], v[132:135], v[190:193], 0
	v_mfma_f32_16x16x32_bf16 v[104:107], v[140:143], v[190:193], 0
	v_mfma_f32_16x16x32_bf16 v[116:119], v[132:135], v[194:197], 0
	v_mfma_f32_16x16x32_bf16 v[120:123], v[140:143], v[194:197], 0
	v_mfma_f32_16x16x32_bf16 v[68:71], v[136:139], v[172:175], v[68:71]
	v_mfma_f32_16x16x32_bf16 v[72:75], v[144:147], v[172:175], v[72:75]
	v_mfma_f32_16x16x32_bf16 v[84:87], v[136:139], v[176:179], v[84:87]
	v_mfma_f32_16x16x32_bf16 v[88:91], v[144:147], v[176:179], v[88:91]
	v_mfma_f32_16x16x32_bf16 v[100:103], v[136:139], v[198:201], v[100:103]
	v_mfma_f32_16x16x32_bf16 v[104:107], v[144:147], v[198:201], v[104:107]
	v_mfma_f32_16x16x32_bf16 v[116:119], v[136:139], v[232:235], v[116:119]
	v_mfma_f32_16x16x32_bf16 v[120:123], v[144:147], v[232:235], v[120:123]
	s_setprio 0
	s_setprio 1
	v_mfma_f32_16x16x32_bf16 v[76:79], v[148:151], v[164:167], 0
	v_mfma_f32_16x16x32_bf16 v[80:83], v[156:159], v[164:167], 0
	v_mfma_f32_16x16x32_bf16 v[92:95], v[148:151], v[168:171], 0
	v_mfma_f32_16x16x32_bf16 v[96:99], v[156:159], v[168:171], 0
	v_mfma_f32_16x16x32_bf16 v[108:111], v[148:151], v[190:193], 0
	v_mfma_f32_16x16x32_bf16 v[112:115], v[156:159], v[190:193], 0
	v_mfma_f32_16x16x32_bf16 v[124:127], v[148:151], v[194:197], 0
	v_mfma_f32_16x16x32_bf16 v[128:131], v[156:159], v[194:197], 0
	v_mfma_f32_16x16x32_bf16 v[76:79], v[152:155], v[172:175], v[76:79]
	v_mfma_f32_16x16x32_bf16 v[80:83], v[160:163], v[172:175], v[80:83]
	v_mfma_f32_16x16x32_bf16 v[92:95], v[152:155], v[176:179], v[92:95]
	v_mfma_f32_16x16x32_bf16 v[96:99], v[160:163], v[176:179], v[96:99]
	v_mfma_f32_16x16x32_bf16 v[108:111], v[152:155], v[198:201], v[108:111]
	v_mfma_f32_16x16x32_bf16 v[112:115], v[160:163], v[198:201], v[112:115]
	v_mfma_f32_16x16x32_bf16 v[124:127], v[152:155], v[232:235], v[124:127]
	v_mfma_f32_16x16x32_bf16 v[128:131], v[160:163], v[232:235], v[128:131]
	s_setprio 0
	s_barrier
	s_add_i32 s31, s31, s33
	v_lshl_add_u64 v[180:181], s[28:29], 0, v[34:35]
	s_mov_b32 m0, s31
	ds_read_b128 v[164:167], v205 offset:16384
	ds_read_b128 v[168:171], v205 offset:18432
	ds_read_b128 v[172:175], v206 offset:16384
	ds_read_b128 v[176:179], v206 offset:18432
	ds_read_b128 v[190:193], v205 offset:20480
	ds_read_b128 v[194:197], v205 offset:22528
	ds_read_b128 v[198:201], v206 offset:20480
	ds_read_b128 v[232:235], v206 offset:22528
	global_load_lds_dwordx4 v[180:181], off
	s_add_i32 m0, s31, 0x2000
	s_add_u32 s34, s28, 0x80000
	v_lshl_add_u64 v[182:183], s[28:29], 0, v[184:185]
	s_addc_u32 s35, s29, 0
	s_add_i32 s25, s25, s33
	global_load_lds_dwordx4 v[182:183], off
	v_lshl_add_u64 v[202:203], s[34:35], 0, v[34:35]
	s_mov_b32 m0, s25
	v_lshl_add_u64 v[218:219], s[40:41], 0, v[186:187]
	global_load_lds_dwordx4 v[202:203], off
	v_lshl_add_u64 v[202:203], s[34:35], 0, v[184:185]
	s_add_i32 m0, s25, 0x2000
	s_nop 0
	global_load_lds_dwordx4 v[202:203], off
	v_lshl_add_u64 v[202:203], s[40:41], 0, v[188:189]
	s_mov_b32 m0, s50
	s_nop 0
	global_load_lds_dwordx4 v[202:203], off
	s_mov_b32 m0, s51
	s_nop 0
	global_load_lds_dwordx4 v[218:219], off
	s_waitcnt vmcnt(8)
	s_waitcnt lgkmcnt(0)
	s_barrier
	s_setprio 1
	s_waitcnt lgkmcnt(0)
	v_mfma_f32_16x16x32_bf16 v[2:5], v[132:135], v[164:167], 0
	v_mfma_f32_16x16x32_bf16 v[6:9], v[140:143], v[164:167], 0
	v_mfma_f32_16x16x32_bf16 v[18:21], v[132:135], v[168:171], 0
	v_mfma_f32_16x16x32_bf16 v[22:25], v[140:143], v[168:171], 0
	v_mfma_f32_16x16x32_bf16 v[36:39], v[132:135], v[190:193], 0
	v_mfma_f32_16x16x32_bf16 v[40:43], v[140:143], v[190:193], 0
	v_mfma_f32_16x16x32_bf16 v[52:55], v[132:135], v[194:197], 0
	v_mfma_f32_16x16x32_bf16 v[56:59], v[140:143], v[194:197], 0
	v_mfma_f32_16x16x32_bf16 v[2:5], v[136:139], v[172:175], v[2:5]
	v_mfma_f32_16x16x32_bf16 v[6:9], v[144:147], v[172:175], v[6:9]
	v_mfma_f32_16x16x32_bf16 v[18:21], v[136:139], v[176:179], v[18:21]
	v_mfma_f32_16x16x32_bf16 v[22:25], v[144:147], v[176:179], v[22:25]
	v_mfma_f32_16x16x32_bf16 v[36:39], v[136:139], v[198:201], v[36:39]
	v_mfma_f32_16x16x32_bf16 v[40:43], v[144:147], v[198:201], v[40:43]
	v_mfma_f32_16x16x32_bf16 v[52:55], v[136:139], v[232:235], v[52:55]
	v_mfma_f32_16x16x32_bf16 v[56:59], v[144:147], v[232:235], v[56:59]
	s_setprio 0
	s_setprio 1
	v_mfma_f32_16x16x32_bf16 v[10:13], v[148:151], v[164:167], 0
	v_mfma_f32_16x16x32_bf16 v[14:17], v[156:159], v[164:167], 0
	v_mfma_f32_16x16x32_bf16 v[26:29], v[148:151], v[168:171], 0
	v_mfma_f32_16x16x32_bf16 v[30:33], v[156:159], v[168:171], 0
	v_mfma_f32_16x16x32_bf16 v[44:47], v[148:151], v[190:193], 0
	v_mfma_f32_16x16x32_bf16 v[48:51], v[156:159], v[190:193], 0
	v_mfma_f32_16x16x32_bf16 v[60:63], v[148:151], v[194:197], 0
	v_mfma_f32_16x16x32_bf16 v[64:67], v[156:159], v[194:197], 0
	v_mfma_f32_16x16x32_bf16 v[10:13], v[152:155], v[172:175], v[10:13]
	v_mfma_f32_16x16x32_bf16 v[14:17], v[160:163], v[172:175], v[14:17]
	v_mfma_f32_16x16x32_bf16 v[26:29], v[152:155], v[176:179], v[26:29]
	v_mfma_f32_16x16x32_bf16 v[30:33], v[160:163], v[176:179], v[30:33]
	v_mfma_f32_16x16x32_bf16 v[44:47], v[152:155], v[198:201], v[44:47]
	v_mfma_f32_16x16x32_bf16 v[48:51], v[160:163], v[198:201], v[48:51]
	v_mfma_f32_16x16x32_bf16 v[60:63], v[152:155], v[232:235], v[60:63]
	v_mfma_f32_16x16x32_bf16 v[64:67], v[160:163], v[232:235], v[64:67]
	s_setprio 0
	s_barrier
	s_add_i32 s25, 0, 0x18000
	s_add_i32 s31, 0, 0x1c000
	v_add_u32_e32 v132, s25, v1
	v_add_u32_e32 v136, s25, v204
	v_add_u32_e32 v140, s66, v1
	v_add_u32_e32 v144, s66, v204
	v_add_u32_e32 v148, s31, v1
	v_add_u32_e32 v152, s31, v204
	v_add_u32_e32 v156, s67, v1
	v_add_u32_e32 v160, s67, v204
	ds_read_b128 v[132:135], v132
	ds_read_b128 v[136:139], v136
	ds_read_b128 v[140:143], v140
	ds_read_b128 v[144:147], v144
	ds_read_b128 v[148:151], v148
	ds_read_b128 v[152:155], v152
	ds_read_b128 v[156:159], v156
	ds_read_b128 v[160:163], v160
	s_add_u32 s34, s40, 0x80000
	s_addc_u32 s35, s41, 0
	s_mov_b32 m0, s52
	v_lshl_add_u64 v[236:237], s[34:35], 0, v[188:189]
	ds_read_b128 v[164:167], v205 offset:32768
	ds_read_b128 v[168:171], v205 offset:34816
	ds_read_b128 v[172:175], v206 offset:32768
	ds_read_b128 v[176:179], v206 offset:34816
	ds_read_b128 v[190:193], v205 offset:36864
	ds_read_b128 v[194:197], v205 offset:38912
	ds_read_b128 v[198:201], v206 offset:36864
	ds_read_b128 v[232:235], v206 offset:38912
	global_load_lds_dwordx4 v[236:237], off
	v_lshl_add_u64 v[236:237], s[34:35], 0, v[186:187]
	s_mov_b32 m0, s53
	s_nop 0
	global_load_lds_dwordx4 v[236:237], off
	s_waitcnt vmcnt(8)
	s_waitcnt lgkmcnt(0)
	s_barrier
	s_setprio 1
	s_waitcnt lgkmcnt(0)
	v_mfma_f32_16x16x32_bf16 v[68:71], v[132:135], v[164:167], v[68:71]
	v_mfma_f32_16x16x32_bf16 v[72:75], v[140:143], v[164:167], v[72:75]
	v_mfma_f32_16x16x32_bf16 v[84:87], v[132:135], v[168:171], v[84:87]
	v_mfma_f32_16x16x32_bf16 v[88:91], v[140:143], v[168:171], v[88:91]
	v_mfma_f32_16x16x32_bf16 v[100:103], v[132:135], v[190:193], v[100:103]
	v_mfma_f32_16x16x32_bf16 v[104:107], v[140:143], v[190:193], v[104:107]
	v_mfma_f32_16x16x32_bf16 v[116:119], v[132:135], v[194:197], v[116:119]
	v_mfma_f32_16x16x32_bf16 v[120:123], v[140:143], v[194:197], v[120:123]
	v_mfma_f32_16x16x32_bf16 v[68:71], v[136:139], v[172:175], v[68:71]
	v_mfma_f32_16x16x32_bf16 v[72:75], v[144:147], v[172:175], v[72:75]
	v_mfma_f32_16x16x32_bf16 v[84:87], v[136:139], v[176:179], v[84:87]
	v_mfma_f32_16x16x32_bf16 v[88:91], v[144:147], v[176:179], v[88:91]
	v_mfma_f32_16x16x32_bf16 v[100:103], v[136:139], v[198:201], v[100:103]
	v_mfma_f32_16x16x32_bf16 v[104:107], v[144:147], v[198:201], v[104:107]
	v_mfma_f32_16x16x32_bf16 v[116:119], v[136:139], v[232:235], v[116:119]
	v_mfma_f32_16x16x32_bf16 v[120:123], v[144:147], v[232:235], v[120:123]
	s_setprio 0
	s_setprio 1
	v_mfma_f32_16x16x32_bf16 v[76:79], v[148:151], v[164:167], v[76:79]
	v_mfma_f32_16x16x32_bf16 v[80:83], v[156:159], v[164:167], v[80:83]
	v_mfma_f32_16x16x32_bf16 v[92:95], v[148:151], v[168:171], v[92:95]
	v_mfma_f32_16x16x32_bf16 v[96:99], v[156:159], v[168:171], v[96:99]
	v_mfma_f32_16x16x32_bf16 v[108:111], v[148:151], v[190:193], v[108:111]
	v_mfma_f32_16x16x32_bf16 v[112:115], v[156:159], v[190:193], v[112:115]
	v_mfma_f32_16x16x32_bf16 v[124:127], v[148:151], v[194:197], v[124:127]
	v_mfma_f32_16x16x32_bf16 v[128:131], v[156:159], v[194:197], v[128:131]
	v_mfma_f32_16x16x32_bf16 v[76:79], v[152:155], v[172:175], v[76:79]
	v_mfma_f32_16x16x32_bf16 v[80:83], v[160:163], v[172:175], v[80:83]
	v_mfma_f32_16x16x32_bf16 v[92:95], v[152:155], v[176:179], v[92:95]
	v_mfma_f32_16x16x32_bf16 v[96:99], v[160:163], v[176:179], v[96:99]
	v_mfma_f32_16x16x32_bf16 v[108:111], v[152:155], v[198:201], v[108:111]
	v_mfma_f32_16x16x32_bf16 v[112:115], v[160:163], v[198:201], v[112:115]
	v_mfma_f32_16x16x32_bf16 v[124:127], v[152:155], v[232:235], v[124:127]
	v_mfma_f32_16x16x32_bf16 v[128:131], v[160:163], v[232:235], v[128:131]
	s_setprio 0
	s_barrier
	s_add_i32 s25, s25, s33
	v_lshl_add_u64 v[180:181], v[180:181], 0, s[68:69]
	s_mov_b32 m0, s25
	ds_read_b128 v[164:167], v205 offset:49152
	ds_read_b128 v[168:171], v205 offset:51200
	ds_read_b128 v[172:175], v206 offset:49152
	ds_read_b128 v[176:179], v206 offset:51200
	ds_read_b128 v[190:193], v205 offset:53248
	ds_read_b128 v[194:197], v205 offset:55296
	ds_read_b128 v[198:201], v206 offset:53248
	ds_read_b128 v[232:235], v206 offset:55296
	global_load_lds_dwordx4 v[180:181], off
	s_add_i32 m0, s25, 0x2000
	s_add_u32 s28, s28, 0x80080
	v_lshl_add_u64 v[180:181], v[182:183], 0, s[68:69]
	s_addc_u32 s29, s29, 0
	s_add_i32 s25, s31, s33
	global_load_lds_dwordx4 v[180:181], off
	v_lshl_add_u64 v[180:181], s[28:29], 0, v[34:35]
	s_mov_b32 m0, s25
	s_nop 0
	global_load_lds_dwordx4 v[180:181], off
	v_lshl_add_u64 v[180:181], s[28:29], 0, v[184:185]
	s_add_i32 m0, s25, 0x2000
	s_nop 0
	global_load_lds_dwordx4 v[180:181], off
	v_lshl_add_u64 v[180:181], v[202:203], 0, s[68:69]
	s_mov_b32 m0, s54
	s_nop 0
	global_load_lds_dwordx4 v[180:181], off
	v_lshl_add_u64 v[180:181], v[218:219], 0, s[68:69]
	s_mov_b32 m0, s55
	s_nop 0
	global_load_lds_dwordx4 v[180:181], off
	s_waitcnt vmcnt(8)
	s_waitcnt lgkmcnt(0)
	s_barrier
	s_setprio 1
	s_waitcnt lgkmcnt(0)
	v_mfma_f32_16x16x32_bf16 v[2:5], v[132:135], v[164:167], v[2:5]
	v_mfma_f32_16x16x32_bf16 v[6:9], v[140:143], v[164:167], v[6:9]
	v_mfma_f32_16x16x32_bf16 v[18:21], v[132:135], v[168:171], v[18:21]
	v_mfma_f32_16x16x32_bf16 v[22:25], v[140:143], v[168:171], v[22:25]
	v_mfma_f32_16x16x32_bf16 v[36:39], v[132:135], v[190:193], v[36:39]
	v_mfma_f32_16x16x32_bf16 v[40:43], v[140:143], v[190:193], v[40:43]
	v_mfma_f32_16x16x32_bf16 v[52:55], v[132:135], v[194:197], v[52:55]
	v_mfma_f32_16x16x32_bf16 v[56:59], v[140:143], v[194:197], v[56:59]
	v_mfma_f32_16x16x32_bf16 v[2:5], v[136:139], v[172:175], v[2:5]
	v_mfma_f32_16x16x32_bf16 v[6:9], v[144:147], v[172:175], v[6:9]
	v_mfma_f32_16x16x32_bf16 v[18:21], v[136:139], v[176:179], v[18:21]
	v_mfma_f32_16x16x32_bf16 v[22:25], v[144:147], v[176:179], v[22:25]
	v_mfma_f32_16x16x32_bf16 v[36:39], v[136:139], v[198:201], v[36:39]
	v_mfma_f32_16x16x32_bf16 v[40:43], v[144:147], v[198:201], v[40:43]
	v_mfma_f32_16x16x32_bf16 v[52:55], v[136:139], v[232:235], v[52:55]
	v_mfma_f32_16x16x32_bf16 v[56:59], v[144:147], v[232:235], v[56:59]
	s_setprio 0
	s_setprio 1
	v_mfma_f32_16x16x32_bf16 v[10:13], v[148:151], v[164:167], v[10:13]
	v_mfma_f32_16x16x32_bf16 v[14:17], v[156:159], v[164:167], v[14:17]
	v_mfma_f32_16x16x32_bf16 v[26:29], v[148:151], v[168:171], v[26:29]
	v_mfma_f32_16x16x32_bf16 v[30:33], v[156:159], v[168:171], v[30:33]
	v_mfma_f32_16x16x32_bf16 v[44:47], v[148:151], v[190:193], v[44:47]
	v_mfma_f32_16x16x32_bf16 v[48:51], v[156:159], v[190:193], v[48:51]
	v_mfma_f32_16x16x32_bf16 v[60:63], v[148:151], v[194:197], v[60:63]
	v_mfma_f32_16x16x32_bf16 v[64:67], v[156:159], v[194:197], v[64:67]
	v_mfma_f32_16x16x32_bf16 v[10:13], v[152:155], v[172:175], v[10:13]
	v_mfma_f32_16x16x32_bf16 v[14:17], v[160:163], v[172:175], v[14:17]
	v_mfma_f32_16x16x32_bf16 v[26:29], v[152:155], v[176:179], v[26:29]
	v_mfma_f32_16x16x32_bf16 v[30:33], v[160:163], v[176:179], v[30:33]
	v_mfma_f32_16x16x32_bf16 v[44:47], v[152:155], v[198:201], v[44:47]
	v_mfma_f32_16x16x32_bf16 v[48:51], v[160:163], v[198:201], v[48:51]
	v_mfma_f32_16x16x32_bf16 v[60:63], v[152:155], v[232:235], v[60:63]
	v_mfma_f32_16x16x32_bf16 v[64:67], v[160:163], v[232:235], v[64:67]
	s_setprio 0
	s_barrier
	s_add_u32 s22, s22, 0x100
	s_addc_u32 s23, s23, 0
	s_add_u32 s21, s21, 0x100
	s_addc_u32 s24, s24, 0
	s_cmp_ge_u32 s30, s9
	s_mov_b32 s25, s30
	s_cbranch_scc1 .Lpeel_done_P3

.LBB0_1022:
	s_ashr_i32 s23, s22, 31
	s_lshl_b64 s[12:13], s[22:23], 20
	v_readlane_b32 s20, v254, 52
	v_readlane_b32 s21, v254, 53
	s_add_u32 s40, s20, s12
	s_addc_u32 s41, s21, s13
	s_and_b64 s[12:13], s[38:39], exec
	s_cselect_b32 s12, s41, s9
	s_cselect_b32 s13, s40, s8
	s_ashr_i32 s19, s18, 31
	s_lshl_b64 s[20:21], s[18:19], 20
	v_readlane_b32 s24, v254, 48
	v_readlane_b32 s25, v254, 49
	s_add_u32 s42, s24, s20
	s_addc_u32 s43, s25, s21
	s_and_b64 s[20:21], s[38:39], exec
	s_cselect_b32 s19, s43, s29
	s_cselect_b32 s20, s42, s28
	s_add_u32 s8, s8, 0x80080
	s_addc_u32 s9, s9, 0
	s_add_u32 s21, s28, 0x100
	s_addc_u32 s23, s29, 0
	s_mov_b32 s24, -2
	v_readlane_b32 s35, v255, 20
	v_readlane_b32 s57, v255, 21
	v_readlane_b32 s58, v255, 22
	v_readlane_b32 s59, v255, 23
	s_mov_b64 s[60:61], 0x80
	s_add_u32 s25, s8, 0xfff80080
	s_addc_u32 s28, s9, -1
	s_add_i32 s30, 0, 0x10000
	s_cmp_eq_u32 s24, 28
	s_cselect_b32 s45, s12, s28
	s_cselect_b32 s44, s13, s25
	v_add_u32_e32 v138, s30, v1
	v_add_u32_e32 v142, s30, v150
	v_add_u32_e32 v146, s35, v1
	v_add_u32_e32 v153, s35, v150
	s_cselect_b32 s29, s19, s23
	s_cselect_b32 s28, s20, s21
	s_add_i32 s25, 0, 0x14000
	ds_read_b128 v[138:141], v138
	ds_read_b128 v[142:145], v142
	ds_read_b128 v[146:149], v146
	ds_read_b128 v[154:157], v153
	v_add_u32_e32 v153, s25, v1
	v_add_u32_e32 v162, s25, v150
	ds_read_b128 v[158:161], v153
	ds_read_b128 v[162:165], v162
	v_add_u32_e32 v153, s57, v1
	v_add_u32_e32 v170, s57, v150
	ds_read_b128 v[166:169], v153
	ds_read_b128 v[170:173], v170
	v_lshl_add_u64 v[178:179], s[8:9], 0, v[136:137]
	s_add_i32 m0, s46, 0xc000
	ds_read_b128 v[174:177], v151
	ds_read_b128 v[184:187], v151 offset:2048
	ds_read_b128 v[188:191], v152
	ds_read_b128 v[192:195], v152 offset:2048
	ds_read_b128 v[196:199], v151 offset:4096
	ds_read_b128 v[200:203], v151 offset:6144
	ds_read_b128 v[204:207], v152 offset:4096
	ds_read_b128 v[208:211], v152 offset:6144
	global_load_lds_dwordx4 v[178:179], off
	v_lshl_add_u64 v[178:179], s[8:9], 0, v[134:135]
	s_add_i32 m0, s46, 0xe000
	s_nop 0
	global_load_lds_dwordx4 v[178:179], off
	s_waitcnt vmcnt(8)
	s_waitcnt lgkmcnt(0)
	s_barrier
	s_setprio 1
	s_waitcnt lgkmcnt(0)
	v_mfma_f32_16x16x32_bf16 v[128:131], v[138:141], v[174:177], 0
	v_mfma_f32_16x16x32_bf16 v[124:127], v[146:149], v[174:177], 0
	v_mfma_f32_16x16x32_bf16 v[112:115], v[138:141], v[184:187], 0
	v_mfma_f32_16x16x32_bf16 v[108:111], v[146:149], v[184:187], 0
	v_mfma_f32_16x16x32_bf16 v[96:99], v[138:141], v[196:199], 0
	v_mfma_f32_16x16x32_bf16 v[92:95], v[146:149], v[196:199], 0
	v_mfma_f32_16x16x32_bf16 v[80:83], v[138:141], v[200:203], 0
	v_mfma_f32_16x16x32_bf16 v[76:79], v[146:149], v[200:203], 0
	v_mfma_f32_16x16x32_bf16 v[128:131], v[142:145], v[188:191], v[128:131]
	v_mfma_f32_16x16x32_bf16 v[124:127], v[154:157], v[188:191], v[124:127]
	v_mfma_f32_16x16x32_bf16 v[112:115], v[142:145], v[192:195], v[112:115]
	v_mfma_f32_16x16x32_bf16 v[108:111], v[154:157], v[192:195], v[108:111]
	v_mfma_f32_16x16x32_bf16 v[96:99], v[142:145], v[204:207], v[96:99]
	v_mfma_f32_16x16x32_bf16 v[92:95], v[154:157], v[204:207], v[92:95]
	v_mfma_f32_16x16x32_bf16 v[80:83], v[142:145], v[208:211], v[80:83]
	v_mfma_f32_16x16x32_bf16 v[76:79], v[154:157], v[208:211], v[76:79]
	s_setprio 0
	s_setprio 1
	v_mfma_f32_16x16x32_bf16 v[120:123], v[158:161], v[174:177], 0
	v_mfma_f32_16x16x32_bf16 v[116:119], v[166:169], v[174:177], 0
	v_mfma_f32_16x16x32_bf16 v[104:107], v[158:161], v[184:187], 0
	v_mfma_f32_16x16x32_bf16 v[100:103], v[166:169], v[184:187], 0
	v_mfma_f32_16x16x32_bf16 v[88:91], v[158:161], v[196:199], 0
	v_mfma_f32_16x16x32_bf16 v[84:87], v[166:169], v[196:199], 0
	v_mfma_f32_16x16x32_bf16 v[72:75], v[158:161], v[200:203], 0
	v_mfma_f32_16x16x32_bf16 v[68:71], v[166:169], v[200:203], 0
	v_mfma_f32_16x16x32_bf16 v[120:123], v[162:165], v[188:191], v[120:123]
	v_mfma_f32_16x16x32_bf16 v[116:119], v[170:173], v[188:191], v[116:119]
	v_mfma_f32_16x16x32_bf16 v[104:107], v[162:165], v[192:195], v[104:107]
	v_mfma_f32_16x16x32_bf16 v[100:103], v[170:173], v[192:195], v[100:103]
	v_mfma_f32_16x16x32_bf16 v[88:91], v[162:165], v[204:207], v[88:91]
	v_mfma_f32_16x16x32_bf16 v[84:87], v[170:173], v[204:207], v[84:87]
	v_mfma_f32_16x16x32_bf16 v[72:75], v[162:165], v[208:211], v[72:75]
	v_mfma_f32_16x16x32_bf16 v[68:71], v[170:173], v[208:211], v[68:71]
	s_setprio 0
	s_barrier
	s_add_i32 s30, s30, s33
	v_lshl_add_u64 v[178:179], s[28:29], 0, v[34:35]
	s_mov_b32 m0, s30
	ds_read_b128 v[174:177], v151 offset:16384
	ds_read_b128 v[184:187], v151 offset:18432
	ds_read_b128 v[188:191], v152 offset:16384
	ds_read_b128 v[192:195], v152 offset:18432
	ds_read_b128 v[196:199], v151 offset:20480
	ds_read_b128 v[200:203], v151 offset:22528
	ds_read_b128 v[204:207], v152 offset:20480
	ds_read_b128 v[208:211], v152 offset:22528
	global_load_lds_dwordx4 v[178:179], off
	s_add_i32 m0, s30, 0x2000
	s_add_u32 s30, s28, 0x80000
	v_lshl_add_u64 v[180:181], s[28:29], 0, v[132:133]
	s_addc_u32 s31, s29, 0
	s_add_i32 s25, s25, s33
	global_load_lds_dwordx4 v[180:181], off
	v_lshl_add_u64 v[182:183], s[30:31], 0, v[34:35]
	s_mov_b32 m0, s25
	v_lshl_add_u64 v[212:213], s[44:45], 0, v[134:135]
	global_load_lds_dwordx4 v[182:183], off
	v_lshl_add_u64 v[182:183], s[30:31], 0, v[132:133]
	s_add_i32 m0, s25, 0x2000
	s_nop 0
	global_load_lds_dwordx4 v[182:183], off
	v_lshl_add_u64 v[182:183], s[44:45], 0, v[136:137]
	s_mov_b32 m0, s46
	s_nop 0
	global_load_lds_dwordx4 v[182:183], off
	s_mov_b32 m0, s47
	s_nop 0
	global_load_lds_dwordx4 v[212:213], off
	s_waitcnt vmcnt(8)
	s_waitcnt lgkmcnt(0)
	s_barrier
	s_setprio 1
	s_waitcnt lgkmcnt(0)
	v_mfma_f32_16x16x32_bf16 v[64:67], v[138:141], v[174:177], 0
	v_mfma_f32_16x16x32_bf16 v[60:63], v[146:149], v[174:177], 0
	v_mfma_f32_16x16x32_bf16 v[48:51], v[138:141], v[184:187], 0
	v_mfma_f32_16x16x32_bf16 v[44:47], v[146:149], v[184:187], 0
	v_mfma_f32_16x16x32_bf16 v[30:33], v[138:141], v[196:199], 0
	v_mfma_f32_16x16x32_bf16 v[26:29], v[146:149], v[196:199], 0
	v_mfma_f32_16x16x32_bf16 v[14:17], v[138:141], v[200:203], 0
	v_mfma_f32_16x16x32_bf16 v[10:13], v[146:149], v[200:203], 0
	v_mfma_f32_16x16x32_bf16 v[64:67], v[142:145], v[188:191], v[64:67]
	v_mfma_f32_16x16x32_bf16 v[60:63], v[154:157], v[188:191], v[60:63]
	v_mfma_f32_16x16x32_bf16 v[48:51], v[142:145], v[192:195], v[48:51]
	v_mfma_f32_16x16x32_bf16 v[44:47], v[154:157], v[192:195], v[44:47]
	v_mfma_f32_16x16x32_bf16 v[30:33], v[142:145], v[204:207], v[30:33]
	v_mfma_f32_16x16x32_bf16 v[26:29], v[154:157], v[204:207], v[26:29]
	v_mfma_f32_16x16x32_bf16 v[14:17], v[142:145], v[208:211], v[14:17]
	v_mfma_f32_16x16x32_bf16 v[10:13], v[154:157], v[208:211], v[10:13]
	s_setprio 0
	s_setprio 1
	v_mfma_f32_16x16x32_bf16 v[56:59], v[158:161], v[174:177], 0
	v_mfma_f32_16x16x32_bf16 v[52:55], v[166:169], v[174:177], 0
	v_mfma_f32_16x16x32_bf16 v[40:43], v[158:161], v[184:187], 0
	v_mfma_f32_16x16x32_bf16 v[36:39], v[166:169], v[184:187], 0
	v_mfma_f32_16x16x32_bf16 v[22:25], v[158:161], v[196:199], 0
	v_mfma_f32_16x16x32_bf16 v[18:21], v[166:169], v[196:199], 0
	v_mfma_f32_16x16x32_bf16 v[6:9], v[158:161], v[200:203], 0
	v_mfma_f32_16x16x32_bf16 v[2:5], v[166:169], v[200:203], 0
	v_mfma_f32_16x16x32_bf16 v[56:59], v[162:165], v[188:191], v[56:59]
	v_mfma_f32_16x16x32_bf16 v[52:55], v[170:173], v[188:191], v[52:55]
	v_mfma_f32_16x16x32_bf16 v[40:43], v[162:165], v[192:195], v[40:43]
	v_mfma_f32_16x16x32_bf16 v[36:39], v[170:173], v[192:195], v[36:39]
	v_mfma_f32_16x16x32_bf16 v[22:25], v[162:165], v[204:207], v[22:25]
	v_mfma_f32_16x16x32_bf16 v[18:21], v[170:173], v[204:207], v[18:21]
	v_mfma_f32_16x16x32_bf16 v[6:9], v[162:165], v[208:211], v[6:9]
	v_mfma_f32_16x16x32_bf16 v[2:5], v[170:173], v[208:211], v[2:5]
	s_setprio 0
	s_barrier
	s_add_i32 s25, 0, 0x18000
	v_add_u32_e32 v138, s25, v1
	v_add_u32_e32 v142, s25, v150
	v_add_u32_e32 v146, s58, v1
	v_add_u32_e32 v153, s58, v150
	s_add_i32 s34, 0, 0x1c000
	ds_read_b128 v[138:141], v138
	ds_read_b128 v[142:145], v142
	ds_read_b128 v[146:149], v146
	ds_read_b128 v[154:157], v153
	v_add_u32_e32 v153, s34, v1
	v_add_u32_e32 v162, s34, v150
	ds_read_b128 v[158:161], v153
	ds_read_b128 v[162:165], v162
	v_add_u32_e32 v153, s59, v1
	v_add_u32_e32 v170, s59, v150
	ds_read_b128 v[166:169], v153
	ds_read_b128 v[170:173], v170
	s_add_u32 s30, s44, 0x80000
	s_addc_u32 s31, s45, 0
	s_mov_b32 m0, s48
	v_lshl_add_u64 v[218:219], s[30:31], 0, v[136:137]
	ds_read_b128 v[174:177], v151 offset:32768
	ds_read_b128 v[184:187], v151 offset:34816
	ds_read_b128 v[188:191], v152 offset:32768
	ds_read_b128 v[192:195], v152 offset:34816
	ds_read_b128 v[196:199], v151 offset:36864
	ds_read_b128 v[200:203], v151 offset:38912
	ds_read_b128 v[204:207], v152 offset:36864
	ds_read_b128 v[208:211], v152 offset:38912
	global_load_lds_dwordx4 v[218:219], off
	v_lshl_add_u64 v[218:219], s[30:31], 0, v[134:135]
	s_mov_b32 m0, s49
	s_nop 0
	global_load_lds_dwordx4 v[218:219], off
	s_waitcnt vmcnt(8)
	s_waitcnt lgkmcnt(0)
	s_barrier
	s_setprio 1
	s_waitcnt lgkmcnt(0)
	v_mfma_f32_16x16x32_bf16 v[128:131], v[138:141], v[174:177], v[128:131]
	v_mfma_f32_16x16x32_bf16 v[124:127], v[146:149], v[174:177], v[124:127]
	v_mfma_f32_16x16x32_bf16 v[112:115], v[138:141], v[184:187], v[112:115]
	v_mfma_f32_16x16x32_bf16 v[108:111], v[146:149], v[184:187], v[108:111]
	v_mfma_f32_16x16x32_bf16 v[96:99], v[138:141], v[196:199], v[96:99]
	v_mfma_f32_16x16x32_bf16 v[92:95], v[146:149], v[196:199], v[92:95]
	v_mfma_f32_16x16x32_bf16 v[80:83], v[138:141], v[200:203], v[80:83]
	v_mfma_f32_16x16x32_bf16 v[76:79], v[146:149], v[200:203], v[76:79]
	v_mfma_f32_16x16x32_bf16 v[128:131], v[142:145], v[188:191], v[128:131]
	v_mfma_f32_16x16x32_bf16 v[124:127], v[154:157], v[188:191], v[124:127]
	v_mfma_f32_16x16x32_bf16 v[112:115], v[142:145], v[192:195], v[112:115]
	v_mfma_f32_16x16x32_bf16 v[108:111], v[154:157], v[192:195], v[108:111]
	v_mfma_f32_16x16x32_bf16 v[96:99], v[142:145], v[204:207], v[96:99]
	v_mfma_f32_16x16x32_bf16 v[92:95], v[154:157], v[204:207], v[92:95]
	v_mfma_f32_16x16x32_bf16 v[80:83], v[142:145], v[208:211], v[80:83]
	v_mfma_f32_16x16x32_bf16 v[76:79], v[154:157], v[208:211], v[76:79]
	s_setprio 0
	s_setprio 1
	v_mfma_f32_16x16x32_bf16 v[120:123], v[158:161], v[174:177], v[120:123]
	v_mfma_f32_16x16x32_bf16 v[116:119], v[166:169], v[174:177], v[116:119]
	v_mfma_f32_16x16x32_bf16 v[104:107], v[158:161], v[184:187], v[104:107]
	v_mfma_f32_16x16x32_bf16 v[100:103], v[166:169], v[184:187], v[100:103]
	v_mfma_f32_16x16x32_bf16 v[88:91], v[158:161], v[196:199], v[88:91]
	v_mfma_f32_16x16x32_bf16 v[84:87], v[166:169], v[196:199], v[84:87]
	v_mfma_f32_16x16x32_bf16 v[72:75], v[158:161], v[200:203], v[72:75]
	v_mfma_f32_16x16x32_bf16 v[68:71], v[166:169], v[200:203], v[68:71]
	v_mfma_f32_16x16x32_bf16 v[120:123], v[162:165], v[188:191], v[120:123]
	v_mfma_f32_16x16x32_bf16 v[116:119], v[170:173], v[188:191], v[116:119]
	v_mfma_f32_16x16x32_bf16 v[104:107], v[162:165], v[192:195], v[104:107]
	v_mfma_f32_16x16x32_bf16 v[100:103], v[170:173], v[192:195], v[100:103]
	v_mfma_f32_16x16x32_bf16 v[88:91], v[162:165], v[204:207], v[88:91]
	v_mfma_f32_16x16x32_bf16 v[84:87], v[170:173], v[204:207], v[84:87]
	v_mfma_f32_16x16x32_bf16 v[72:75], v[162:165], v[208:211], v[72:75]
	v_mfma_f32_16x16x32_bf16 v[68:71], v[170:173], v[208:211], v[68:71]
	s_setprio 0
	s_barrier
	s_add_i32 s25, s25, s33
	v_lshl_add_u64 v[178:179], v[178:179], 0, s[60:61]
	s_mov_b32 m0, s25
	ds_read_b128 v[174:177], v151 offset:49152
	ds_read_b128 v[184:187], v151 offset:51200
	ds_read_b128 v[188:191], v152 offset:49152
	ds_read_b128 v[192:195], v152 offset:51200
	ds_read_b128 v[196:199], v151 offset:53248
	ds_read_b128 v[200:203], v151 offset:55296
	ds_read_b128 v[204:207], v152 offset:53248
	ds_read_b128 v[208:211], v152 offset:55296
	global_load_lds_dwordx4 v[178:179], off
	s_add_i32 m0, s25, 0x2000
	s_add_u32 s28, s28, 0x80080
	v_lshl_add_u64 v[178:179], v[180:181], 0, s[60:61]
	s_addc_u32 s29, s29, 0
	s_add_i32 s25, s34, s33
	global_load_lds_dwordx4 v[178:179], off
	v_lshl_add_u64 v[178:179], s[28:29], 0, v[34:35]
	s_mov_b32 m0, s25
	s_nop 0
	global_load_lds_dwordx4 v[178:179], off
	v_lshl_add_u64 v[178:179], s[28:29], 0, v[132:133]
	s_add_i32 m0, s25, 0x2000
	s_nop 0
	global_load_lds_dwordx4 v[178:179], off
	v_lshl_add_u64 v[178:179], v[182:183], 0, s[60:61]
	s_mov_b32 m0, s52
	s_nop 0
	global_load_lds_dwordx4 v[178:179], off
	v_lshl_add_u64 v[178:179], v[212:213], 0, s[60:61]
	s_mov_b32 m0, s53
	s_nop 0
	global_load_lds_dwordx4 v[178:179], off
	s_waitcnt vmcnt(8)
	s_waitcnt lgkmcnt(0)
	s_barrier
	s_setprio 1
	s_waitcnt lgkmcnt(0)
	v_mfma_f32_16x16x32_bf16 v[64:67], v[138:141], v[174:177], v[64:67]
	v_mfma_f32_16x16x32_bf16 v[60:63], v[146:149], v[174:177], v[60:63]
	v_mfma_f32_16x16x32_bf16 v[48:51], v[138:141], v[184:187], v[48:51]
	v_mfma_f32_16x16x32_bf16 v[44:47], v[146:149], v[184:187], v[44:47]
	v_mfma_f32_16x16x32_bf16 v[30:33], v[138:141], v[196:199], v[30:33]
	v_mfma_f32_16x16x32_bf16 v[26:29], v[146:149], v[196:199], v[26:29]
	v_mfma_f32_16x16x32_bf16 v[14:17], v[138:141], v[200:203], v[14:17]
	v_mfma_f32_16x16x32_bf16 v[10:13], v[146:149], v[200:203], v[10:13]
	v_mfma_f32_16x16x32_bf16 v[64:67], v[142:145], v[188:191], v[64:67]
	v_mfma_f32_16x16x32_bf16 v[60:63], v[154:157], v[188:191], v[60:63]
	v_mfma_f32_16x16x32_bf16 v[48:51], v[142:145], v[192:195], v[48:51]
	v_mfma_f32_16x16x32_bf16 v[44:47], v[154:157], v[192:195], v[44:47]
	v_mfma_f32_16x16x32_bf16 v[30:33], v[142:145], v[204:207], v[30:33]
	v_mfma_f32_16x16x32_bf16 v[26:29], v[154:157], v[204:207], v[26:29]
	v_mfma_f32_16x16x32_bf16 v[14:17], v[142:145], v[208:211], v[14:17]
	v_mfma_f32_16x16x32_bf16 v[10:13], v[154:157], v[208:211], v[10:13]
	s_setprio 0
	s_setprio 1
	v_mfma_f32_16x16x32_bf16 v[56:59], v[158:161], v[174:177], v[56:59]
	v_mfma_f32_16x16x32_bf16 v[52:55], v[166:169], v[174:177], v[52:55]
	v_mfma_f32_16x16x32_bf16 v[40:43], v[158:161], v[184:187], v[40:43]
	v_mfma_f32_16x16x32_bf16 v[36:39], v[166:169], v[184:187], v[36:39]
	v_mfma_f32_16x16x32_bf16 v[22:25], v[158:161], v[196:199], v[22:25]
	v_mfma_f32_16x16x32_bf16 v[18:21], v[166:169], v[196:199], v[18:21]
	v_mfma_f32_16x16x32_bf16 v[6:9], v[158:161], v[200:203], v[6:9]
	v_mfma_f32_16x16x32_bf16 v[2:5], v[166:169], v[200:203], v[2:5]
	v_mfma_f32_16x16x32_bf16 v[56:59], v[162:165], v[188:191], v[56:59]
	v_mfma_f32_16x16x32_bf16 v[52:55], v[170:173], v[188:191], v[52:55]
	v_mfma_f32_16x16x32_bf16 v[40:43], v[162:165], v[192:195], v[40:43]
	v_mfma_f32_16x16x32_bf16 v[36:39], v[170:173], v[192:195], v[36:39]
	v_mfma_f32_16x16x32_bf16 v[22:25], v[162:165], v[204:207], v[22:25]
	v_mfma_f32_16x16x32_bf16 v[18:21], v[170:173], v[204:207], v[18:21]
	v_mfma_f32_16x16x32_bf16 v[6:9], v[162:165], v[208:211], v[6:9]
	v_mfma_f32_16x16x32_bf16 v[2:5], v[170:173], v[208:211], v[2:5]
	s_setprio 0
	s_barrier
	s_add_i32 s24, s24, 2
	s_add_u32 s8, s8, 0x100
	s_addc_u32 s9, s9, 0
	s_add_u32 s21, s21, 0x100
	s_addc_u32 s23, s23, 0
	s_cmp_gt_u32 s24, 29
	s_cbranch_scc1 .Lpeel_done_P4

.Lpeel_done_P4:
	s_and_b64 vcc, exec, s[6:7]
	s_cbranch_vccz .LBB0_1026
	s_barrier
.LBB0_1026:
	v_mov_b32_e32 v140, v0
	s_lshl_b32 s11, s11, 8
	s_add_i32 s8, s11, s50
	v_bfe_u32 v138, v140, 2, 4
	v_or_b32_e32 v144, s8, v138
	s_lshl_b32 s8, s10, 8
	v_lshlrev_b32_e32 v138, 3, v140
	v_and_or_b32 v138, v138, 24, s8
	v_or_b32_e32 v138, s51, v138
	v_and_b32_e32 v153, 15, v140
	v_ashrrev_i32_e32 v139, 31, v138
	v_readlane_b32 s12, v254, 38
	v_bfe_u32 v154, v140, 4, 2
	v_and_b32_e32 v141, 63, v140
	v_lshlrev_b32_e32 v142, 4, v153
	v_lshlrev_b32_e32 v140, 6, v140
	s_movk_i32 s8, 0xfc
	v_lshlrev_b64 v[138:139], 1, v[138:139]
	v_readlane_b32 s13, v254, 39
	v_ashrrev_i32_e32 v145, 31, v144
	v_lshl_or_b32 v156, v154, 2, v142
	v_bitop3_b32 v155, v140, s8, v141 bitop3:0xc8
	v_lshl_add_u64 v[140:141], s[12:13], 0, v[138:139]
	v_lshlrev_b64 v[142:143], 12, v[144:145]
	v_lshl_add_u64 v[146:147], v[140:141], 0, v[142:143]
	global_load_dwordx4 v[158:161], v[146:147], off
	global_load_dwordx4 v[162:165], v[146:147], off offset:256
	v_or_b32_e32 v146, 16, v144
	v_ashrrev_i32_e32 v147, 31, v146
	v_lshlrev_b64 v[148:149], 12, v[146:147]
	v_lshl_add_u64 v[146:147], v[140:141], 0, v[148:149]
	global_load_dwordx4 v[166:169], v[146:147], off
	global_load_dwordx4 v[170:173], v[146:147], off offset:256
	v_or_b32_e32 v146, 32, v144
	v_ashrrev_i32_e32 v147, 31, v146
	v_lshlrev_b64 v[146:147], 12, v[146:147]
	v_lshl_add_u64 v[174:175], v[140:141], 0, v[146:147]
	global_load_dwordx4 v[186:189], v[174:175], off
	global_load_dwordx4 v[190:193], v[174:175], off offset:256
	v_or_b32_e32 v144, 48, v144
	v_ashrrev_i32_e32 v145, 31, v144
	v_lshlrev_b64 v[144:145], 12, v[144:145]
	v_lshl_add_u64 v[174:175], v[140:141], 0, v[144:145]
	global_load_dwordx4 v[194:197], v[174:175], off
	global_load_dwordx4 v[198:201], v[174:175], off offset:256
	s_mov_b64 s[8:9], 0x80000
	v_cmp_eq_u32_e32 vcc, 0, v154
	s_waitcnt vmcnt(0)
	ds_bpermute_b32 v180, v156, v158
	ds_bpermute_b32 v181, v156, v159
	ds_bpermute_b32 v182, v156, v160
	ds_bpermute_b32 v183, v156, v161
	ds_bpermute_b32 v185, v156, v162
	ds_bpermute_b32 v202, v156, v163
	ds_bpermute_b32 v174, v156, v172
	ds_bpermute_b32 v203, v156, v164
	ds_bpermute_b32 v204, v156, v165
	ds_bpermute_b32 v184, v156, v166
	ds_bpermute_b32 v172, v156, v186
	s_waitcnt lgkmcnt(10)
	v_lshlrev_b32_e32 v186, 16, v180
	v_and_b32_e32 v180, 0xffff0000, v180
	v_add_f32_e32 v129, v129, v180
	s_waitcnt lgkmcnt(9)
	v_lshlrev_b32_e32 v180, 16, v181
	v_add_f32_e32 v180, v130, v180
	v_and_b32_e32 v130, 0xffff0000, v181
	v_add_f32_e32 v131, v131, v130
	s_waitcnt lgkmcnt(8)
	v_lshlrev_b32_e32 v130, 16, v182
	v_add_f32_e32 v124, v124, v130
	v_and_b32_e32 v130, 0xffff0000, v182
	v_add_f32_e32 v125, v125, v130
	s_waitcnt lgkmcnt(7)
	v_lshlrev_b32_e32 v130, 16, v183
	v_add_f32_e32 v126, v126, v130
	v_and_b32_e32 v130, 0xffff0000, v183
	v_add_f32_e32 v128, v128, v186
	v_add_f32_e32 v127, v127, v130
	v_mul_f32_e32 v130, v129, v129
	v_mul_f32_e32 v181, v131, v131
	v_fmac_f32_e32 v130, v128, v128
	v_fmac_f32_e32 v181, v180, v180
	v_add_f32_e32 v130, v130, v181
	v_mul_f32_e32 v181, v125, v125
	v_mul_f32_e32 v182, v127, v127
	v_cvt_pk_bf16_f32 v128, v128, v129
	v_cvt_pk_bf16_f32 v129, v180, v131
	v_cvt_pk_bf16_f32 v131, v124, v125
	v_cvt_pk_bf16_f32 v127, v126, v127
	v_fmac_f32_e32 v181, v124, v124
	v_fmac_f32_e32 v182, v126, v126
	ds_bpermute_b32 v124, v155, v128
	ds_bpermute_b32 v125, v155, v129
	ds_bpermute_b32 v126, v155, v131
	ds_bpermute_b32 v127, v155, v127
	v_lshl_add_u64 v[128:129], s[12:13], 0, v[142:143]
	v_lshl_add_u64 v[128:129], v[128:129], 0, v[138:139]
	ds_bpermute_b32 v179, v156, v167
	ds_bpermute_b32 v178, v156, v168
	s_waitcnt lgkmcnt(2)
	global_store_dwordx4 v[128:129], v[124:127], off
	ds_bpermute_b32 v177, v156, v169
	ds_bpermute_b32 v176, v156, v170
	v_lshlrev_b32_e32 v124, 16, v185
	v_add_f32_e32 v120, v120, v124
	v_and_b32_e32 v124, 0xffff0000, v185
	v_add_f32_e32 v121, v121, v124
	v_lshlrev_b32_e32 v124, 16, v202
	v_add_f32_e32 v122, v122, v124
	v_and_b32_e32 v124, 0xffff0000, v202
	v_add_f32_e32 v123, v123, v124
	v_lshlrev_b32_e32 v124, 16, v203
	v_add_f32_e32 v124, v116, v124
	v_and_b32_e32 v116, 0xffff0000, v203
	v_add_f32_e32 v117, v117, v116
	v_lshlrev_b32_e32 v116, 16, v204
	v_add_f32_e32 v118, v118, v116
	v_and_b32_e32 v116, 0xffff0000, v204
	v_add_f32_e32 v119, v119, v116
	v_mul_f32_e32 v116, v121, v121
	v_mul_f32_e32 v125, v123, v123
	v_fmac_f32_e32 v116, v120, v120
	v_fmac_f32_e32 v125, v122, v122
	v_add_f32_e32 v116, v116, v125
	v_mul_f32_e32 v125, v117, v117
	v_mul_f32_e32 v126, v119, v119
	v_cvt_pk_bf16_f32 v120, v120, v121
	v_cvt_pk_bf16_f32 v121, v122, v123
	v_cvt_pk_bf16_f32 v117, v124, v117
	v_fmac_f32_e32 v126, v118, v118
	v_cvt_pk_bf16_f32 v122, v118, v119
	ds_bpermute_b32 v118, v155, v120
	ds_bpermute_b32 v120, v155, v117
	v_lshlrev_b32_e32 v117, 16, v184
	v_add_f32_e32 v112, v112, v117
	v_and_b32_e32 v117, 0xffff0000, v184
	v_add_f32_e32 v117, v113, v117
	s_waitcnt lgkmcnt(5)
	v_lshlrev_b32_e32 v113, 16, v179
	ds_bpermute_b32 v119, v155, v121
	ds_bpermute_b32 v121, v155, v122
	v_add_f32_e32 v113, v114, v113
	v_and_b32_e32 v114, 0xffff0000, v179
	v_add_f32_e32 v114, v115, v114
	s_waitcnt lgkmcnt(6)
	v_lshlrev_b32_e32 v115, 16, v178
	v_add_f32_e32 v108, v108, v115
	v_and_b32_e32 v115, 0xffff0000, v178
	ds_bpermute_b32 v175, v156, v171
	v_add_f32_e32 v115, v109, v115
	s_waitcnt lgkmcnt(6)
	v_lshlrev_b32_e32 v109, 16, v177
	v_add_f32_e32 v109, v110, v109
	v_and_b32_e32 v110, 0xffff0000, v177
	s_waitcnt lgkmcnt(1)
	global_store_dwordx4 v[128:129], v[118:121], off offset:256
	v_add_f32_e32 v110, v111, v110
	v_cvt_pk_bf16_f32 v111, v112, v117
	ds_bpermute_b32 v118, v155, v111
	v_lshlrev_b32_e32 v111, 16, v176
	ds_bpermute_b32 v173, v156, v173
	v_add_f32_e32 v104, v104, v111
	v_and_b32_e32 v111, 0xffff0000, v176
	v_cvt_pk_bf16_f32 v119, v113, v114
	v_cvt_pk_bf16_f32 v120, v108, v115
	v_cvt_pk_bf16_f32 v121, v109, v110
	v_add_f32_e32 v111, v105, v111
	s_waitcnt lgkmcnt(2)
	v_lshlrev_b32_e32 v105, 16, v175
	ds_bpermute_b32 v119, v155, v119
	ds_bpermute_b32 v120, v155, v120
	ds_bpermute_b32 v121, v155, v121
	v_add_f32_e32 v105, v106, v105
	v_and_b32_e32 v106, 0xffff0000, v175
	v_add_f32_e32 v106, v107, v106
	v_lshlrev_b32_e32 v107, 16, v174
	v_add_f32_e32 v100, v100, v107
	v_and_b32_e32 v107, 0xffff0000, v174
	ds_bpermute_b32 v171, v156, v187
	v_lshl_add_u64 v[122:123], s[12:13], 0, v[148:149]
	v_add_f32_e32 v107, v101, v107
	s_waitcnt lgkmcnt(4)
	v_lshlrev_b32_e32 v101, 16, v173
	v_lshl_add_u64 v[122:123], v[122:123], 0, v[138:139]
	v_add_f32_e32 v101, v102, v101
	v_and_b32_e32 v102, 0xffff0000, v173
	ds_bpermute_b32 v170, v156, v188
	s_waitcnt lgkmcnt(2)
	global_store_dwordx4 v[122:123], v[118:121], off
	v_add_f32_e32 v102, v103, v102
	v_cvt_pk_bf16_f32 v103, v104, v111
	ds_bpermute_b32 v118, v155, v103
	v_lshlrev_b32_e32 v103, 16, v172
	ds_bpermute_b32 v169, v156, v189
	v_add_f32_e32 v96, v96, v103
	v_and_b32_e32 v103, 0xffff0000, v172
	v_cvt_pk_bf16_f32 v119, v105, v106
	v_cvt_pk_bf16_f32 v120, v100, v107
	v_cvt_pk_bf16_f32 v121, v101, v102
	v_add_f32_e32 v103, v97, v103
	s_waitcnt lgkmcnt(3)
	v_lshlrev_b32_e32 v97, 16, v171
	ds_bpermute_b32 v119, v155, v119
	ds_bpermute_b32 v120, v155, v120
	ds_bpermute_b32 v121, v155, v121
	v_add_f32_e32 v97, v98, v97
	v_and_b32_e32 v98, 0xffff0000, v171
	ds_bpermute_b32 v168, v156, v190
	v_add_f32_e32 v98, v99, v98
	s_waitcnt lgkmcnt(6)
	v_lshlrev_b32_e32 v99, 16, v170
	v_add_f32_e32 v92, v92, v99
	v_and_b32_e32 v99, 0xffff0000, v170
	ds_bpermute_b32 v167, v156, v191
	v_add_f32_e32 v99, v93, v99
	s_waitcnt lgkmcnt(5)
	v_lshlrev_b32_e32 v93, 16, v169
	v_add_f32_e32 v93, v94, v93
	v_and_b32_e32 v94, 0xffff0000, v169
	ds_bpermute_b32 v166, v156, v192
	s_waitcnt lgkmcnt(3)
	global_store_dwordx4 v[122:123], v[118:121], off offset:256
	v_add_f32_e32 v94, v95, v94
	v_cvt_pk_bf16_f32 v95, v96, v103
	ds_bpermute_b32 v118, v155, v95
	s_waitcnt lgkmcnt(3)
	v_lshlrev_b32_e32 v95, 16, v168
	ds_bpermute_b32 v165, v156, v193
	v_add_f32_e32 v88, v88, v95
	v_and_b32_e32 v95, 0xffff0000, v168
	v_cvt_pk_bf16_f32 v119, v97, v98
	v_cvt_pk_bf16_f32 v120, v92, v99
	v_cvt_pk_bf16_f32 v121, v93, v94
	v_add_f32_e32 v95, v89, v95
	s_waitcnt lgkmcnt(3)
	v_lshlrev_b32_e32 v89, 16, v167
	ds_bpermute_b32 v119, v155, v119
	ds_bpermute_b32 v120, v155, v120
	ds_bpermute_b32 v121, v155, v121
	v_add_f32_e32 v89, v90, v89
	v_and_b32_e32 v90, 0xffff0000, v167
	ds_bpermute_b32 v164, v156, v194
	v_add_f32_e32 v90, v91, v90
	s_waitcnt lgkmcnt(6)
	v_lshlrev_b32_e32 v91, 16, v166
	v_add_f32_e32 v84, v84, v91
	v_and_b32_e32 v91, 0xffff0000, v166
	ds_bpermute_b32 v163, v156, v195
	v_lshl_add_u64 v[122:123], s[12:13], 0, v[146:147]
	v_add_f32_e32 v91, v85, v91
	s_waitcnt lgkmcnt(5)
	v_lshlrev_b32_e32 v85, 16, v165
	v_lshl_add_u64 v[122:123], v[122:123], 0, v[138:139]
	v_add_f32_e32 v85, v86, v85
	v_and_b32_e32 v86, 0xffff0000, v165
	ds_bpermute_b32 v162, v156, v196
	s_waitcnt lgkmcnt(3)
	global_store_dwordx4 v[122:123], v[118:121], off
	v_add_f32_e32 v86, v87, v86
	v_cvt_pk_bf16_f32 v87, v88, v95
	ds_bpermute_b32 v118, v155, v87
	s_waitcnt lgkmcnt(3)
	v_lshlrev_b32_e32 v87, 16, v164
	ds_bpermute_b32 v161, v156, v197
	v_add_f32_e32 v80, v80, v87
	v_and_b32_e32 v87, 0xffff0000, v164
	v_cvt_pk_bf16_f32 v119, v89, v90
	v_cvt_pk_bf16_f32 v120, v84, v91
	v_cvt_pk_bf16_f32 v121, v85, v86
	v_add_f32_e32 v87, v81, v87
	s_waitcnt lgkmcnt(3)
	v_lshlrev_b32_e32 v81, 16, v163
	ds_bpermute_b32 v119, v155, v119
	ds_bpermute_b32 v120, v155, v120
	ds_bpermute_b32 v121, v155, v121
	v_add_f32_e32 v81, v82, v81
	v_and_b32_e32 v82, 0xffff0000, v163
	v_add_f32_e32 v82, v83, v82
	s_waitcnt lgkmcnt(5)
	v_lshlrev_b32_e32 v83, 16, v162
	v_add_f32_e32 v76, v76, v83
	v_and_b32_e32 v83, 0xffff0000, v162
	v_add_f32_e32 v83, v77, v83
	s_waitcnt lgkmcnt(3)
	v_lshlrev_b32_e32 v77, 16, v161
	ds_bpermute_b32 v160, v156, v198
	v_add_f32_e32 v77, v78, v77
	v_and_b32_e32 v78, 0xffff0000, v161
	s_waitcnt lgkmcnt(1)
	global_store_dwordx4 v[122:123], v[118:121], off offset:256
	v_add_f32_e32 v78, v79, v78
	v_cvt_pk_bf16_f32 v79, v80, v87
	ds_bpermute_b32 v159, v156, v199
	v_cvt_pk_bf16_f32 v119, v81, v82
	v_cvt_pk_bf16_f32 v120, v76, v83
	v_cvt_pk_bf16_f32 v121, v77, v78
	ds_bpermute_b32 v118, v155, v79
	ds_bpermute_b32 v119, v155, v119
	ds_bpermute_b32 v120, v155, v120
	ds_bpermute_b32 v121, v155, v121
	ds_bpermute_b32 v158, v156, v200
	v_fmac_f32_e32 v125, v124, v124
	v_lshl_add_u64 v[122:123], s[12:13], 0, v[144:145]
	s_waitcnt lgkmcnt(6)
	v_lshlrev_b32_e32 v79, 16, v160
	ds_bpermute_b32 v157, v156, v201
	v_add_f32_e32 v125, v125, v126
	v_lshl_add_u64 v[126:127], v[122:123], 0, v[138:139]
	v_add_f32_e32 v79, v72, v79
	v_and_b32_e32 v72, 0xffff0000, v160
	s_waitcnt lgkmcnt(2)
	global_store_dwordx4 v[126:127], v[118:121], off
	v_add_f32_e32 v181, v181, v182
	v_add_f32_e32 v130, v130, v181
	v_add_f32_e32 v121, v73, v72
	v_lshlrev_b32_e32 v72, 16, v159
	v_add_f32_e32 v118, v74, v72
	v_and_b32_e32 v72, 0xffff0000, v159
	v_add_f32_e32 v122, v75, v72
	s_waitcnt lgkmcnt(1)
	v_lshlrev_b32_e32 v72, 16, v158
	v_add_f32_e32 v119, v68, v72
	v_and_b32_e32 v68, 0xffff0000, v158
	v_add_f32_e32 v123, v69, v68
	s_waitcnt lgkmcnt(0)
	v_lshlrev_b32_e32 v68, 16, v157
	v_add_f32_e32 v120, v70, v68
	v_and_b32_e32 v68, 0xffff0000, v157
	v_add_f32_e32 v124, v71, v68
	v_cvt_pk_bf16_f32 v68, v79, v121
	v_cvt_pk_bf16_f32 v69, v118, v122
	v_cvt_pk_bf16_f32 v70, v119, v123
	v_cvt_pk_bf16_f32 v71, v120, v124
	ds_bpermute_b32 v68, v155, v68
	ds_bpermute_b32 v69, v155, v69
	ds_bpermute_b32 v70, v155, v70
	ds_bpermute_b32 v71, v155, v71
	v_lshl_add_u64 v[74:75], v[142:143], 0, s[8:9]
	s_mov_b64 s[8:9], 0x90000
	v_lshl_add_u64 v[72:73], v[142:143], 0, s[8:9]
	s_mov_b64 s[8:9], 0xa0000
	s_waitcnt lgkmcnt(0)
	global_store_dwordx4 v[126:127], v[68:71], off offset:256
	v_add_f32_e32 v116, v116, v125
	v_add_f32_e32 v116, v130, v116
	v_lshl_add_u64 v[68:69], v[140:141], 0, v[74:75]
	global_load_dwordx4 v[126:129], v[68:69], off
	global_load_dwordx4 v[144:147], v[68:69], off offset:256
	v_lshl_add_u64 v[68:69], v[140:141], 0, v[72:73]
	global_load_dwordx4 v[158:161], v[68:69], off
	global_load_dwordx4 v[162:165], v[68:69], off offset:256
	v_lshl_add_u64 v[70:71], v[142:143], 0, s[8:9]
	v_lshl_add_u64 v[68:69], v[140:141], 0, v[70:71]
	global_load_dwordx4 v[166:169], v[68:69], off
	global_load_dwordx4 v[170:173], v[68:69], off offset:256
	s_mov_b64 s[8:9], 0xb0000
	v_lshl_add_u64 v[68:69], v[142:143], 0, s[8:9]
	v_lshl_add_u64 v[130:131], v[140:141], 0, v[68:69]
	global_load_dwordx4 v[140:143], v[130:131], off
	global_load_dwordx4 v[174:177], v[130:131], off offset:256
	v_lshl_add_u64 v[74:75], s[12:13], 0, v[74:75]
	v_lshl_add_u64 v[74:75], v[74:75], 0, v[138:139]
	v_lshl_add_u64 v[72:73], s[12:13], 0, v[72:73]
	v_lshl_add_u64 v[70:71], s[12:13], 0, v[70:71]
	v_lshl_add_u64 v[68:69], s[12:13], 0, v[68:69]
	s_waitcnt vmcnt(7)
	ds_bpermute_b32 v125, v156, v126
	ds_bpermute_b32 v126, v156, v127
	ds_bpermute_b32 v127, v156, v128
	ds_bpermute_b32 v128, v156, v129
	s_waitcnt vmcnt(6)
	ds_bpermute_b32 v130, v156, v144
	s_waitcnt lgkmcnt(4)
	v_lshlrev_b32_e32 v129, 16, v125
	v_and_b32_e32 v125, 0xffff0000, v125
	v_add_f32_e32 v125, v65, v125
	s_waitcnt lgkmcnt(3)
	v_lshlrev_b32_e32 v65, 16, v126
	v_add_f32_e32 v65, v66, v65
	v_and_b32_e32 v66, 0xffff0000, v126
	v_add_f32_e32 v66, v67, v66
	s_waitcnt lgkmcnt(2)
	v_lshlrev_b32_e32 v67, 16, v127
	v_add_f32_e32 v60, v60, v67
	v_and_b32_e32 v67, 0xffff0000, v127
	ds_bpermute_b32 v131, v156, v145
	v_add_f32_e32 v67, v61, v67
	s_waitcnt lgkmcnt(2)
	v_lshlrev_b32_e32 v61, 16, v128
	v_add_f32_e32 v61, v62, v61
	v_and_b32_e32 v62, 0xffff0000, v128
	ds_bpermute_b32 v144, v156, v146
	v_add_f32_e32 v64, v64, v129
	v_add_f32_e32 v62, v63, v62
	v_cvt_pk_bf16_f32 v63, v64, v125
	ds_bpermute_b32 v126, v155, v63
	s_waitcnt lgkmcnt(3)
	v_lshlrev_b32_e32 v63, 16, v130
	ds_bpermute_b32 v145, v156, v147
	v_add_f32_e32 v56, v56, v63
	v_and_b32_e32 v63, 0xffff0000, v130
	v_cvt_pk_bf16_f32 v127, v65, v66
	v_cvt_pk_bf16_f32 v128, v60, v67
	v_cvt_pk_bf16_f32 v129, v61, v62
	v_add_f32_e32 v63, v57, v63
	s_waitcnt lgkmcnt(3)
	v_lshlrev_b32_e32 v57, 16, v131
	ds_bpermute_b32 v127, v155, v127
	ds_bpermute_b32 v128, v155, v128
	ds_bpermute_b32 v129, v155, v129
	v_add_f32_e32 v57, v58, v57
	v_and_b32_e32 v58, 0xffff0000, v131
	s_waitcnt vmcnt(5)
	ds_bpermute_b32 v146, v156, v158
	v_add_f32_e32 v58, v59, v58
	s_waitcnt lgkmcnt(6)
	v_lshlrev_b32_e32 v59, 16, v144
	v_add_f32_e32 v52, v52, v59
	v_and_b32_e32 v59, 0xffff0000, v144
	ds_bpermute_b32 v147, v156, v159
	v_add_f32_e32 v59, v53, v59
	s_waitcnt lgkmcnt(5)
	v_lshlrev_b32_e32 v53, 16, v145
	v_add_f32_e32 v53, v54, v53
	v_and_b32_e32 v54, 0xffff0000, v145
	ds_bpermute_b32 v148, v156, v160
	s_waitcnt lgkmcnt(3)
	global_store_dwordx4 v[74:75], v[126:129], off
	v_add_f32_e32 v54, v55, v54
	v_cvt_pk_bf16_f32 v55, v56, v63
	ds_bpermute_b32 v126, v155, v55
	s_waitcnt lgkmcnt(3)
	v_lshlrev_b32_e32 v55, 16, v146
	ds_bpermute_b32 v149, v156, v161
	v_add_f32_e32 v48, v48, v55
	v_and_b32_e32 v55, 0xffff0000, v146
	v_cvt_pk_bf16_f32 v127, v57, v58
	v_cvt_pk_bf16_f32 v128, v52, v59
	v_cvt_pk_bf16_f32 v129, v53, v54
	v_add_f32_e32 v55, v49, v55
	s_waitcnt lgkmcnt(3)
	v_lshlrev_b32_e32 v49, 16, v147
	ds_bpermute_b32 v127, v155, v127
	ds_bpermute_b32 v128, v155, v128
	ds_bpermute_b32 v129, v155, v129
	v_add_f32_e32 v49, v50, v49
	v_and_b32_e32 v50, 0xffff0000, v147
	s_waitcnt vmcnt(5)
	ds_bpermute_b32 v157, v156, v162
	v_add_f32_e32 v50, v51, v50
	s_waitcnt lgkmcnt(6)
	v_lshlrev_b32_e32 v51, 16, v148
	v_add_f32_e32 v44, v44, v51
	v_and_b32_e32 v51, 0xffff0000, v148
	ds_bpermute_b32 v158, v156, v163
	v_add_f32_e32 v51, v45, v51
	s_waitcnt lgkmcnt(5)
	v_lshlrev_b32_e32 v45, 16, v149
	v_add_f32_e32 v45, v46, v45
	v_and_b32_e32 v46, 0xffff0000, v149
	ds_bpermute_b32 v159, v156, v164
	s_waitcnt lgkmcnt(3)
	global_store_dwordx4 v[74:75], v[126:129], off offset:256
	v_add_f32_e32 v46, v47, v46
	v_cvt_pk_bf16_f32 v47, v48, v55
	ds_bpermute_b32 v126, v155, v47
	s_waitcnt lgkmcnt(3)
	v_lshlrev_b32_e32 v47, 16, v157
	ds_bpermute_b32 v160, v156, v165
	v_add_f32_e32 v40, v40, v47
	v_and_b32_e32 v47, 0xffff0000, v157
	v_cvt_pk_bf16_f32 v74, v49, v50
	v_cvt_pk_bf16_f32 v75, v44, v51
	v_cvt_pk_bf16_f32 v129, v45, v46
	v_add_f32_e32 v47, v41, v47
	s_waitcnt lgkmcnt(3)
	v_lshlrev_b32_e32 v41, 16, v158
	ds_bpermute_b32 v127, v155, v74
	ds_bpermute_b32 v128, v155, v75
	ds_bpermute_b32 v129, v155, v129
	v_add_f32_e32 v41, v42, v41
	v_and_b32_e32 v42, 0xffff0000, v158
	s_waitcnt vmcnt(5)
	ds_bpermute_b32 v161, v156, v166
	v_add_f32_e32 v42, v43, v42
	s_waitcnt lgkmcnt(6)
	v_lshlrev_b32_e32 v43, 16, v159
	v_add_f32_e32 v36, v36, v43
	v_and_b32_e32 v43, 0xffff0000, v159
	ds_bpermute_b32 v162, v156, v167
	v_add_f32_e32 v43, v37, v43
	s_waitcnt lgkmcnt(5)
	v_lshlrev_b32_e32 v37, 16, v160
	v_lshl_add_u64 v[130:131], v[72:73], 0, v[138:139]
	v_add_f32_e32 v37, v38, v37
	v_and_b32_e32 v38, 0xffff0000, v160
	ds_bpermute_b32 v163, v156, v168
	s_waitcnt lgkmcnt(3)
	global_store_dwordx4 v[130:131], v[126:129], off
	v_add_f32_e32 v38, v39, v38
	v_cvt_pk_bf16_f32 v39, v40, v47
	ds_bpermute_b32 v72, v155, v39
	s_waitcnt lgkmcnt(3)
	v_lshlrev_b32_e32 v39, 16, v161
	ds_bpermute_b32 v164, v156, v169
	v_add_f32_e32 v30, v30, v39
	v_and_b32_e32 v39, 0xffff0000, v161
	v_cvt_pk_bf16_f32 v73, v41, v42
	v_cvt_pk_bf16_f32 v74, v36, v43
	v_cvt_pk_bf16_f32 v75, v37, v38
	v_add_f32_e32 v39, v31, v39
	s_waitcnt lgkmcnt(3)
	v_lshlrev_b32_e32 v31, 16, v162
	ds_bpermute_b32 v73, v155, v73
	ds_bpermute_b32 v74, v155, v74
	ds_bpermute_b32 v75, v155, v75
	v_add_f32_e32 v31, v32, v31
	v_and_b32_e32 v32, 0xffff0000, v162
	s_waitcnt vmcnt(5)
	ds_bpermute_b32 v165, v156, v170
	v_add_f32_e32 v32, v33, v32
	s_waitcnt lgkmcnt(6)
	v_lshlrev_b32_e32 v33, 16, v163
	v_add_f32_e32 v26, v26, v33
	v_and_b32_e32 v33, 0xffff0000, v163
	ds_bpermute_b32 v166, v156, v171
	v_add_f32_e32 v33, v27, v33
	s_waitcnt lgkmcnt(5)
	v_lshlrev_b32_e32 v27, 16, v164
	v_add_f32_e32 v27, v28, v27
	v_and_b32_e32 v28, 0xffff0000, v164
	ds_bpermute_b32 v167, v156, v172
	s_waitcnt lgkmcnt(3)
	global_store_dwordx4 v[130:131], v[72:75], off offset:256
	v_add_f32_e32 v28, v29, v28
	v_cvt_pk_bf16_f32 v29, v30, v39
	ds_bpermute_b32 v72, v155, v29
	s_waitcnt lgkmcnt(3)
	v_lshlrev_b32_e32 v29, 16, v165
	ds_bpermute_b32 v168, v156, v173
	v_add_f32_e32 v22, v22, v29
	v_and_b32_e32 v29, 0xffff0000, v165
	v_cvt_pk_bf16_f32 v73, v31, v32
	v_cvt_pk_bf16_f32 v74, v26, v33
	v_cvt_pk_bf16_f32 v75, v27, v28
	v_add_f32_e32 v29, v23, v29
	s_waitcnt lgkmcnt(3)
	v_lshlrev_b32_e32 v23, 16, v166
	ds_bpermute_b32 v73, v155, v73
	ds_bpermute_b32 v74, v155, v74
	ds_bpermute_b32 v75, v155, v75
	v_add_f32_e32 v23, v24, v23
	v_and_b32_e32 v24, 0xffff0000, v166
	s_waitcnt vmcnt(5)
	ds_bpermute_b32 v140, v156, v140
	v_add_f32_e32 v24, v25, v24
	s_waitcnt lgkmcnt(6)
	v_lshlrev_b32_e32 v25, 16, v167
	v_add_f32_e32 v18, v18, v25
	v_and_b32_e32 v25, 0xffff0000, v167
	ds_bpermute_b32 v141, v156, v141
	v_add_f32_e32 v25, v19, v25
	s_waitcnt lgkmcnt(5)
	v_lshlrev_b32_e32 v19, 16, v168
	v_lshl_add_u64 v[126:127], v[70:71], 0, v[138:139]
	v_add_f32_e32 v19, v20, v19
	v_and_b32_e32 v20, 0xffff0000, v168
	ds_bpermute_b32 v142, v156, v142
	s_waitcnt lgkmcnt(3)
	global_store_dwordx4 v[126:127], v[72:75], off
	v_add_f32_e32 v20, v21, v20
	v_cvt_pk_bf16_f32 v21, v22, v29
	ds_bpermute_b32 v70, v155, v21
	s_waitcnt lgkmcnt(3)
	v_lshlrev_b32_e32 v21, 16, v140
	ds_bpermute_b32 v143, v156, v143
	v_add_f32_e32 v14, v14, v21
	v_and_b32_e32 v21, 0xffff0000, v140
	v_cvt_pk_bf16_f32 v71, v23, v24
	v_cvt_pk_bf16_f32 v72, v18, v25
	v_cvt_pk_bf16_f32 v73, v19, v20
	v_add_f32_e32 v21, v15, v21
	s_waitcnt lgkmcnt(3)
	v_lshlrev_b32_e32 v15, 16, v141
	ds_bpermute_b32 v71, v155, v71
	ds_bpermute_b32 v72, v155, v72
	ds_bpermute_b32 v73, v155, v73
	v_add_f32_e32 v15, v16, v15
	v_and_b32_e32 v16, 0xffff0000, v141
	s_waitcnt vmcnt(5)
	ds_bpermute_b32 v169, v156, v174
	v_add_f32_e32 v16, v17, v16
	s_waitcnt lgkmcnt(6)
	v_lshlrev_b32_e32 v17, 16, v142
	v_add_f32_e32 v10, v10, v17
	v_and_b32_e32 v17, 0xffff0000, v142
	ds_bpermute_b32 v170, v156, v175
	v_add_f32_e32 v17, v11, v17
	s_waitcnt lgkmcnt(5)
	v_lshlrev_b32_e32 v11, 16, v143
	v_add_f32_e32 v11, v12, v11
	v_and_b32_e32 v12, 0xffff0000, v143
	ds_bpermute_b32 v171, v156, v176
	s_waitcnt lgkmcnt(3)
	global_store_dwordx4 v[126:127], v[70:73], off offset:256
	v_add_f32_e32 v12, v13, v12
	v_cvt_pk_bf16_f32 v13, v14, v21
	ds_bpermute_b32 v70, v155, v13
	s_waitcnt lgkmcnt(3)
	v_lshlrev_b32_e32 v13, 16, v169
	ds_bpermute_b32 v156, v156, v177
	v_add_f32_e32 v6, v6, v13
	v_and_b32_e32 v13, 0xffff0000, v169
	v_cvt_pk_bf16_f32 v71, v15, v16
	v_cvt_pk_bf16_f32 v72, v10, v17
	v_cvt_pk_bf16_f32 v73, v11, v12
	v_add_f32_e32 v13, v7, v13
	s_waitcnt lgkmcnt(3)
	v_lshlrev_b32_e32 v7, 16, v170
	ds_bpermute_b32 v71, v155, v71
	ds_bpermute_b32 v72, v155, v72
	ds_bpermute_b32 v73, v155, v73
	v_add_f32_e32 v7, v8, v7
	v_and_b32_e32 v8, 0xffff0000, v170
	v_add_f32_e32 v8, v9, v8
	s_waitcnt lgkmcnt(5)
	v_lshlrev_b32_e32 v9, 16, v171
	v_add_f32_e32 v2, v2, v9
	v_and_b32_e32 v9, 0xffff0000, v171
	v_add_f32_e32 v9, v3, v9
	s_waitcnt lgkmcnt(3)
	v_lshlrev_b32_e32 v3, 16, v156
	v_lshl_add_u64 v[74:75], v[68:69], 0, v[138:139]
	v_add_f32_e32 v3, v4, v3
	v_and_b32_e32 v4, 0xffff0000, v156
	s_waitcnt lgkmcnt(0)
	global_store_dwordx4 v[74:75], v[70:73], off
	v_add_f32_e32 v4, v5, v4
	v_cvt_pk_bf16_f32 v5, v6, v13
	v_cvt_pk_bf16_f32 v69, v7, v8
	ds_bpermute_b32 v68, v155, v5
	v_cvt_pk_bf16_f32 v70, v2, v9
	v_cvt_pk_bf16_f32 v71, v3, v4
	ds_bpermute_b32 v69, v155, v69
	ds_bpermute_b32 v70, v155, v70
	ds_bpermute_b32 v71, v155, v71
	v_or_b32_e32 v5, s50, v153
	v_lshl_add_u32 v5, v5, 4, s55
	s_waitcnt lgkmcnt(0)
	global_store_dwordx4 v[74:75], v[68:71], off offset:256
	ds_swizzle_b32 v68, v116 offset:swizzle(SWAP,16)
	s_waitcnt lgkmcnt(0)
	v_add_f32_e32 v68, v116, v68
	v_mov_b32_e32 v69, v68
	s_nop 1
	v_permlane32_swap_b32_e32 v68, v69
	s_and_saveexec_b64 s[8:9], vcc
	v_add_f32_e32 v68, v68, v69
	ds_write_b32 v5, v68
	s_or_b64 exec, exec, s[8:9]
	v_mul_f32_e32 v68, v117, v117
	v_mul_f32_e32 v69, v114, v114
	v_fmac_f32_e32 v68, v112, v112
	v_fmac_f32_e32 v69, v113, v113
	v_add_f32_e32 v68, v68, v69
	v_mul_f32_e32 v69, v115, v115
	v_mul_f32_e32 v70, v110, v110
	v_fmac_f32_e32 v69, v108, v108
	v_fmac_f32_e32 v70, v109, v109
	v_add_f32_e32 v69, v69, v70
	v_add_f32_e32 v68, v68, v69
	v_mul_f32_e32 v69, v111, v111
	v_mul_f32_e32 v70, v106, v106
	v_fmac_f32_e32 v69, v104, v104
	v_fmac_f32_e32 v70, v105, v105
	v_add_f32_e32 v69, v69, v70
	v_mul_f32_e32 v70, v107, v107
	v_mul_f32_e32 v71, v102, v102
	v_fmac_f32_e32 v70, v100, v100
	v_fmac_f32_e32 v71, v101, v101
	v_add_f32_e32 v70, v70, v71
	v_add_f32_e32 v69, v69, v70
	v_add_f32_e32 v68, v68, v69
	ds_swizzle_b32 v69, v68 offset:swizzle(SWAP,16)
	s_waitcnt lgkmcnt(0)
	v_add_f32_e32 v68, v68, v69
	v_mov_b32_e32 v69, v68
	s_nop 1
	v_permlane32_swap_b32_e32 v68, v69
	s_and_saveexec_b64 s[8:9], vcc
	v_add_f32_e32 v68, v68, v69
	ds_write_b32 v5, v68 offset:256
	s_or_b64 exec, exec, s[8:9]
	v_mul_f32_e32 v68, v103, v103
	v_mul_f32_e32 v69, v98, v98
	v_fmac_f32_e32 v68, v96, v96
	v_fmac_f32_e32 v69, v97, v97
	v_add_f32_e32 v68, v68, v69
	v_mul_f32_e32 v69, v99, v99
	v_mul_f32_e32 v70, v94, v94
	v_fmac_f32_e32 v69, v92, v92
	v_fmac_f32_e32 v70, v93, v93
	v_add_f32_e32 v69, v69, v70
	v_add_f32_e32 v68, v68, v69
	v_mul_f32_e32 v69, v95, v95
	v_mul_f32_e32 v70, v90, v90
	v_fmac_f32_e32 v69, v88, v88
	v_fmac_f32_e32 v70, v89, v89
	v_add_f32_e32 v69, v69, v70
	v_mul_f32_e32 v70, v91, v91
	v_mul_f32_e32 v71, v86, v86
	v_fmac_f32_e32 v70, v84, v84
	v_fmac_f32_e32 v71, v85, v85
	v_add_f32_e32 v70, v70, v71
	v_add_f32_e32 v69, v69, v70
	v_add_f32_e32 v68, v68, v69
	ds_swizzle_b32 v69, v68 offset:swizzle(SWAP,16)
	s_waitcnt lgkmcnt(0)
	v_add_f32_e32 v68, v68, v69
	v_mov_b32_e32 v69, v68
	s_nop 1
	v_permlane32_swap_b32_e32 v68, v69
	s_and_saveexec_b64 s[8:9], vcc
	v_add_f32_e32 v68, v68, v69
	ds_write_b32 v5, v68 offset:512
	s_or_b64 exec, exec, s[8:9]
	v_mul_f32_e32 v68, v87, v87
	v_mul_f32_e32 v69, v82, v82
	v_fmac_f32_e32 v68, v80, v80
	v_fmac_f32_e32 v69, v81, v81
	v_add_f32_e32 v68, v68, v69
	v_mul_f32_e32 v69, v83, v83
	v_mul_f32_e32 v70, v78, v78
	v_fmac_f32_e32 v69, v76, v76
	v_fmac_f32_e32 v70, v77, v77
	v_add_f32_e32 v69, v69, v70
	v_add_f32_e32 v68, v68, v69
	v_mul_f32_e32 v69, v121, v121
	v_mul_f32_e32 v70, v122, v122
	v_fmac_f32_e32 v69, v79, v79
	v_fmac_f32_e32 v70, v118, v118
	v_add_f32_e32 v69, v69, v70
	v_mul_f32_e32 v70, v123, v123
	v_mul_f32_e32 v71, v124, v124
	v_fmac_f32_e32 v70, v119, v119
	v_fmac_f32_e32 v71, v120, v120
	v_add_f32_e32 v70, v70, v71
	v_add_f32_e32 v69, v69, v70
	v_add_f32_e32 v68, v68, v69
	ds_swizzle_b32 v69, v68 offset:swizzle(SWAP,16)
	s_waitcnt lgkmcnt(0)
	v_add_f32_e32 v68, v68, v69
	v_mov_b32_e32 v69, v68
	s_nop 1
	v_permlane32_swap_b32_e32 v68, v69
	s_and_saveexec_b64 s[8:9], vcc
	v_add_f32_e32 v68, v68, v69
	ds_write_b32 v5, v68 offset:768
	s_or_b64 exec, exec, s[8:9]
	v_mul_f32_e32 v68, v125, v125
	v_fmac_f32_e32 v68, v64, v64
	v_mul_f32_e32 v64, v66, v66
	v_fmac_f32_e32 v64, v65, v65
	v_mul_f32_e32 v65, v67, v67
	v_fmac_f32_e32 v65, v60, v60
	v_mul_f32_e32 v60, v62, v62
	v_fmac_f32_e32 v60, v61, v61
	v_mul_f32_e32 v61, v63, v63
	v_fmac_f32_e32 v61, v56, v56
	v_mul_f32_e32 v56, v58, v58
	v_fmac_f32_e32 v56, v57, v57
	v_mul_f32_e32 v57, v59, v59
	v_fmac_f32_e32 v57, v52, v52
	v_mul_f32_e32 v52, v54, v54
	v_fmac_f32_e32 v52, v53, v53
	v_add_f32_e32 v64, v68, v64
	v_add_f32_e32 v60, v65, v60
	v_add_f32_e32 v56, v61, v56
	v_add_f32_e32 v52, v57, v52
	v_add_f32_e32 v60, v64, v60
	v_add_f32_e32 v52, v56, v52
	v_add_f32_e32 v52, v60, v52
	ds_swizzle_b32 v53, v52 offset:swizzle(SWAP,16)
	s_waitcnt lgkmcnt(0)
	v_add_f32_e32 v52, v52, v53
	v_mov_b32_e32 v53, v52
	s_nop 1
	v_permlane32_swap_b32_e32 v52, v53
	s_and_saveexec_b64 s[8:9], vcc
	v_add_f32_e32 v52, v52, v53
	ds_write_b32 v5, v52 offset:2048
	s_or_b64 exec, exec, s[8:9]
	v_mul_f32_e32 v52, v55, v55
	v_fmac_f32_e32 v52, v48, v48
	v_mul_f32_e32 v48, v50, v50
	v_fmac_f32_e32 v48, v49, v49
	v_mul_f32_e32 v49, v51, v51
	v_fmac_f32_e32 v49, v44, v44
	v_mul_f32_e32 v44, v46, v46
	v_fmac_f32_e32 v44, v45, v45
	v_mul_f32_e32 v45, v47, v47
	v_fmac_f32_e32 v45, v40, v40
	v_mul_f32_e32 v40, v42, v42
	v_fmac_f32_e32 v40, v41, v41
	v_mul_f32_e32 v41, v43, v43
	v_fmac_f32_e32 v41, v36, v36
	v_mul_f32_e32 v36, v38, v38
	v_fmac_f32_e32 v36, v37, v37
	v_add_f32_e32 v48, v52, v48
	v_add_f32_e32 v44, v49, v44
	v_add_f32_e32 v40, v45, v40
	v_add_f32_e32 v36, v41, v36
	v_add_f32_e32 v44, v48, v44
	v_add_f32_e32 v36, v40, v36
	v_add_f32_e32 v36, v44, v36
	ds_swizzle_b32 v37, v36 offset:swizzle(SWAP,16)
	s_waitcnt lgkmcnt(0)
	v_add_f32_e32 v36, v36, v37
	v_mov_b32_e32 v37, v36
	s_nop 1
	v_permlane32_swap_b32_e32 v36, v37
	s_and_saveexec_b64 s[8:9], vcc
	v_add_f32_e32 v36, v36, v37
	ds_write_b32 v5, v36 offset:2304
	s_or_b64 exec, exec, s[8:9]
	v_mul_f32_e32 v36, v39, v39
	v_fmac_f32_e32 v36, v30, v30
	v_mul_f32_e32 v30, v32, v32
	v_fmac_f32_e32 v30, v31, v31
	v_mul_f32_e32 v31, v33, v33
	v_fmac_f32_e32 v31, v26, v26
	v_mul_f32_e32 v26, v28, v28
	v_fmac_f32_e32 v26, v27, v27
	v_mul_f32_e32 v27, v29, v29
	v_fmac_f32_e32 v27, v22, v22
	v_mul_f32_e32 v22, v24, v24
	v_fmac_f32_e32 v22, v23, v23
	v_mul_f32_e32 v23, v25, v25
	v_fmac_f32_e32 v23, v18, v18
	v_mul_f32_e32 v18, v20, v20
	v_fmac_f32_e32 v18, v19, v19
	v_add_f32_e32 v30, v36, v30
	v_add_f32_e32 v26, v31, v26
	v_add_f32_e32 v22, v27, v22
	v_add_f32_e32 v18, v23, v18
	v_add_f32_e32 v26, v30, v26
	v_add_f32_e32 v18, v22, v18
	v_add_f32_e32 v18, v26, v18
	ds_swizzle_b32 v19, v18 offset:swizzle(SWAP,16)
	s_waitcnt lgkmcnt(0)
	v_add_f32_e32 v18, v18, v19
	v_mov_b32_e32 v19, v18
	s_nop 1
	v_permlane32_swap_b32_e32 v18, v19
	s_and_saveexec_b64 s[8:9], vcc
	v_add_f32_e32 v18, v18, v19
	ds_write_b32 v5, v18 offset:2560
	s_or_b64 exec, exec, s[8:9]
	v_mul_f32_e32 v18, v21, v21
	v_fmac_f32_e32 v18, v14, v14
	v_mul_f32_e32 v14, v16, v16
	v_fmac_f32_e32 v14, v15, v15
	v_mul_f32_e32 v15, v17, v17
	v_fmac_f32_e32 v15, v10, v10
	v_mul_f32_e32 v10, v12, v12
	v_fmac_f32_e32 v10, v11, v11
	v_mul_f32_e32 v11, v13, v13
	v_fmac_f32_e32 v11, v6, v6
	v_mul_f32_e32 v6, v8, v8
	v_fmac_f32_e32 v6, v7, v7
	v_mul_f32_e32 v7, v9, v9
	v_fmac_f32_e32 v7, v2, v2
	v_mul_f32_e32 v2, v4, v4
	v_fmac_f32_e32 v2, v3, v3
	v_add_f32_e32 v14, v18, v14
	v_add_f32_e32 v10, v15, v10
	v_add_f32_e32 v6, v11, v6
	v_add_f32_e32 v2, v7, v2
	v_add_f32_e32 v10, v14, v10
	v_add_f32_e32 v2, v6, v2
	v_add_f32_e32 v2, v10, v2
	ds_swizzle_b32 v3, v2 offset:swizzle(SWAP,16)
	s_waitcnt lgkmcnt(0)
	v_add_f32_e32 v2, v2, v3
	v_mov_b32_e32 v3, v2
	s_nop 1
	v_permlane32_swap_b32_e32 v2, v3
	s_and_saveexec_b64 s[8:9], vcc
	v_add_f32_e32 v2, v2, v3
	ds_write_b32 v5, v2 offset:2816
	s_or_b64 exec, exec, s[8:9]
	v_lshlrev_b32_e32 v2, 4, v154
	s_waitcnt lgkmcnt(0)
	s_barrier
	v_or3_b32 v2, v2, s54, v153
	s_movk_i32 s8, 0x100
	v_cmp_gt_i32_e32 vcc, s8, v2
	s_and_saveexec_b64 s[8:9], vcc
	s_cbranch_execz .LBB0_1044
	v_lshl_add_u32 v3, v2, 4, 0
	v_add_u32_e32 v3, 0x20400, v3
	ds_read_b128 v[4:7], v3
	v_add_u32_e32 v2, s11, v2
	v_ashrrev_i32_e32 v3, 31, v2
	v_readlane_b32 s12, v252, 61
	v_lshlrev_b64 v[2:3], 5, v[2:3]
	s_waitcnt lgkmcnt(0)
	v_mov_b32_e32 v8, v5
	v_mov_b32_e32 v9, v6
	v_mov_b32_e32 v5, v7
	v_readlane_b32 s13, v252, 62
	v_pk_add_f32 v[4:5], v[8:9], v[4:5]
	s_ashr_i32 s11, s10, 31
	v_lshl_add_u64 v[2:3], s[12:13], 0, v[2:3]
	v_add_f32_e32 v4, v4, v5
	v_lshl_add_u64 v[2:3], s[10:11], 2, v[2:3]
	global_store_dword v[2:3], v4, off

.LBB0_1113:
	s_ashr_i32 s19, s18, 31
	s_lshl_b64 s[20:21], s[18:19], 20
	v_readlane_b32 s22, v254, 38
	v_readlane_b32 s23, v254, 39
	s_add_u32 s22, s22, s20
	s_addc_u32 s23, s23, s21
	s_and_b64 s[20:21], s[38:39], exec
	s_cselect_b32 s13, s23, s9
	s_cselect_b32 s19, s22, s8
	s_ashr_i32 s11, s10, 31
	s_lshl_b64 s[20:21], s[10:11], 20
	v_readlane_b32 s30, v254, 8
	v_readlane_b32 s31, v254, 9
	s_add_u32 s40, s30, s20
	s_addc_u32 s41, s31, s21
	v_mov_b32_e32 v2, v0
	s_and_b64 s[20:21], s[38:39], exec
	s_cselect_b32 s20, s41, s29
	s_cselect_b32 s21, s40, s28
	s_lshl_b32 s11, s24, 8
	v_and_or_b32 v2, v2, 63, s50
	v_or_b32_e32 v2, s11, v2
	v_ashrrev_i32_e32 v3, 31, v2
	v_readlane_b32 s24, v252, 61
	v_lshlrev_b64 v[2:3], 5, v[2:3]
	v_readlane_b32 s25, v252, 62
	s_add_u32 s8, s8, 0x80080
	s_addc_u32 s9, s9, 0
	v_lshl_add_u64 v[2:3], s[24:25], 0, v[2:3]
	global_load_dwordx4 v[116:119], v[2:3], off offset:16
	global_load_dwordx4 v[120:123], v[2:3], off
	s_add_u32 s24, s28, 0x100
	s_addc_u32 s25, s29, 0
	s_mov_b32 s30, -2
	v_readlane_b32 s57, v255, 20
	v_readlane_b32 s58, v255, 21
	v_readlane_b32 s59, v255, 22
	v_readlane_b32 s60, v255, 23
	s_mov_b64 s[62:63], 0x80
	s_add_u32 s28, s8, 0xfff80080
	s_addc_u32 s29, s9, -1
	s_add_i32 s31, 0, 0x10000
	s_cmp_eq_u32 s30, 28
	v_add_u32_e32 v149, s31, v1
	v_add_u32_e32 v154, s31, v146
	s_cselect_b32 s43, s13, s29
	s_cselect_b32 s42, s19, s28
	ds_read_b128 v[150:153], v149
	ds_read_b128 v[154:157], v154
	v_add_u32_e32 v149, s57, v1
	v_add_u32_e32 v162, s57, v146
	s_cselect_b32 s29, s20, s25
	s_cselect_b32 s28, s21, s24
	s_add_i32 s56, 0, 0x14000
	ds_read_b128 v[158:161], v149
	ds_read_b128 v[162:165], v162
	v_add_u32_e32 v149, s56, v1
	v_add_u32_e32 v170, s56, v146
	ds_read_b128 v[166:169], v149
	ds_read_b128 v[170:173], v170
	v_add_u32_e32 v149, s58, v1
	v_add_u32_e32 v178, s58, v146
	ds_read_b128 v[174:177], v149
	ds_read_b128 v[184:187], v178
	v_lshl_add_u64 v[178:179], s[8:9], 0, v[144:145]
	s_add_i32 m0, s34, 0xc000
	ds_read_b128 v[188:191], v147
	ds_read_b128 v[192:195], v147 offset:2048
	ds_read_b128 v[196:199], v148
	ds_read_b128 v[200:203], v148 offset:2048
	ds_read_b128 v[204:207], v147 offset:4096
	ds_read_b128 v[208:211], v147 offset:6144
	ds_read_b128 v[224:227], v148 offset:4096
	ds_read_b128 v[228:231], v148 offset:6144
	global_load_lds_dwordx4 v[178:179], off
	v_lshl_add_u64 v[178:179], s[8:9], 0, v[142:143]
	s_add_i32 m0, s34, 0xe000
	s_nop 0
	global_load_lds_dwordx4 v[178:179], off
	s_waitcnt vmcnt(8)
	s_waitcnt lgkmcnt(0)
	s_barrier
	s_setprio 1
	s_waitcnt lgkmcnt(0)
	v_mfma_f32_16x16x32_bf16 v[132:135], v[150:153], v[188:191], 0
	v_mfma_f32_16x16x32_bf16 v[124:127], v[158:161], v[188:191], 0
	v_mfma_f32_16x16x32_bf16 v[108:111], v[150:153], v[192:195], 0
	v_mfma_f32_16x16x32_bf16 v[100:103], v[158:161], v[192:195], 0
	v_mfma_f32_16x16x32_bf16 v[92:95], v[150:153], v[204:207], 0
	v_mfma_f32_16x16x32_bf16 v[84:87], v[158:161], v[204:207], 0
	v_mfma_f32_16x16x32_bf16 v[76:79], v[150:153], v[208:211], 0
	v_mfma_f32_16x16x32_bf16 v[68:71], v[158:161], v[208:211], 0
	v_mfma_f32_16x16x32_bf16 v[132:135], v[154:157], v[196:199], v[132:135]
	v_mfma_f32_16x16x32_bf16 v[124:127], v[162:165], v[196:199], v[124:127]
	v_mfma_f32_16x16x32_bf16 v[108:111], v[154:157], v[200:203], v[108:111]
	v_mfma_f32_16x16x32_bf16 v[100:103], v[162:165], v[200:203], v[100:103]
	v_mfma_f32_16x16x32_bf16 v[92:95], v[154:157], v[224:227], v[92:95]
	v_mfma_f32_16x16x32_bf16 v[84:87], v[162:165], v[224:227], v[84:87]
	v_mfma_f32_16x16x32_bf16 v[76:79], v[154:157], v[228:231], v[76:79]
	v_mfma_f32_16x16x32_bf16 v[68:71], v[162:165], v[228:231], v[68:71]
	s_setprio 0
	s_setprio 1
	v_mfma_f32_16x16x32_bf16 v[136:139], v[166:169], v[188:191], 0
	v_mfma_f32_16x16x32_bf16 v[128:131], v[174:177], v[188:191], 0
	v_mfma_f32_16x16x32_bf16 v[112:115], v[166:169], v[192:195], 0
	v_mfma_f32_16x16x32_bf16 v[104:107], v[174:177], v[192:195], 0
	v_mfma_f32_16x16x32_bf16 v[96:99], v[166:169], v[204:207], 0
	v_mfma_f32_16x16x32_bf16 v[88:91], v[174:177], v[204:207], 0
	v_mfma_f32_16x16x32_bf16 v[80:83], v[166:169], v[208:211], 0
	v_mfma_f32_16x16x32_bf16 v[72:75], v[174:177], v[208:211], 0
	v_mfma_f32_16x16x32_bf16 v[136:139], v[170:173], v[196:199], v[136:139]
	v_mfma_f32_16x16x32_bf16 v[128:131], v[184:187], v[196:199], v[128:131]
	v_mfma_f32_16x16x32_bf16 v[112:115], v[170:173], v[200:203], v[112:115]
	v_mfma_f32_16x16x32_bf16 v[104:107], v[184:187], v[200:203], v[104:107]
	v_mfma_f32_16x16x32_bf16 v[96:99], v[170:173], v[224:227], v[96:99]
	v_mfma_f32_16x16x32_bf16 v[88:91], v[184:187], v[224:227], v[88:91]
	v_mfma_f32_16x16x32_bf16 v[80:83], v[170:173], v[228:231], v[80:83]
	v_mfma_f32_16x16x32_bf16 v[72:75], v[184:187], v[228:231], v[72:75]
	s_setprio 0
	s_barrier
	s_add_i32 s31, s31, s33
	v_lshl_add_u64 v[178:179], s[28:29], 0, v[34:35]
	s_mov_b32 m0, s31
	ds_read_b128 v[188:191], v147 offset:16384
	ds_read_b128 v[192:195], v147 offset:18432
	ds_read_b128 v[196:199], v148 offset:16384
	ds_read_b128 v[200:203], v148 offset:18432
	ds_read_b128 v[204:207], v147 offset:20480
	ds_read_b128 v[208:211], v147 offset:22528
	ds_read_b128 v[224:227], v148 offset:20480
	ds_read_b128 v[228:231], v148 offset:22528
	global_load_lds_dwordx4 v[178:179], off
	s_add_i32 m0, s31, 0x2000
	s_add_u32 s54, s28, 0x80000
	v_lshl_add_u64 v[180:181], s[28:29], 0, v[140:141]
	s_addc_u32 s55, s29, 0
	s_add_i32 s31, s56, s33
	global_load_lds_dwordx4 v[180:181], off
	v_lshl_add_u64 v[182:183], s[54:55], 0, v[34:35]
	s_mov_b32 m0, s31
	v_lshl_add_u64 v[212:213], s[42:43], 0, v[142:143]
	global_load_lds_dwordx4 v[182:183], off
	v_lshl_add_u64 v[182:183], s[54:55], 0, v[140:141]
	s_add_i32 m0, s31, 0x2000
	s_nop 0
	global_load_lds_dwordx4 v[182:183], off
	v_lshl_add_u64 v[182:183], s[42:43], 0, v[144:145]
	s_mov_b32 m0, s34
	s_nop 0
	global_load_lds_dwordx4 v[182:183], off
	s_mov_b32 m0, s35
	s_nop 0
	global_load_lds_dwordx4 v[212:213], off
	s_waitcnt vmcnt(8)
	s_waitcnt lgkmcnt(0)
	s_barrier
	s_setprio 1
	s_waitcnt lgkmcnt(0)
	v_mfma_f32_16x16x32_bf16 v[60:63], v[150:153], v[188:191], 0
	v_mfma_f32_16x16x32_bf16 v[52:55], v[158:161], v[188:191], 0
	v_mfma_f32_16x16x32_bf16 v[44:47], v[150:153], v[192:195], 0
	v_mfma_f32_16x16x32_bf16 v[36:39], v[158:161], v[192:195], 0
	v_mfma_f32_16x16x32_bf16 v[26:29], v[150:153], v[204:207], 0
	v_mfma_f32_16x16x32_bf16 v[18:21], v[158:161], v[204:207], 0
	v_mfma_f32_16x16x32_bf16 v[10:13], v[150:153], v[208:211], 0
	v_mfma_f32_16x16x32_bf16 v[6:9], v[158:161], v[208:211], 0
	v_mfma_f32_16x16x32_bf16 v[60:63], v[154:157], v[196:199], v[60:63]
	v_mfma_f32_16x16x32_bf16 v[52:55], v[162:165], v[196:199], v[52:55]
	v_mfma_f32_16x16x32_bf16 v[44:47], v[154:157], v[200:203], v[44:47]
	v_mfma_f32_16x16x32_bf16 v[36:39], v[162:165], v[200:203], v[36:39]
	v_mfma_f32_16x16x32_bf16 v[26:29], v[154:157], v[224:227], v[26:29]
	v_mfma_f32_16x16x32_bf16 v[18:21], v[162:165], v[224:227], v[18:21]
	v_mfma_f32_16x16x32_bf16 v[10:13], v[154:157], v[228:231], v[10:13]
	v_mfma_f32_16x16x32_bf16 v[6:9], v[162:165], v[228:231], v[6:9]
	s_setprio 0
	s_setprio 1
	v_mfma_f32_16x16x32_bf16 v[64:67], v[166:169], v[188:191], 0
	v_mfma_f32_16x16x32_bf16 v[56:59], v[174:177], v[188:191], 0
	v_mfma_f32_16x16x32_bf16 v[48:51], v[166:169], v[192:195], 0
	v_mfma_f32_16x16x32_bf16 v[40:43], v[174:177], v[192:195], 0
	v_mfma_f32_16x16x32_bf16 v[30:33], v[166:169], v[204:207], 0
	v_mfma_f32_16x16x32_bf16 v[22:25], v[174:177], v[204:207], 0
	v_mfma_f32_16x16x32_bf16 v[14:17], v[166:169], v[208:211], 0
	v_mfma_f32_16x16x32_bf16 v[2:5], v[174:177], v[208:211], 0
	v_mfma_f32_16x16x32_bf16 v[64:67], v[170:173], v[196:199], v[64:67]
	v_mfma_f32_16x16x32_bf16 v[56:59], v[184:187], v[196:199], v[56:59]
	v_mfma_f32_16x16x32_bf16 v[48:51], v[170:173], v[200:203], v[48:51]
	v_mfma_f32_16x16x32_bf16 v[40:43], v[184:187], v[200:203], v[40:43]
	v_mfma_f32_16x16x32_bf16 v[30:33], v[170:173], v[224:227], v[30:33]
	v_mfma_f32_16x16x32_bf16 v[22:25], v[184:187], v[224:227], v[22:25]
	v_mfma_f32_16x16x32_bf16 v[14:17], v[170:173], v[228:231], v[14:17]
	v_mfma_f32_16x16x32_bf16 v[2:5], v[184:187], v[228:231], v[2:5]
	s_setprio 0
	s_barrier
	s_add_i32 s31, 0, 0x18000
	v_add_u32_e32 v149, s31, v1
	v_add_u32_e32 v154, s31, v146
	ds_read_b128 v[150:153], v149
	ds_read_b128 v[154:157], v154
	v_add_u32_e32 v149, s59, v1
	v_add_u32_e32 v162, s59, v146
	s_add_i32 s54, 0, 0x1c000
	ds_read_b128 v[158:161], v149
	ds_read_b128 v[162:165], v162
	v_add_u32_e32 v149, s54, v1
	v_add_u32_e32 v170, s54, v146
	ds_read_b128 v[166:169], v149
	ds_read_b128 v[170:173], v170
	v_add_u32_e32 v149, s60, v1
	v_add_u32_e32 v184, s60, v146
	ds_read_b128 v[174:177], v149
	ds_read_b128 v[184:187], v184
	s_add_u32 s42, s42, 0x80000
	s_addc_u32 s43, s43, 0
	s_mov_b32 m0, s44
	v_lshl_add_u64 v[218:219], s[42:43], 0, v[144:145]
	ds_read_b128 v[188:191], v147 offset:32768
	ds_read_b128 v[192:195], v147 offset:34816
	ds_read_b128 v[196:199], v148 offset:32768
	ds_read_b128 v[200:203], v148 offset:34816
	ds_read_b128 v[204:207], v147 offset:36864
	ds_read_b128 v[208:211], v147 offset:38912
	ds_read_b128 v[224:227], v148 offset:36864
	ds_read_b128 v[228:231], v148 offset:38912
	global_load_lds_dwordx4 v[218:219], off
	v_lshl_add_u64 v[218:219], s[42:43], 0, v[142:143]
	s_mov_b32 m0, s45
	s_nop 0
	global_load_lds_dwordx4 v[218:219], off
	s_waitcnt vmcnt(8)
	s_waitcnt lgkmcnt(0)
	s_barrier
	s_setprio 1
	s_waitcnt lgkmcnt(0)
	v_mfma_f32_16x16x32_bf16 v[132:135], v[150:153], v[188:191], v[132:135]
	v_mfma_f32_16x16x32_bf16 v[124:127], v[158:161], v[188:191], v[124:127]
	v_mfma_f32_16x16x32_bf16 v[108:111], v[150:153], v[192:195], v[108:111]
	v_mfma_f32_16x16x32_bf16 v[100:103], v[158:161], v[192:195], v[100:103]
	v_mfma_f32_16x16x32_bf16 v[92:95], v[150:153], v[204:207], v[92:95]
	v_mfma_f32_16x16x32_bf16 v[84:87], v[158:161], v[204:207], v[84:87]
	v_mfma_f32_16x16x32_bf16 v[76:79], v[150:153], v[208:211], v[76:79]
	v_mfma_f32_16x16x32_bf16 v[68:71], v[158:161], v[208:211], v[68:71]
	v_mfma_f32_16x16x32_bf16 v[132:135], v[154:157], v[196:199], v[132:135]
	v_mfma_f32_16x16x32_bf16 v[124:127], v[162:165], v[196:199], v[124:127]
	v_mfma_f32_16x16x32_bf16 v[108:111], v[154:157], v[200:203], v[108:111]
	v_mfma_f32_16x16x32_bf16 v[100:103], v[162:165], v[200:203], v[100:103]
	v_mfma_f32_16x16x32_bf16 v[92:95], v[154:157], v[224:227], v[92:95]
	v_mfma_f32_16x16x32_bf16 v[84:87], v[162:165], v[224:227], v[84:87]
	v_mfma_f32_16x16x32_bf16 v[76:79], v[154:157], v[228:231], v[76:79]
	v_mfma_f32_16x16x32_bf16 v[68:71], v[162:165], v[228:231], v[68:71]
	s_setprio 0
	s_setprio 1
	v_mfma_f32_16x16x32_bf16 v[136:139], v[166:169], v[188:191], v[136:139]
	v_mfma_f32_16x16x32_bf16 v[128:131], v[174:177], v[188:191], v[128:131]
	v_mfma_f32_16x16x32_bf16 v[112:115], v[166:169], v[192:195], v[112:115]
	v_mfma_f32_16x16x32_bf16 v[104:107], v[174:177], v[192:195], v[104:107]
	v_mfma_f32_16x16x32_bf16 v[96:99], v[166:169], v[204:207], v[96:99]
	v_mfma_f32_16x16x32_bf16 v[88:91], v[174:177], v[204:207], v[88:91]
	v_mfma_f32_16x16x32_bf16 v[80:83], v[166:169], v[208:211], v[80:83]
	v_mfma_f32_16x16x32_bf16 v[72:75], v[174:177], v[208:211], v[72:75]
	v_mfma_f32_16x16x32_bf16 v[136:139], v[170:173], v[196:199], v[136:139]
	v_mfma_f32_16x16x32_bf16 v[128:131], v[184:187], v[196:199], v[128:131]
	v_mfma_f32_16x16x32_bf16 v[112:115], v[170:173], v[200:203], v[112:115]
	v_mfma_f32_16x16x32_bf16 v[104:107], v[184:187], v[200:203], v[104:107]
	v_mfma_f32_16x16x32_bf16 v[96:99], v[170:173], v[224:227], v[96:99]
	v_mfma_f32_16x16x32_bf16 v[88:91], v[184:187], v[224:227], v[88:91]
	v_mfma_f32_16x16x32_bf16 v[80:83], v[170:173], v[228:231], v[80:83]
	v_mfma_f32_16x16x32_bf16 v[72:75], v[184:187], v[228:231], v[72:75]
	s_setprio 0
	s_barrier
	s_add_i32 s31, s31, s33
	v_lshl_add_u64 v[178:179], v[178:179], 0, s[62:63]
	s_mov_b32 m0, s31
	ds_read_b128 v[188:191], v147 offset:49152
	ds_read_b128 v[192:195], v147 offset:51200
	ds_read_b128 v[196:199], v148 offset:49152
	ds_read_b128 v[200:203], v148 offset:51200
	ds_read_b128 v[204:207], v147 offset:53248
	ds_read_b128 v[208:211], v147 offset:55296
	ds_read_b128 v[224:227], v148 offset:53248
	ds_read_b128 v[228:231], v148 offset:55296
	global_load_lds_dwordx4 v[178:179], off
	s_add_i32 m0, s31, 0x2000
	s_add_u32 s28, s28, 0x80080
	v_lshl_add_u64 v[178:179], v[180:181], 0, s[62:63]
	s_addc_u32 s29, s29, 0
	s_add_i32 s31, s54, s33
	global_load_lds_dwordx4 v[178:179], off
	v_lshl_add_u64 v[178:179], s[28:29], 0, v[34:35]
	s_mov_b32 m0, s31
	s_nop 0
	global_load_lds_dwordx4 v[178:179], off
	v_lshl_add_u64 v[178:179], s[28:29], 0, v[140:141]
	s_add_i32 m0, s31, 0x2000
	s_nop 0
	global_load_lds_dwordx4 v[178:179], off
	v_lshl_add_u64 v[178:179], v[182:183], 0, s[62:63]
	s_mov_b32 m0, s48
	s_nop 0
	global_load_lds_dwordx4 v[178:179], off
	v_lshl_add_u64 v[178:179], v[212:213], 0, s[62:63]
	s_mov_b32 m0, s49
	s_nop 0
	global_load_lds_dwordx4 v[178:179], off
	s_waitcnt vmcnt(8)
	s_waitcnt lgkmcnt(0)
	s_barrier
	s_setprio 1
	s_waitcnt lgkmcnt(0)
	v_mfma_f32_16x16x32_bf16 v[60:63], v[150:153], v[188:191], v[60:63]
	v_mfma_f32_16x16x32_bf16 v[52:55], v[158:161], v[188:191], v[52:55]
	v_mfma_f32_16x16x32_bf16 v[44:47], v[150:153], v[192:195], v[44:47]
	v_mfma_f32_16x16x32_bf16 v[36:39], v[158:161], v[192:195], v[36:39]
	v_mfma_f32_16x16x32_bf16 v[26:29], v[150:153], v[204:207], v[26:29]
	v_mfma_f32_16x16x32_bf16 v[18:21], v[158:161], v[204:207], v[18:21]
	v_mfma_f32_16x16x32_bf16 v[10:13], v[150:153], v[208:211], v[10:13]
	v_mfma_f32_16x16x32_bf16 v[6:9], v[158:161], v[208:211], v[6:9]
	v_mfma_f32_16x16x32_bf16 v[60:63], v[154:157], v[196:199], v[60:63]
	v_mfma_f32_16x16x32_bf16 v[52:55], v[162:165], v[196:199], v[52:55]
	v_mfma_f32_16x16x32_bf16 v[44:47], v[154:157], v[200:203], v[44:47]
	v_mfma_f32_16x16x32_bf16 v[36:39], v[162:165], v[200:203], v[36:39]
	v_mfma_f32_16x16x32_bf16 v[26:29], v[154:157], v[224:227], v[26:29]
	v_mfma_f32_16x16x32_bf16 v[18:21], v[162:165], v[224:227], v[18:21]
	v_mfma_f32_16x16x32_bf16 v[10:13], v[154:157], v[228:231], v[10:13]
	v_mfma_f32_16x16x32_bf16 v[6:9], v[162:165], v[228:231], v[6:9]
	s_setprio 0
	s_setprio 1
	v_mfma_f32_16x16x32_bf16 v[64:67], v[166:169], v[188:191], v[64:67]
	v_mfma_f32_16x16x32_bf16 v[56:59], v[174:177], v[188:191], v[56:59]
	v_mfma_f32_16x16x32_bf16 v[48:51], v[166:169], v[192:195], v[48:51]
	v_mfma_f32_16x16x32_bf16 v[40:43], v[174:177], v[192:195], v[40:43]
	v_mfma_f32_16x16x32_bf16 v[30:33], v[166:169], v[204:207], v[30:33]
	v_mfma_f32_16x16x32_bf16 v[22:25], v[174:177], v[204:207], v[22:25]
	v_mfma_f32_16x16x32_bf16 v[14:17], v[166:169], v[208:211], v[14:17]
	v_mfma_f32_16x16x32_bf16 v[2:5], v[174:177], v[208:211], v[2:5]
	v_mfma_f32_16x16x32_bf16 v[64:67], v[170:173], v[196:199], v[64:67]
	v_mfma_f32_16x16x32_bf16 v[56:59], v[184:187], v[196:199], v[56:59]
	v_mfma_f32_16x16x32_bf16 v[48:51], v[170:173], v[200:203], v[48:51]
	v_mfma_f32_16x16x32_bf16 v[40:43], v[184:187], v[200:203], v[40:43]
	v_mfma_f32_16x16x32_bf16 v[30:33], v[170:173], v[224:227], v[30:33]
	v_mfma_f32_16x16x32_bf16 v[22:25], v[184:187], v[224:227], v[22:25]
	v_mfma_f32_16x16x32_bf16 v[14:17], v[170:173], v[228:231], v[14:17]
	v_mfma_f32_16x16x32_bf16 v[2:5], v[184:187], v[228:231], v[2:5]
	s_setprio 0
	s_barrier
	s_add_i32 s30, s30, 2
	s_add_u32 s8, s8, 0x100
	s_addc_u32 s9, s9, 0
	s_add_u32 s24, s24, 0x100
	s_addc_u32 s25, s25, 0
	s_cmp_gt_u32 s30, 29
	s_cbranch_scc1 .Lpeel_done_P6

.LBB0_1119:
	s_or_b64 exec, exec, s[8:9]
	s_add_i32 s11, s11, s46
	s_waitcnt vmcnt(0)
	v_bfe_u32 v117, v150, 2, 4
	v_or_b32_e32 v121, s11, v117
	s_lshl_b32 s8, s12, 7
	v_lshlrev_b32_e32 v117, 3, v149
	v_and_or_b32 v117, v117, 24, s8
	v_and_b32_e32 v116, 63, v150
	v_or_b32_e32 v118, s47, v117
	v_lshlrev_b32_e32 v117, 6, v149
	s_movk_i32 s8, 0xfc
	v_bitop3_b32 v120, v117, s8, v116 bitop3:0xc8
	v_readlane_b32 s8, v255, 5
	v_readlane_b32 s9, v255, 6
	v_ashrrev_i32_e32 v119, 31, v118
	s_movk_i32 s11, 0x2c00
	v_mov_b64_e32 v[116:117], s[8:9]
	v_mad_i64_i32 v[122:123], s[8:9], v121, s11, v[116:117]
	v_lshlrev_b64 v[118:119], 1, v[118:119]
	s_waitcnt lgkmcnt(0)
	s_barrier
	v_lshl_add_u64 v[150:151], v[122:123], 0, v[118:119]
	v_lshl_add_u32 v122, v149, 2, s51
	ds_read_b32 v123, v122
	v_pk_mul_f32 v[130:131], v[126:127], v[130:131]
	v_pk_mul_f32 v[138:139], v[134:135], v[138:139]
	v_pk_mul_f32 v[136:137], v[132:133], v[136:137]
	v_pk_mul_f32 v[128:129], v[124:125], v[128:129]
	s_waitcnt lgkmcnt(0)
	v_mul_f32_e32 v152, 0xbfb8aa3b, v123
	v_pk_mul_f32 v[126:127], v[126:127], v[152:153] op_sel_hi:[1,0]
	v_pk_mul_f32 v[132:133], v[132:133], v[152:153] op_sel_hi:[1,0]
	v_pk_mul_f32 v[134:135], v[134:135], v[152:153] op_sel_hi:[1,0]
	v_pk_mul_f32 v[124:125], v[124:125], v[152:153] op_sel_hi:[1,0]
	v_exp_f32_e32 v126, v126
	v_exp_f32_e32 v127, v127
	v_exp_f32_e32 v132, v132
	v_exp_f32_e32 v133, v133
	v_exp_f32_e32 v134, v134
	v_exp_f32_e32 v135, v135
	v_exp_f32_e32 v124, v124
	v_exp_f32_e32 v125, v125
	v_pk_add_f32 v[126:127], v[126:127], 1.0 op_sel_hi:[1,0]
	v_pk_add_f32 v[132:133], v[132:133], 1.0 op_sel_hi:[1,0]
	v_pk_add_f32 v[134:135], v[134:135], 1.0 op_sel_hi:[1,0]
	v_pk_add_f32 v[124:125], v[124:125], 1.0 op_sel_hi:[1,0]
	v_rcp_f32_e32 v126, v126
	v_rcp_f32_e32 v127, v127
	v_rcp_f32_e32 v132, v132
	v_rcp_f32_e32 v133, v133
	v_rcp_f32_e32 v134, v134
	v_rcp_f32_e32 v135, v135
	v_rcp_f32_e32 v124, v124
	v_rcp_f32_e32 v125, v125
	v_mul_f32_e32 v154, v123, v123
	v_pk_mul_f32 v[126:127], v[154:155], v[126:127] op_sel_hi:[0,1]
	v_pk_mul_f32 v[132:133], v[154:155], v[132:133] op_sel_hi:[0,1]
	v_pk_mul_f32 v[134:135], v[154:155], v[134:135] op_sel_hi:[0,1]
	v_pk_mul_f32 v[124:125], v[154:155], v[124:125] op_sel_hi:[0,1]
	v_pk_mul_f32 v[126:127], v[130:131], v[126:127]
	v_pk_mul_f32 v[132:133], v[136:137], v[132:133]
	v_pk_mul_f32 v[134:135], v[138:139], v[134:135]
	v_pk_mul_f32 v[124:125], v[128:129], v[124:125]
	v_cvt_pk_bf16_f32 v123, v132, v133
	v_cvt_pk_bf16_f32 v128, v134, v135
	v_pk_mul_f32 v[106:107], v[102:103], v[106:107]
	v_cvt_pk_bf16_f32 v129, v124, v125
	v_cvt_pk_bf16_f32 v127, v126, v127
	ds_bpermute_b32 v124, v120, v123
	ds_bpermute_b32 v125, v120, v128
	ds_bpermute_b32 v126, v120, v129
	ds_bpermute_b32 v127, v120, v127
	v_or_b32_e32 v123, 16, v121
	v_pk_mul_f32 v[114:115], v[110:111], v[114:115]
	v_pk_mul_f32 v[112:113], v[108:109], v[112:113]
	v_pk_mul_f32 v[104:105], v[100:101], v[104:105]
	s_waitcnt lgkmcnt(0)
	global_store_dwordx4 v[150:151], v[124:127], off
	v_pk_mul_f32 v[90:91], v[86:87], v[90:91]
	v_pk_mul_f32 v[98:99], v[94:95], v[98:99]
	v_mad_i64_i32 v[124:125], s[8:9], v123, s11, v[116:117]
	ds_read_b32 v123, v122 offset:64
	v_lshl_add_u64 v[124:125], v[124:125], 0, v[118:119]
	v_pk_mul_f32 v[96:97], v[92:93], v[96:97]
	v_pk_mul_f32 v[88:89], v[84:85], v[88:89]
	v_pk_mul_f32 v[74:75], v[70:71], v[74:75]
	s_waitcnt lgkmcnt(0)
	v_mul_f32_e32 v126, 0xbfb8aa3b, v123
	v_pk_mul_f32 v[102:103], v[102:103], v[126:127] op_sel_hi:[1,0]
	v_pk_mul_f32 v[108:109], v[108:109], v[126:127] op_sel_hi:[1,0]
	v_pk_mul_f32 v[110:111], v[110:111], v[126:127] op_sel_hi:[1,0]
	v_pk_mul_f32 v[100:101], v[100:101], v[126:127] op_sel_hi:[1,0]
	v_exp_f32_e32 v102, v102
	v_exp_f32_e32 v103, v103
	v_exp_f32_e32 v108, v108
	v_exp_f32_e32 v109, v109
	v_exp_f32_e32 v110, v110
	v_exp_f32_e32 v111, v111
	v_exp_f32_e32 v100, v100
	v_exp_f32_e32 v101, v101
	v_pk_add_f32 v[102:103], v[102:103], 1.0 op_sel_hi:[1,0]
	v_pk_add_f32 v[108:109], v[108:109], 1.0 op_sel_hi:[1,0]
	v_pk_add_f32 v[110:111], v[110:111], 1.0 op_sel_hi:[1,0]
	v_pk_add_f32 v[100:101], v[100:101], 1.0 op_sel_hi:[1,0]
	v_rcp_f32_e32 v102, v102
	v_rcp_f32_e32 v103, v103
	v_rcp_f32_e32 v108, v108
	v_rcp_f32_e32 v109, v109
	v_rcp_f32_e32 v110, v110
	v_rcp_f32_e32 v111, v111
	v_rcp_f32_e32 v100, v100
	v_rcp_f32_e32 v101, v101
	v_mul_f32_e32 v128, v123, v123
	v_pk_mul_f32 v[102:103], v[128:129], v[102:103] op_sel_hi:[0,1]
	v_pk_mul_f32 v[108:109], v[128:129], v[108:109] op_sel_hi:[0,1]
	v_pk_mul_f32 v[110:111], v[128:129], v[110:111] op_sel_hi:[0,1]
	v_pk_mul_f32 v[100:101], v[128:129], v[100:101] op_sel_hi:[0,1]
	v_pk_mul_f32 v[102:103], v[106:107], v[102:103]
	v_pk_mul_f32 v[108:109], v[112:113], v[108:109]
	v_pk_mul_f32 v[110:111], v[114:115], v[110:111]
	v_pk_mul_f32 v[100:101], v[104:105], v[100:101]
	v_cvt_pk_bf16_f32 v104, v108, v109
	v_cvt_pk_bf16_f32 v105, v110, v111
	v_pk_mul_f32 v[82:83], v[78:79], v[82:83]
	v_cvt_pk_bf16_f32 v106, v100, v101
	v_cvt_pk_bf16_f32 v103, v102, v103
	ds_bpermute_b32 v100, v120, v104
	ds_bpermute_b32 v101, v120, v105
	ds_bpermute_b32 v102, v120, v106
	ds_bpermute_b32 v103, v120, v103
	v_pk_mul_f32 v[80:81], v[76:77], v[80:81]
	v_pk_mul_f32 v[72:73], v[68:69], v[72:73]
	v_pk_mul_f32 v[58:59], v[54:55], v[58:59]
	v_pk_mul_f32 v[66:67], v[62:63], v[66:67]
	s_waitcnt lgkmcnt(0)
	global_store_dwordx4 v[124:125], v[100:103], off
	ds_read_b32 v103, v122 offset:128
	v_pk_mul_f32 v[64:65], v[60:61], v[64:65]
	v_or_b32_e32 v100, 32, v121
	v_mad_i64_i32 v[100:101], s[8:9], v100, s11, v[116:117]
	s_waitcnt lgkmcnt(0)
	v_mul_f32_e32 v102, 0xbfb8aa3b, v103
	v_pk_mul_f32 v[86:87], v[86:87], v[102:103] op_sel_hi:[1,0]
	v_pk_mul_f32 v[92:93], v[92:93], v[102:103] op_sel_hi:[1,0]
	v_pk_mul_f32 v[94:95], v[94:95], v[102:103] op_sel_hi:[1,0]
	v_pk_mul_f32 v[84:85], v[84:85], v[102:103] op_sel_hi:[1,0]
	v_exp_f32_e32 v86, v86
	v_exp_f32_e32 v87, v87
	v_exp_f32_e32 v92, v92
	v_exp_f32_e32 v93, v93
	v_exp_f32_e32 v94, v94
	v_exp_f32_e32 v95, v95
	v_exp_f32_e32 v84, v84
	v_exp_f32_e32 v85, v85
	v_pk_add_f32 v[86:87], v[86:87], 1.0 op_sel_hi:[1,0]
	v_pk_add_f32 v[92:93], v[92:93], 1.0 op_sel_hi:[1,0]
	v_pk_add_f32 v[94:95], v[94:95], 1.0 op_sel_hi:[1,0]
	v_pk_add_f32 v[84:85], v[84:85], 1.0 op_sel_hi:[1,0]
	v_rcp_f32_e32 v86, v86
	v_rcp_f32_e32 v87, v87
	v_rcp_f32_e32 v92, v92
	v_rcp_f32_e32 v93, v93
	v_rcp_f32_e32 v94, v94
	v_rcp_f32_e32 v95, v95
	v_rcp_f32_e32 v84, v84
	v_rcp_f32_e32 v85, v85
	v_mul_f32_e32 v104, v103, v103
	v_pk_mul_f32 v[86:87], v[104:105], v[86:87] op_sel_hi:[0,1]
	v_pk_mul_f32 v[92:93], v[104:105], v[92:93] op_sel_hi:[0,1]
	v_pk_mul_f32 v[94:95], v[104:105], v[94:95] op_sel_hi:[0,1]
	v_pk_mul_f32 v[84:85], v[104:105], v[84:85] op_sel_hi:[0,1]
	v_pk_mul_f32 v[86:87], v[90:91], v[86:87]
	v_pk_mul_f32 v[92:93], v[96:97], v[92:93]
	v_pk_mul_f32 v[94:95], v[98:99], v[94:95]
	v_pk_mul_f32 v[84:85], v[88:89], v[84:85]
	v_cvt_pk_bf16_f32 v88, v92, v93
	v_cvt_pk_bf16_f32 v89, v94, v95
	v_lshl_add_u64 v[100:101], v[100:101], 0, v[118:119]
	v_cvt_pk_bf16_f32 v90, v84, v85
	v_cvt_pk_bf16_f32 v87, v86, v87
	ds_bpermute_b32 v84, v120, v88
	ds_bpermute_b32 v85, v120, v89
	ds_bpermute_b32 v86, v120, v90
	ds_bpermute_b32 v87, v120, v87
	v_pk_mul_f32 v[56:57], v[52:53], v[56:57]
	v_pk_mul_f32 v[42:43], v[38:39], v[42:43]
	v_pk_mul_f32 v[50:51], v[46:47], v[50:51]
	v_pk_mul_f32 v[48:49], v[44:45], v[48:49]
	s_waitcnt lgkmcnt(0)
	global_store_dwordx4 v[100:101], v[84:87], off
	ds_read_b32 v87, v122 offset:192
	v_pk_mul_f32 v[40:41], v[36:37], v[40:41]
	v_or_b32_e32 v84, 48, v121
	v_mad_i64_i32 v[84:85], s[8:9], v84, s11, v[116:117]
	s_waitcnt lgkmcnt(0)
	v_mul_f32_e32 v86, 0xbfb8aa3b, v87
	v_pk_mul_f32 v[70:71], v[70:71], v[86:87] op_sel_hi:[1,0]
	v_pk_mul_f32 v[76:77], v[76:77], v[86:87] op_sel_hi:[1,0]
	v_pk_mul_f32 v[78:79], v[78:79], v[86:87] op_sel_hi:[1,0]
	v_pk_mul_f32 v[68:69], v[68:69], v[86:87] op_sel_hi:[1,0]
	v_exp_f32_e32 v70, v70
	v_exp_f32_e32 v71, v71
	v_exp_f32_e32 v76, v76
	v_exp_f32_e32 v77, v77
	v_exp_f32_e32 v78, v78
	v_exp_f32_e32 v79, v79
	v_exp_f32_e32 v68, v68
	v_exp_f32_e32 v69, v69
	v_pk_add_f32 v[70:71], v[70:71], 1.0 op_sel_hi:[1,0]
	v_pk_add_f32 v[76:77], v[76:77], 1.0 op_sel_hi:[1,0]
	v_pk_add_f32 v[78:79], v[78:79], 1.0 op_sel_hi:[1,0]
	v_pk_add_f32 v[68:69], v[68:69], 1.0 op_sel_hi:[1,0]
	v_rcp_f32_e32 v70, v70
	v_rcp_f32_e32 v71, v71
	v_rcp_f32_e32 v76, v76
	v_rcp_f32_e32 v77, v77
	v_rcp_f32_e32 v78, v78
	v_rcp_f32_e32 v79, v79
	v_rcp_f32_e32 v68, v68
	v_rcp_f32_e32 v69, v69
	v_mul_f32_e32 v88, v87, v87
	v_pk_mul_f32 v[70:71], v[88:89], v[70:71] op_sel_hi:[0,1]
	v_pk_mul_f32 v[76:77], v[88:89], v[76:77] op_sel_hi:[0,1]
	v_pk_mul_f32 v[78:79], v[88:89], v[78:79] op_sel_hi:[0,1]
	v_pk_mul_f32 v[68:69], v[88:89], v[68:69] op_sel_hi:[0,1]
	v_pk_mul_f32 v[70:71], v[74:75], v[70:71]
	v_pk_mul_f32 v[76:77], v[80:81], v[76:77]
	v_pk_mul_f32 v[78:79], v[82:83], v[78:79]
	v_pk_mul_f32 v[68:69], v[72:73], v[68:69]
	v_cvt_pk_bf16_f32 v72, v76, v77
	v_cvt_pk_bf16_f32 v73, v78, v79
	v_lshl_add_u64 v[84:85], v[84:85], 0, v[118:119]
	v_cvt_pk_bf16_f32 v74, v68, v69
	v_cvt_pk_bf16_f32 v71, v70, v71
	ds_bpermute_b32 v68, v120, v72
	ds_bpermute_b32 v69, v120, v73
	ds_bpermute_b32 v70, v120, v74
	ds_bpermute_b32 v71, v120, v71
	v_pk_mul_f32 v[24:25], v[20:21], v[24:25]
	v_pk_mul_f32 v[32:33], v[28:29], v[32:33]
	v_pk_mul_f32 v[30:31], v[26:27], v[30:31]
	v_pk_mul_f32 v[22:23], v[18:19], v[22:23]
	s_waitcnt lgkmcnt(0)
	global_store_dwordx4 v[84:85], v[68:71], off
	ds_read_b32 v71, v122 offset:512
	v_pk_mul_f32 v[2:3], v[6:7], v[2:3]
	v_add_u32_e32 v68, 0x80, v121
	v_mad_i64_i32 v[68:69], s[8:9], v68, s11, v[116:117]
	s_waitcnt lgkmcnt(0)
	v_mul_f32_e32 v70, 0xbfb8aa3b, v71
	v_pk_mul_f32 v[54:55], v[54:55], v[70:71] op_sel_hi:[1,0]
	v_pk_mul_f32 v[60:61], v[60:61], v[70:71] op_sel_hi:[1,0]
	v_pk_mul_f32 v[62:63], v[62:63], v[70:71] op_sel_hi:[1,0]
	v_pk_mul_f32 v[52:53], v[52:53], v[70:71] op_sel_hi:[1,0]
	v_exp_f32_e32 v54, v54
	v_exp_f32_e32 v55, v55
	v_exp_f32_e32 v60, v60
	v_exp_f32_e32 v61, v61
	v_exp_f32_e32 v62, v62
	v_exp_f32_e32 v63, v63
	v_exp_f32_e32 v52, v52
	v_exp_f32_e32 v53, v53
	v_pk_add_f32 v[54:55], v[54:55], 1.0 op_sel_hi:[1,0]
	v_pk_add_f32 v[60:61], v[60:61], 1.0 op_sel_hi:[1,0]
	v_pk_add_f32 v[62:63], v[62:63], 1.0 op_sel_hi:[1,0]
	v_pk_add_f32 v[52:53], v[52:53], 1.0 op_sel_hi:[1,0]
	v_rcp_f32_e32 v54, v54
	v_rcp_f32_e32 v55, v55
	v_rcp_f32_e32 v60, v60
	v_rcp_f32_e32 v61, v61
	v_rcp_f32_e32 v62, v62
	v_rcp_f32_e32 v63, v63
	v_rcp_f32_e32 v52, v52
	v_rcp_f32_e32 v53, v53
	v_mul_f32_e32 v72, v71, v71
	v_pk_mul_f32 v[54:55], v[72:73], v[54:55] op_sel_hi:[0,1]
	v_pk_mul_f32 v[60:61], v[72:73], v[60:61] op_sel_hi:[0,1]
	v_pk_mul_f32 v[62:63], v[72:73], v[62:63] op_sel_hi:[0,1]
	v_pk_mul_f32 v[52:53], v[72:73], v[52:53] op_sel_hi:[0,1]
	v_pk_mul_f32 v[54:55], v[58:59], v[54:55]
	v_pk_mul_f32 v[60:61], v[64:65], v[60:61]
	v_pk_mul_f32 v[62:63], v[66:67], v[62:63]
	v_pk_mul_f32 v[52:53], v[56:57], v[52:53]
	v_cvt_pk_bf16_f32 v56, v60, v61
	v_cvt_pk_bf16_f32 v57, v62, v63
	v_lshl_add_u64 v[68:69], v[68:69], 0, v[118:119]
	v_cvt_pk_bf16_f32 v58, v52, v53
	v_cvt_pk_bf16_f32 v55, v54, v55
	ds_bpermute_b32 v52, v120, v56
	ds_bpermute_b32 v53, v120, v57
	ds_bpermute_b32 v54, v120, v58
	ds_bpermute_b32 v55, v120, v55
	v_pk_mul_f32 v[16:17], v[12:13], v[16:17]
	v_pk_mul_f32 v[14:15], v[10:11], v[14:15]
	v_pk_mul_f32 v[4:5], v[8:9], v[4:5]
	s_andn2_b64 vcc, exec, s[38:39]
	s_waitcnt lgkmcnt(0)
	global_store_dwordx4 v[68:69], v[52:55], off
	ds_read_b32 v55, v122 offset:576
	s_waitcnt lgkmcnt(0)
	v_mul_f32_e32 v56, v55, v55
	v_mul_f32_e32 v54, 0xbfb8aa3b, v55
	v_pk_mul_f32 v[38:39], v[38:39], v[54:55] op_sel_hi:[1,0]
	v_pk_mul_f32 v[44:45], v[44:45], v[54:55] op_sel_hi:[1,0]
	v_pk_mul_f32 v[46:47], v[46:47], v[54:55] op_sel_hi:[1,0]
	v_pk_mul_f32 v[36:37], v[36:37], v[54:55] op_sel_hi:[1,0]
	v_exp_f32_e32 v38, v38
	v_exp_f32_e32 v39, v39
	v_exp_f32_e32 v44, v44
	v_exp_f32_e32 v45, v45
	v_exp_f32_e32 v46, v46
	v_exp_f32_e32 v47, v47
	v_exp_f32_e32 v36, v36
	v_exp_f32_e32 v37, v37
	v_pk_add_f32 v[38:39], v[38:39], 1.0 op_sel_hi:[1,0]
	v_pk_add_f32 v[44:45], v[44:45], 1.0 op_sel_hi:[1,0]
	v_pk_add_f32 v[46:47], v[46:47], 1.0 op_sel_hi:[1,0]
	v_pk_add_f32 v[36:37], v[36:37], 1.0 op_sel_hi:[1,0]
	v_rcp_f32_e32 v38, v38
	v_rcp_f32_e32 v39, v39
	v_rcp_f32_e32 v44, v44
	v_rcp_f32_e32 v45, v45
	v_rcp_f32_e32 v46, v46
	v_rcp_f32_e32 v47, v47
	v_rcp_f32_e32 v36, v36
	v_rcp_f32_e32 v37, v37
	v_pk_mul_f32 v[38:39], v[56:57], v[38:39] op_sel_hi:[0,1]
	v_pk_mul_f32 v[44:45], v[56:57], v[44:45] op_sel_hi:[0,1]
	v_pk_mul_f32 v[46:47], v[56:57], v[46:47] op_sel_hi:[0,1]
	v_pk_mul_f32 v[36:37], v[56:57], v[36:37] op_sel_hi:[0,1]
	v_pk_mul_f32 v[38:39], v[42:43], v[38:39]
	v_pk_mul_f32 v[44:45], v[48:49], v[44:45]
	v_pk_mul_f32 v[46:47], v[50:51], v[46:47]
	v_pk_mul_f32 v[36:37], v[40:41], v[36:37]
	v_cvt_pk_bf16_f32 v40, v44, v45
	v_cvt_pk_bf16_f32 v41, v46, v47
	v_add_u32_e32 v52, 0x90, v121
	v_cvt_pk_bf16_f32 v42, v36, v37
	v_cvt_pk_bf16_f32 v39, v38, v39
	ds_bpermute_b32 v36, v120, v40
	ds_bpermute_b32 v37, v120, v41
	ds_bpermute_b32 v38, v120, v42
	ds_bpermute_b32 v39, v120, v39
	v_mad_i64_i32 v[52:53], s[8:9], v52, s11, v[116:117]
	v_lshl_add_u64 v[52:53], v[52:53], 0, v[118:119]
	s_waitcnt lgkmcnt(0)
	global_store_dwordx4 v[52:53], v[36:39], off
	ds_read_b32 v39, v122 offset:640
	s_nop 0
	v_add_u32_e32 v36, 0xa0, v121
	v_mad_i64_i32 v[36:37], s[8:9], v36, s11, v[116:117]
	v_lshl_add_u64 v[36:37], v[36:37], 0, v[118:119]
	s_waitcnt lgkmcnt(0)
	v_mul_f32_e32 v38, 0xbfb8aa3b, v39
	v_pk_mul_f32 v[20:21], v[20:21], v[38:39] op_sel_hi:[1,0]
	v_pk_mul_f32 v[26:27], v[26:27], v[38:39] op_sel_hi:[1,0]
	v_pk_mul_f32 v[28:29], v[28:29], v[38:39] op_sel_hi:[1,0]
	v_pk_mul_f32 v[18:19], v[18:19], v[38:39] op_sel_hi:[1,0]
	v_exp_f32_e32 v20, v20
	v_exp_f32_e32 v21, v21
	v_exp_f32_e32 v26, v26
	v_exp_f32_e32 v27, v27
	v_exp_f32_e32 v28, v28
	v_exp_f32_e32 v29, v29
	v_exp_f32_e32 v18, v18
	v_exp_f32_e32 v19, v19
	v_pk_add_f32 v[20:21], v[20:21], 1.0 op_sel_hi:[1,0]
	v_pk_add_f32 v[26:27], v[26:27], 1.0 op_sel_hi:[1,0]
	v_pk_add_f32 v[28:29], v[28:29], 1.0 op_sel_hi:[1,0]
	v_pk_add_f32 v[18:19], v[18:19], 1.0 op_sel_hi:[1,0]
	v_rcp_f32_e32 v20, v20
	v_rcp_f32_e32 v21, v21
	v_rcp_f32_e32 v26, v26
	v_rcp_f32_e32 v27, v27
	v_rcp_f32_e32 v28, v28
	v_rcp_f32_e32 v29, v29
	v_rcp_f32_e32 v18, v18
	v_rcp_f32_e32 v19, v19
	v_mul_f32_e32 v40, v39, v39
	v_pk_mul_f32 v[20:21], v[40:41], v[20:21] op_sel_hi:[0,1]
	v_pk_mul_f32 v[26:27], v[40:41], v[26:27] op_sel_hi:[0,1]
	v_pk_mul_f32 v[28:29], v[40:41], v[28:29] op_sel_hi:[0,1]
	v_pk_mul_f32 v[18:19], v[40:41], v[18:19] op_sel_hi:[0,1]
	v_pk_mul_f32 v[20:21], v[24:25], v[20:21]
	v_pk_mul_f32 v[26:27], v[30:31], v[26:27]
	v_pk_mul_f32 v[28:29], v[32:33], v[28:29]
	v_pk_mul_f32 v[18:19], v[22:23], v[18:19]
	v_cvt_pk_bf16_f32 v22, v26, v27
	v_cvt_pk_bf16_f32 v23, v28, v29
	s_nop 0
	v_cvt_pk_bf16_f32 v24, v18, v19
	v_cvt_pk_bf16_f32 v21, v20, v21
	ds_bpermute_b32 v18, v120, v22
	ds_bpermute_b32 v19, v120, v23
	ds_bpermute_b32 v20, v120, v24
	ds_bpermute_b32 v21, v120, v21
	s_waitcnt lgkmcnt(0)
	global_store_dwordx4 v[36:37], v[18:21], off
	ds_read_b32 v21, v122 offset:704
	s_nop 0
	v_add_u32_e32 v18, 0xb0, v121
	v_mad_i64_i32 v[18:19], s[8:9], v18, s11, v[116:117]
	v_lshl_add_u64 v[18:19], v[18:19], 0, v[118:119]
	s_waitcnt lgkmcnt(0)
	v_mul_f32_e32 v20, 0xbfb8aa3b, v21
	v_pk_mul_f32 v[6:7], v[6:7], v[20:21] op_sel_hi:[1,0]
	v_mul_f32_e32 v22, v21, v21
	v_exp_f32_e32 v6, v6
	v_exp_f32_e32 v7, v7
	v_pk_mul_f32 v[10:11], v[10:11], v[20:21] op_sel_hi:[1,0]
	v_pk_mul_f32 v[12:13], v[12:13], v[20:21] op_sel_hi:[1,0]
	v_exp_f32_e32 v10, v10
	v_pk_add_f32 v[6:7], v[6:7], 1.0 op_sel_hi:[1,0]
	v_exp_f32_e32 v11, v11
	v_rcp_f32_e32 v6, v6
	v_rcp_f32_e32 v7, v7
	v_exp_f32_e32 v12, v12
	v_exp_f32_e32 v13, v13
	v_pk_add_f32 v[10:11], v[10:11], 1.0 op_sel_hi:[1,0]
	v_pk_mul_f32 v[6:7], v[22:23], v[6:7] op_sel_hi:[0,1]
	v_pk_mul_f32 v[2:3], v[2:3], v[6:7]
	v_pk_mul_f32 v[6:7], v[8:9], v[20:21] op_sel_hi:[1,0]
	v_pk_add_f32 v[12:13], v[12:13], 1.0 op_sel_hi:[1,0]
	v_exp_f32_e32 v6, v6
	v_exp_f32_e32 v7, v7
	v_rcp_f32_e32 v10, v10
	v_rcp_f32_e32 v11, v11
	v_rcp_f32_e32 v12, v12
	v_pk_add_f32 v[6:7], v[6:7], 1.0 op_sel_hi:[1,0]
	v_rcp_f32_e32 v13, v13
	v_rcp_f32_e32 v6, v6
	v_rcp_f32_e32 v7, v7
	v_pk_mul_f32 v[10:11], v[22:23], v[10:11] op_sel_hi:[0,1]
	v_pk_mul_f32 v[12:13], v[22:23], v[12:13] op_sel_hi:[0,1]
	v_pk_mul_f32 v[10:11], v[14:15], v[10:11]
	v_pk_mul_f32 v[6:7], v[22:23], v[6:7] op_sel_hi:[0,1]
	v_pk_mul_f32 v[4:5], v[4:5], v[6:7]
	v_pk_mul_f32 v[12:13], v[16:17], v[12:13]
	v_cvt_pk_bf16_f32 v6, v10, v11
	s_mov_b64 s[8:9], -1
	v_cvt_pk_bf16_f32 v7, v12, v13
	v_cvt_pk_bf16_f32 v8, v2, v3
	v_cvt_pk_bf16_f32 v5, v4, v5
	ds_bpermute_b32 v2, v120, v6
	ds_bpermute_b32 v3, v120, v7
	ds_bpermute_b32 v4, v120, v8
	ds_bpermute_b32 v5, v120, v5
	s_waitcnt lgkmcnt(0)
	global_store_dwordx4 v[18:19], v[2:5], off
	s_cbranch_vccnz .LBB0_1110
	s_andn2_b64 vcc, exec, s[4:5]
	s_cbranch_vccnz .LBB0_1109
	s_barrier
	s_branch .LBB0_1109

.LBB0_1194:
	s_add_u32 s8, s8, 0x160080
	s_addc_u32 s9, s9, 0
	s_add_u32 s20, s18, 0x100
	s_addc_u32 s21, s19, 0
	s_mov_b32 s24, -2
	v_readlane_b32 s35, v255, 20
	v_readlane_b32 s40, v255, 21
	v_readlane_b32 s41, v255, 22
	v_readlane_b32 s57, v255, 23
	s_mov_b64 s[58:59], 0x80
	s_add_u32 s18, s8, 0xffea0080
	s_addc_u32 s19, s9, -1
	s_add_i32 s25, 0, 0x10000
	s_cmpk_eq_i32 s24, 0x54
	s_cselect_b32 s23, s45, s19
	s_cselect_b32 s22, s44, s18
	s_cselect_b32 s19, s47, s21
	s_cselect_b32 s18, s46, s20
	s_add_i32 s34, 0, 0x14000
	v_add_u32_e32 v138, s25, v1
	v_add_u32_e32 v142, s25, v160
	v_add_u32_e32 v146, s35, v1
	v_add_u32_e32 v150, s35, v160
	v_add_u32_e32 v154, s34, v1
	v_add_u32_e32 v158, s34, v160
	ds_read_b128 v[138:141], v138
	ds_read_b128 v[142:145], v142
	ds_read_b128 v[146:149], v146
	ds_read_b128 v[150:153], v150
	ds_read_b128 v[154:157], v154
	ds_read_b128 v[164:167], v158
	v_add_u32_e32 v158, s40, v1
	v_add_u32_e32 v159, s40, v160
	ds_read_b128 v[168:171], v158
	ds_read_b128 v[172:175], v159
	v_lshl_add_u64 v[158:159], s[8:9], 0, v[136:137]
	s_add_i32 m0, s29, 0xc000
	ds_read_b128 v[176:179], v161
	ds_read_b128 v[184:187], v161 offset:2048
	ds_read_b128 v[188:191], v162
	ds_read_b128 v[192:195], v162 offset:2048
	ds_read_b128 v[196:199], v161 offset:4096
	ds_read_b128 v[200:203], v161 offset:6144
	ds_read_b128 v[204:207], v162 offset:4096
	ds_read_b128 v[208:211], v162 offset:6144
	global_load_lds_dwordx4 v[158:159], off
	v_lshl_add_u64 v[158:159], s[8:9], 0, v[134:135]
	s_add_i32 m0, s29, 0xe000
	s_nop 0
	global_load_lds_dwordx4 v[158:159], off
	s_waitcnt vmcnt(8)
	s_waitcnt lgkmcnt(0)
	s_barrier
	s_setprio 1
	s_waitcnt lgkmcnt(0)
	v_mfma_f32_16x16x32_bf16 v[128:131], v[138:141], v[176:179], 0
	v_mfma_f32_16x16x32_bf16 v[124:127], v[146:149], v[176:179], 0
	v_mfma_f32_16x16x32_bf16 v[112:115], v[138:141], v[184:187], 0
	v_mfma_f32_16x16x32_bf16 v[108:111], v[146:149], v[184:187], 0
	v_mfma_f32_16x16x32_bf16 v[96:99], v[138:141], v[196:199], 0
	v_mfma_f32_16x16x32_bf16 v[92:95], v[146:149], v[196:199], 0
	v_mfma_f32_16x16x32_bf16 v[80:83], v[138:141], v[200:203], 0
	v_mfma_f32_16x16x32_bf16 v[76:79], v[146:149], v[200:203], 0
	v_mfma_f32_16x16x32_bf16 v[128:131], v[142:145], v[188:191], v[128:131]
	v_mfma_f32_16x16x32_bf16 v[124:127], v[150:153], v[188:191], v[124:127]
	v_mfma_f32_16x16x32_bf16 v[112:115], v[142:145], v[192:195], v[112:115]
	v_mfma_f32_16x16x32_bf16 v[108:111], v[150:153], v[192:195], v[108:111]
	v_mfma_f32_16x16x32_bf16 v[96:99], v[142:145], v[204:207], v[96:99]
	v_mfma_f32_16x16x32_bf16 v[92:95], v[150:153], v[204:207], v[92:95]
	v_mfma_f32_16x16x32_bf16 v[80:83], v[142:145], v[208:211], v[80:83]
	v_mfma_f32_16x16x32_bf16 v[76:79], v[150:153], v[208:211], v[76:79]
	s_setprio 0
	s_setprio 1
	v_mfma_f32_16x16x32_bf16 v[120:123], v[154:157], v[176:179], 0
	v_mfma_f32_16x16x32_bf16 v[116:119], v[168:171], v[176:179], 0
	v_mfma_f32_16x16x32_bf16 v[104:107], v[154:157], v[184:187], 0
	v_mfma_f32_16x16x32_bf16 v[100:103], v[168:171], v[184:187], 0
	v_mfma_f32_16x16x32_bf16 v[88:91], v[154:157], v[196:199], 0
	v_mfma_f32_16x16x32_bf16 v[84:87], v[168:171], v[196:199], 0
	v_mfma_f32_16x16x32_bf16 v[72:75], v[154:157], v[200:203], 0
	v_mfma_f32_16x16x32_bf16 v[68:71], v[168:171], v[200:203], 0
	v_mfma_f32_16x16x32_bf16 v[120:123], v[164:167], v[188:191], v[120:123]
	v_mfma_f32_16x16x32_bf16 v[116:119], v[172:175], v[188:191], v[116:119]
	v_mfma_f32_16x16x32_bf16 v[104:107], v[164:167], v[192:195], v[104:107]
	v_mfma_f32_16x16x32_bf16 v[100:103], v[172:175], v[192:195], v[100:103]
	v_mfma_f32_16x16x32_bf16 v[88:91], v[164:167], v[204:207], v[88:91]
	v_mfma_f32_16x16x32_bf16 v[84:87], v[172:175], v[204:207], v[84:87]
	v_mfma_f32_16x16x32_bf16 v[72:75], v[164:167], v[208:211], v[72:75]
	v_mfma_f32_16x16x32_bf16 v[68:71], v[172:175], v[208:211], v[68:71]
	s_setprio 0
	s_barrier
	s_add_i32 s25, s25, s28
	v_lshl_add_u64 v[158:159], s[18:19], 0, v[34:35]
	s_mov_b32 m0, s25
	ds_read_b128 v[176:179], v161 offset:16384
	ds_read_b128 v[184:187], v161 offset:18432
	ds_read_b128 v[188:191], v162 offset:16384
	ds_read_b128 v[192:195], v162 offset:18432
	ds_read_b128 v[196:199], v161 offset:20480
	ds_read_b128 v[200:203], v161 offset:22528
	ds_read_b128 v[204:207], v162 offset:20480
	ds_read_b128 v[208:211], v162 offset:22528
	global_load_lds_dwordx4 v[158:159], off
	s_add_i32 m0, s25, 0x2000
	s_add_u32 s30, s18, 0x160000
	v_lshl_add_u64 v[180:181], s[18:19], 0, v[132:133]
	s_addc_u32 s31, s19, 0
	s_add_i32 s25, s34, s28
	global_load_lds_dwordx4 v[180:181], off
	v_lshl_add_u64 v[182:183], s[30:31], 0, v[34:35]
	s_mov_b32 m0, s25
	v_lshl_add_u64 v[212:213], s[22:23], 0, v[134:135]
	global_load_lds_dwordx4 v[182:183], off
	v_lshl_add_u64 v[182:183], s[30:31], 0, v[132:133]
	s_add_i32 m0, s25, 0x2000
	s_nop 0
	global_load_lds_dwordx4 v[182:183], off
	v_lshl_add_u64 v[182:183], s[22:23], 0, v[136:137]
	s_mov_b32 m0, s29
	s_nop 0
	global_load_lds_dwordx4 v[182:183], off
	s_mov_b32 m0, s33
	s_nop 0
	global_load_lds_dwordx4 v[212:213], off
	s_waitcnt vmcnt(8)
	s_waitcnt lgkmcnt(0)
	s_barrier
	s_setprio 1
	s_waitcnt lgkmcnt(0)
	v_mfma_f32_16x16x32_bf16 v[64:67], v[138:141], v[176:179], 0
	v_mfma_f32_16x16x32_bf16 v[60:63], v[146:149], v[176:179], 0
	v_mfma_f32_16x16x32_bf16 v[48:51], v[138:141], v[184:187], 0
	v_mfma_f32_16x16x32_bf16 v[44:47], v[146:149], v[184:187], 0
	v_mfma_f32_16x16x32_bf16 v[30:33], v[138:141], v[196:199], 0
	v_mfma_f32_16x16x32_bf16 v[26:29], v[146:149], v[196:199], 0
	v_mfma_f32_16x16x32_bf16 v[14:17], v[138:141], v[200:203], 0
	v_mfma_f32_16x16x32_bf16 v[10:13], v[146:149], v[200:203], 0
	v_mfma_f32_16x16x32_bf16 v[64:67], v[142:145], v[188:191], v[64:67]
	v_mfma_f32_16x16x32_bf16 v[60:63], v[150:153], v[188:191], v[60:63]
	v_mfma_f32_16x16x32_bf16 v[48:51], v[142:145], v[192:195], v[48:51]
	v_mfma_f32_16x16x32_bf16 v[44:47], v[150:153], v[192:195], v[44:47]
	v_mfma_f32_16x16x32_bf16 v[30:33], v[142:145], v[204:207], v[30:33]
	v_mfma_f32_16x16x32_bf16 v[26:29], v[150:153], v[204:207], v[26:29]
	v_mfma_f32_16x16x32_bf16 v[14:17], v[142:145], v[208:211], v[14:17]
	v_mfma_f32_16x16x32_bf16 v[10:13], v[150:153], v[208:211], v[10:13]
	s_setprio 0
	s_setprio 1
	v_mfma_f32_16x16x32_bf16 v[56:59], v[154:157], v[176:179], 0
	v_mfma_f32_16x16x32_bf16 v[52:55], v[168:171], v[176:179], 0
	v_mfma_f32_16x16x32_bf16 v[40:43], v[154:157], v[184:187], 0
	v_mfma_f32_16x16x32_bf16 v[36:39], v[168:171], v[184:187], 0
	v_mfma_f32_16x16x32_bf16 v[22:25], v[154:157], v[196:199], 0
	v_mfma_f32_16x16x32_bf16 v[18:21], v[168:171], v[196:199], 0
	v_mfma_f32_16x16x32_bf16 v[6:9], v[154:157], v[200:203], 0
	v_mfma_f32_16x16x32_bf16 v[2:5], v[168:171], v[200:203], 0
	v_mfma_f32_16x16x32_bf16 v[56:59], v[164:167], v[188:191], v[56:59]
	v_mfma_f32_16x16x32_bf16 v[52:55], v[172:175], v[188:191], v[52:55]
	v_mfma_f32_16x16x32_bf16 v[40:43], v[164:167], v[192:195], v[40:43]
	v_mfma_f32_16x16x32_bf16 v[36:39], v[172:175], v[192:195], v[36:39]
	v_mfma_f32_16x16x32_bf16 v[22:25], v[164:167], v[204:207], v[22:25]
	v_mfma_f32_16x16x32_bf16 v[18:21], v[172:175], v[204:207], v[18:21]
	v_mfma_f32_16x16x32_bf16 v[6:9], v[164:167], v[208:211], v[6:9]
	v_mfma_f32_16x16x32_bf16 v[2:5], v[172:175], v[208:211], v[2:5]
	s_setprio 0
	s_barrier
	s_add_i32 s25, 0, 0x18000
	s_add_i32 s30, 0, 0x1c000
	v_add_u32_e32 v138, s25, v1
	v_add_u32_e32 v142, s25, v160
	v_add_u32_e32 v146, s41, v1
	v_add_u32_e32 v150, s41, v160
	v_add_u32_e32 v154, s30, v1
	v_add_u32_e32 v163, s30, v160
	ds_read_b128 v[138:141], v138
	ds_read_b128 v[142:145], v142
	ds_read_b128 v[146:149], v146
	ds_read_b128 v[150:153], v150
	ds_read_b128 v[154:157], v154
	ds_read_b128 v[164:167], v163
	v_add_u32_e32 v163, s57, v1
	v_add_u32_e32 v172, s57, v160
	ds_read_b128 v[168:171], v163
	ds_read_b128 v[172:175], v172
	s_add_u32 s22, s22, 0x160000
	s_addc_u32 s23, s23, 0
	s_mov_b32 m0, s48
	v_lshl_add_u64 v[218:219], s[22:23], 0, v[136:137]
	ds_read_b128 v[176:179], v161 offset:32768
	ds_read_b128 v[184:187], v161 offset:34816
	ds_read_b128 v[188:191], v162 offset:32768
	ds_read_b128 v[192:195], v162 offset:34816
	ds_read_b128 v[196:199], v161 offset:36864
	ds_read_b128 v[200:203], v161 offset:38912
	ds_read_b128 v[204:207], v162 offset:36864
	ds_read_b128 v[208:211], v162 offset:38912
	global_load_lds_dwordx4 v[218:219], off
	v_lshl_add_u64 v[218:219], s[22:23], 0, v[134:135]
	s_mov_b32 m0, s49
	s_nop 0
	global_load_lds_dwordx4 v[218:219], off
	s_waitcnt vmcnt(8)
	s_waitcnt lgkmcnt(0)
	s_barrier
	s_setprio 1
	s_waitcnt lgkmcnt(0)
	v_mfma_f32_16x16x32_bf16 v[128:131], v[138:141], v[176:179], v[128:131]
	v_mfma_f32_16x16x32_bf16 v[124:127], v[146:149], v[176:179], v[124:127]
	v_mfma_f32_16x16x32_bf16 v[112:115], v[138:141], v[184:187], v[112:115]
	v_mfma_f32_16x16x32_bf16 v[108:111], v[146:149], v[184:187], v[108:111]
	v_mfma_f32_16x16x32_bf16 v[96:99], v[138:141], v[196:199], v[96:99]
	v_mfma_f32_16x16x32_bf16 v[92:95], v[146:149], v[196:199], v[92:95]
	v_mfma_f32_16x16x32_bf16 v[80:83], v[138:141], v[200:203], v[80:83]
	v_mfma_f32_16x16x32_bf16 v[76:79], v[146:149], v[200:203], v[76:79]
	v_mfma_f32_16x16x32_bf16 v[128:131], v[142:145], v[188:191], v[128:131]
	v_mfma_f32_16x16x32_bf16 v[124:127], v[150:153], v[188:191], v[124:127]
	v_mfma_f32_16x16x32_bf16 v[112:115], v[142:145], v[192:195], v[112:115]
	v_mfma_f32_16x16x32_bf16 v[108:111], v[150:153], v[192:195], v[108:111]
	v_mfma_f32_16x16x32_bf16 v[96:99], v[142:145], v[204:207], v[96:99]
	v_mfma_f32_16x16x32_bf16 v[92:95], v[150:153], v[204:207], v[92:95]
	v_mfma_f32_16x16x32_bf16 v[80:83], v[142:145], v[208:211], v[80:83]
	v_mfma_f32_16x16x32_bf16 v[76:79], v[150:153], v[208:211], v[76:79]
	s_setprio 0
	s_setprio 1
	v_mfma_f32_16x16x32_bf16 v[120:123], v[154:157], v[176:179], v[120:123]
	v_mfma_f32_16x16x32_bf16 v[116:119], v[168:171], v[176:179], v[116:119]
	v_mfma_f32_16x16x32_bf16 v[104:107], v[154:157], v[184:187], v[104:107]
	v_mfma_f32_16x16x32_bf16 v[100:103], v[168:171], v[184:187], v[100:103]
	v_mfma_f32_16x16x32_bf16 v[88:91], v[154:157], v[196:199], v[88:91]
	v_mfma_f32_16x16x32_bf16 v[84:87], v[168:171], v[196:199], v[84:87]
	v_mfma_f32_16x16x32_bf16 v[72:75], v[154:157], v[200:203], v[72:75]
	v_mfma_f32_16x16x32_bf16 v[68:71], v[168:171], v[200:203], v[68:71]
	v_mfma_f32_16x16x32_bf16 v[120:123], v[164:167], v[188:191], v[120:123]
	v_mfma_f32_16x16x32_bf16 v[116:119], v[172:175], v[188:191], v[116:119]
	v_mfma_f32_16x16x32_bf16 v[104:107], v[164:167], v[192:195], v[104:107]
	v_mfma_f32_16x16x32_bf16 v[100:103], v[172:175], v[192:195], v[100:103]
	v_mfma_f32_16x16x32_bf16 v[88:91], v[164:167], v[204:207], v[88:91]
	v_mfma_f32_16x16x32_bf16 v[84:87], v[172:175], v[204:207], v[84:87]
	v_mfma_f32_16x16x32_bf16 v[72:75], v[164:167], v[208:211], v[72:75]
	v_mfma_f32_16x16x32_bf16 v[68:71], v[172:175], v[208:211], v[68:71]
	s_setprio 0
	s_barrier
	s_add_i32 s22, s25, s28
	v_lshl_add_u64 v[158:159], v[158:159], 0, s[58:59]
	s_mov_b32 m0, s22
	ds_read_b128 v[176:179], v161 offset:49152
	ds_read_b128 v[184:187], v161 offset:51200
	ds_read_b128 v[188:191], v162 offset:49152
	ds_read_b128 v[192:195], v162 offset:51200
	ds_read_b128 v[196:199], v161 offset:53248
	ds_read_b128 v[200:203], v161 offset:55296
	ds_read_b128 v[204:207], v162 offset:53248
	ds_read_b128 v[208:211], v162 offset:55296
	global_load_lds_dwordx4 v[158:159], off
	s_add_i32 m0, s22, 0x2000
	s_add_u32 s18, s18, 0x160080
	v_lshl_add_u64 v[158:159], v[180:181], 0, s[58:59]
	s_addc_u32 s19, s19, 0
	s_add_i32 s22, s30, s28
	global_load_lds_dwordx4 v[158:159], off
	v_lshl_add_u64 v[158:159], s[18:19], 0, v[34:35]
	s_mov_b32 m0, s22
	s_nop 0
	global_load_lds_dwordx4 v[158:159], off
	v_lshl_add_u64 v[158:159], s[18:19], 0, v[132:133]
	s_add_i32 m0, s22, 0x2000
	s_nop 0
	global_load_lds_dwordx4 v[158:159], off
	v_lshl_add_u64 v[158:159], v[182:183], 0, s[58:59]
	s_mov_b32 m0, s53
	s_nop 0
	global_load_lds_dwordx4 v[158:159], off
	v_lshl_add_u64 v[158:159], v[212:213], 0, s[58:59]
	s_mov_b32 m0, s54
	s_nop 0
	global_load_lds_dwordx4 v[158:159], off
	s_waitcnt vmcnt(8)
	s_waitcnt lgkmcnt(0)
	s_barrier
	s_setprio 1
	s_waitcnt lgkmcnt(0)
	v_mfma_f32_16x16x32_bf16 v[64:67], v[138:141], v[176:179], v[64:67]
	v_mfma_f32_16x16x32_bf16 v[60:63], v[146:149], v[176:179], v[60:63]
	v_mfma_f32_16x16x32_bf16 v[48:51], v[138:141], v[184:187], v[48:51]
	v_mfma_f32_16x16x32_bf16 v[44:47], v[146:149], v[184:187], v[44:47]
	v_mfma_f32_16x16x32_bf16 v[30:33], v[138:141], v[196:199], v[30:33]
	v_mfma_f32_16x16x32_bf16 v[26:29], v[146:149], v[196:199], v[26:29]
	v_mfma_f32_16x16x32_bf16 v[14:17], v[138:141], v[200:203], v[14:17]
	v_mfma_f32_16x16x32_bf16 v[10:13], v[146:149], v[200:203], v[10:13]
	v_mfma_f32_16x16x32_bf16 v[64:67], v[142:145], v[188:191], v[64:67]
	v_mfma_f32_16x16x32_bf16 v[60:63], v[150:153], v[188:191], v[60:63]
	v_mfma_f32_16x16x32_bf16 v[48:51], v[142:145], v[192:195], v[48:51]
	v_mfma_f32_16x16x32_bf16 v[44:47], v[150:153], v[192:195], v[44:47]
	v_mfma_f32_16x16x32_bf16 v[30:33], v[142:145], v[204:207], v[30:33]
	v_mfma_f32_16x16x32_bf16 v[26:29], v[150:153], v[204:207], v[26:29]
	v_mfma_f32_16x16x32_bf16 v[14:17], v[142:145], v[208:211], v[14:17]
	v_mfma_f32_16x16x32_bf16 v[10:13], v[150:153], v[208:211], v[10:13]
	s_setprio 0
	s_setprio 1
	v_mfma_f32_16x16x32_bf16 v[56:59], v[154:157], v[176:179], v[56:59]
	v_mfma_f32_16x16x32_bf16 v[52:55], v[168:171], v[176:179], v[52:55]
	v_mfma_f32_16x16x32_bf16 v[40:43], v[154:157], v[184:187], v[40:43]
	v_mfma_f32_16x16x32_bf16 v[36:39], v[168:171], v[184:187], v[36:39]
	v_mfma_f32_16x16x32_bf16 v[22:25], v[154:157], v[196:199], v[22:25]
	v_mfma_f32_16x16x32_bf16 v[18:21], v[168:171], v[196:199], v[18:21]
	v_mfma_f32_16x16x32_bf16 v[6:9], v[154:157], v[200:203], v[6:9]
	v_mfma_f32_16x16x32_bf16 v[2:5], v[168:171], v[200:203], v[2:5]
	v_mfma_f32_16x16x32_bf16 v[56:59], v[164:167], v[188:191], v[56:59]
	v_mfma_f32_16x16x32_bf16 v[52:55], v[172:175], v[188:191], v[52:55]
	v_mfma_f32_16x16x32_bf16 v[40:43], v[164:167], v[192:195], v[40:43]
	v_mfma_f32_16x16x32_bf16 v[36:39], v[172:175], v[192:195], v[36:39]
	v_mfma_f32_16x16x32_bf16 v[22:25], v[164:167], v[204:207], v[22:25]
	v_mfma_f32_16x16x32_bf16 v[18:21], v[172:175], v[204:207], v[18:21]
	v_mfma_f32_16x16x32_bf16 v[6:9], v[164:167], v[208:211], v[6:9]
	v_mfma_f32_16x16x32_bf16 v[2:5], v[172:175], v[208:211], v[2:5]
	s_setprio 0
	s_barrier
	s_add_i32 s24, s24, 2
	s_add_u32 s8, s8, 0x100
	s_addc_u32 s9, s9, 0
	s_add_u32 s20, s20, 0x100
	s_addc_u32 s21, s21, 0
	s_cmpk_gt_u32 s24, 0x55
	s_cbranch_scc1 .Lpeel_done_P7

.LBB0_1198:
	v_mov_b32_e32 v141, v0
	s_lshl_b32 s8, s13, 8
	s_add_i32 s8, s8, s51
	v_bfe_u32 v138, v141, 2, 4
	v_or_b32_e32 v140, s8, v138
	s_lshl_b32 s8, s12, 8
	v_lshlrev_b32_e32 v138, 3, v141
	v_and_b32_e32 v142, 15, v141
	v_and_b32_e32 v143, 63, v141
	v_and_or_b32 v138, v138, 24, s8
	v_lshrrev_b32_e32 v144, 2, v141
	v_lshlrev_b32_e32 v141, 6, v141
	s_movk_i32 s8, 0xfc
	v_or_b32_e32 v138, s52, v138
	v_bitop3_b32 v163, v141, s8, v143 bitop3:0xc8
	v_readlane_b32 s8, v254, 38
	v_ashrrev_i32_e32 v139, 31, v138
	v_lshlrev_b32_e32 v142, 4, v142
	v_readlane_b32 s9, v254, 39
	v_ashrrev_i32_e32 v141, 31, v140
	v_and_or_b32 v164, v144, 12, v142
	v_lshl_add_u64 v[142:143], v[138:139], 1, s[8:9]
	v_lshlrev_b64 v[144:145], 12, v[140:141]
	v_lshl_add_u64 v[154:155], v[142:143], 0, v[144:145]
	global_load_dwordx4 v[166:169], v[154:155], off
	global_load_dwordx4 v[170:173], v[154:155], off offset:256
	v_or_b32_e32 v156, 16, v140
	v_ashrrev_i32_e32 v157, 31, v156
	v_lshlrev_b64 v[144:145], 12, v[156:157]
	v_lshl_add_u64 v[150:151], v[142:143], 0, v[144:145]
	v_or_b32_e32 v152, 32, v140
	global_load_dwordx4 v[174:177], v[150:151], off
	global_load_dwordx4 v[196:199], v[150:151], off offset:256
	v_ashrrev_i32_e32 v153, 31, v152
	v_or_b32_e32 v148, 48, v140
	v_lshlrev_b64 v[144:145], 12, v[152:153]
	v_ashrrev_i32_e32 v149, 31, v148
	v_lshl_add_u64 v[146:147], v[142:143], 0, v[144:145]
	v_lshlrev_b64 v[144:145], 12, v[148:149]
	v_lshl_add_u64 v[144:145], v[142:143], 0, v[144:145]
	global_load_dwordx4 v[200:203], v[146:147], off
	global_load_dwordx4 v[204:207], v[146:147], off offset:256
	global_load_dwordx4 v[208:211], v[144:145], off
	global_load_dwordx4 v[224:227], v[144:145], off offset:256
	v_lshlrev_b64 v[158:159], 11, v[140:141]
	v_lshl_add_u64 v[158:159], v[158:159], 0, v[138:139]
	s_andn2_b64 vcc, exec, s[42:43]
	s_waitcnt vmcnt(0)
	ds_bpermute_b32 v180, v164, v166
	ds_bpermute_b32 v181, v164, v167
	ds_bpermute_b32 v182, v164, v168
	ds_bpermute_b32 v183, v164, v169
	ds_bpermute_b32 v195, v164, v170
	ds_bpermute_b32 v194, v164, v171
	ds_bpermute_b32 v193, v164, v172
	ds_bpermute_b32 v187, v164, v196
	s_waitcnt lgkmcnt(7)
	v_lshlrev_b32_e32 v196, 16, v180
	v_and_b32_e32 v180, 0xffff0000, v180
	v_add_f32_e32 v128, v128, v196
	v_add_f32_e32 v196, v129, v180
	s_waitcnt lgkmcnt(6)
	v_lshlrev_b32_e32 v129, 16, v181
	v_add_f32_e32 v129, v130, v129
	v_and_b32_e32 v130, 0xffff0000, v181
	v_add_f32_e32 v131, v131, v130
	s_waitcnt lgkmcnt(5)
	v_lshlrev_b32_e32 v130, 16, v182
	ds_bpermute_b32 v192, v164, v173
	ds_bpermute_b32 v191, v164, v174
	ds_bpermute_b32 v190, v164, v175
	ds_bpermute_b32 v189, v164, v176
	ds_bpermute_b32 v188, v164, v177
	ds_bpermute_b32 v186, v164, v197
	ds_bpermute_b32 v185, v164, v198
	ds_bpermute_b32 v184, v164, v199
	ds_bpermute_b32 v179, v164, v200
	ds_bpermute_b32 v178, v164, v201
	ds_bpermute_b32 v177, v164, v202
	ds_bpermute_b32 v176, v164, v203
	ds_bpermute_b32 v175, v164, v204
	ds_bpermute_b32 v174, v164, v205
	ds_bpermute_b32 v173, v164, v206
	ds_bpermute_b32 v172, v164, v207
	ds_bpermute_b32 v171, v164, v208
	ds_bpermute_b32 v170, v164, v209
	ds_bpermute_b32 v169, v164, v210
	ds_bpermute_b32 v168, v164, v211
	ds_bpermute_b32 v167, v164, v224
	ds_bpermute_b32 v166, v164, v225
	ds_bpermute_b32 v165, v164, v226
	ds_bpermute_b32 v141, v164, v227
	v_add_f32_e32 v130, v124, v130
	v_and_b32_e32 v124, 0xffff0000, v182
	v_add_f32_e32 v197, v125, v124
	s_waitcnt lgkmcnt(14)
	v_lshlrev_b32_e32 v124, 16, v183
	v_add_f32_e32 v126, v126, v124
	v_and_b32_e32 v124, 0xffff0000, v183
	v_add_f32_e32 v127, v127, v124
	v_cndmask_b32_e64 v124, 0, 1, s[42:43]
	v_cmp_ne_u32_e64 s[40:41], 1, v124
	v_lshl_add_u64 v[124:125], v[158:159], 2, s[6:7]
	s_cbranch_vccnz .LBB0_1249
	ds_bpermute_b32 v198, v163, v128
	ds_bpermute_b32 v199, v163, v196
	ds_bpermute_b32 v200, v163, v129
	ds_bpermute_b32 v201, v163, v131
	ds_bpermute_b32 v202, v163, v130
	ds_bpermute_b32 v203, v163, v197
	ds_bpermute_b32 v204, v163, v126
	ds_bpermute_b32 v205, v163, v127
	s_waitcnt lgkmcnt(4)
	global_store_dwordx4 v[124:125], v[198:201], off
	s_waitcnt lgkmcnt(0)
	global_store_dwordx4 v[124:125], v[202:205], off offset:16
	s_cbranch_execnz .LBB0_1201
.LBB0_1200:
	v_cvt_pk_bf16_f32 v128, v128, v196
	v_cvt_pk_bf16_f32 v129, v129, v131
	v_cvt_pk_bf16_f32 v130, v130, v197
	v_cvt_pk_bf16_f32 v131, v126, v127
	ds_bpermute_b32 v126, v163, v128
	ds_bpermute_b32 v127, v163, v129
	ds_bpermute_b32 v128, v163, v130
	ds_bpermute_b32 v129, v163, v131
	s_waitcnt lgkmcnt(0)
	global_store_dwordx4 v[154:155], v[126:129], off
.LBB0_1201:
	s_nop 1
	v_lshlrev_b32_e32 v126, 16, v195
	v_add_f32_e32 v120, v120, v126
	v_and_b32_e32 v126, 0xffff0000, v195
	v_add_f32_e32 v126, v121, v126
	v_lshlrev_b32_e32 v121, 16, v194
	v_add_f32_e32 v121, v122, v121
	v_and_b32_e32 v122, 0xffff0000, v194
	v_add_f32_e32 v122, v123, v122
	v_lshlrev_b32_e32 v123, 16, v193
	v_add_f32_e32 v116, v116, v123
	v_and_b32_e32 v123, 0xffff0000, v193
	v_add_f32_e32 v123, v117, v123
	v_lshlrev_b32_e32 v117, 16, v192
	v_add_f32_e32 v117, v118, v117
	v_and_b32_e32 v118, 0xffff0000, v192
	s_and_b64 vcc, exec, s[40:41]
	v_add_f32_e32 v118, v119, v118
	s_cbranch_vccnz .LBB0_1250
	ds_bpermute_b32 v128, v163, v120
	ds_bpermute_b32 v129, v163, v126
	ds_bpermute_b32 v130, v163, v121
	ds_bpermute_b32 v131, v163, v122
	ds_bpermute_b32 v192, v163, v116
	ds_bpermute_b32 v193, v163, v123
	ds_bpermute_b32 v194, v163, v117
	ds_bpermute_b32 v195, v163, v118
	s_waitcnt lgkmcnt(4)
	global_store_dwordx4 v[124:125], v[128:131], off offset:512
	s_waitcnt lgkmcnt(0)
	global_store_dwordx4 v[124:125], v[192:195], off offset:528
	s_cbranch_execnz .LBB0_1204
.LBB0_1203:
	v_cvt_pk_bf16_f32 v119, v120, v126
	v_cvt_pk_bf16_f32 v120, v121, v122
	v_cvt_pk_bf16_f32 v121, v116, v123
	v_cvt_pk_bf16_f32 v122, v117, v118
	ds_bpermute_b32 v116, v163, v119
	ds_bpermute_b32 v117, v163, v120
	ds_bpermute_b32 v118, v163, v121
	ds_bpermute_b32 v119, v163, v122
	s_waitcnt lgkmcnt(0)
	global_store_dwordx4 v[154:155], v[116:119], off offset:256
.LBB0_1204:
	s_nop 1
	v_lshlrev_b64 v[116:117], 11, v[156:157]
	v_lshl_add_u64 v[118:119], v[116:117], 0, v[138:139]
	v_lshlrev_b32_e32 v116, 16, v191
	v_add_f32_e32 v112, v112, v116
	v_and_b32_e32 v116, 0xffff0000, v191
	v_add_f32_e32 v116, v113, v116
	v_lshlrev_b32_e32 v113, 16, v190
	v_add_f32_e32 v113, v114, v113
	v_and_b32_e32 v114, 0xffff0000, v190
	v_add_f32_e32 v115, v115, v114
	v_lshlrev_b32_e32 v114, 16, v189
	v_add_f32_e32 v114, v108, v114
	v_and_b32_e32 v108, 0xffff0000, v189
	v_add_f32_e32 v117, v109, v108
	v_lshlrev_b32_e32 v108, 16, v188
	v_add_f32_e32 v110, v110, v108
	v_and_b32_e32 v108, 0xffff0000, v188
	v_add_f32_e32 v111, v111, v108
	s_and_b64 vcc, exec, s[40:41]
	v_lshl_add_u64 v[108:109], v[118:119], 2, s[6:7]
	s_cbranch_vccnz .LBB0_1251
	ds_bpermute_b32 v118, v163, v112
	ds_bpermute_b32 v119, v163, v116
	ds_bpermute_b32 v120, v163, v113
	ds_bpermute_b32 v121, v163, v115
	ds_bpermute_b32 v122, v163, v114
	ds_bpermute_b32 v123, v163, v117
	ds_bpermute_b32 v124, v163, v110
	ds_bpermute_b32 v125, v163, v111
	s_waitcnt lgkmcnt(4)
	global_store_dwordx4 v[108:109], v[118:121], off
	s_waitcnt lgkmcnt(0)
	global_store_dwordx4 v[108:109], v[122:125], off offset:16
	s_cbranch_execnz .LBB0_1207
.LBB0_1206:
	v_cvt_pk_bf16_f32 v112, v112, v116
	v_cvt_pk_bf16_f32 v113, v113, v115
	v_cvt_pk_bf16_f32 v114, v114, v117
	v_cvt_pk_bf16_f32 v115, v110, v111
	ds_bpermute_b32 v110, v163, v112
	ds_bpermute_b32 v111, v163, v113
	ds_bpermute_b32 v112, v163, v114
	ds_bpermute_b32 v113, v163, v115
	s_waitcnt lgkmcnt(0)
	global_store_dwordx4 v[150:151], v[110:113], off
.LBB0_1207:
	s_nop 1
	v_lshlrev_b32_e32 v110, 16, v187
	v_add_f32_e32 v104, v104, v110
	v_and_b32_e32 v110, 0xffff0000, v187
	v_add_f32_e32 v110, v105, v110
	v_lshlrev_b32_e32 v105, 16, v186
	v_add_f32_e32 v105, v106, v105
	v_and_b32_e32 v106, 0xffff0000, v186
	v_add_f32_e32 v106, v107, v106
	v_lshlrev_b32_e32 v107, 16, v185
	v_add_f32_e32 v100, v100, v107
	v_and_b32_e32 v107, 0xffff0000, v185
	v_add_f32_e32 v107, v101, v107
	v_lshlrev_b32_e32 v101, 16, v184
	v_add_f32_e32 v101, v102, v101
	v_and_b32_e32 v102, 0xffff0000, v184
	s_and_b64 vcc, exec, s[40:41]
	v_add_f32_e32 v102, v103, v102
	s_cbranch_vccnz .LBB0_1252
	ds_bpermute_b32 v112, v163, v104
	ds_bpermute_b32 v113, v163, v110
	ds_bpermute_b32 v114, v163, v105
	ds_bpermute_b32 v115, v163, v106
	ds_bpermute_b32 v116, v163, v100
	ds_bpermute_b32 v117, v163, v107
	ds_bpermute_b32 v118, v163, v101
	ds_bpermute_b32 v119, v163, v102
	s_waitcnt lgkmcnt(4)
	global_store_dwordx4 v[108:109], v[112:115], off offset:512
	s_waitcnt lgkmcnt(0)
	global_store_dwordx4 v[108:109], v[116:119], off offset:528
	s_cbranch_execnz .LBB0_1210
.LBB0_1209:
	v_cvt_pk_bf16_f32 v103, v104, v110
	v_cvt_pk_bf16_f32 v104, v105, v106
	v_cvt_pk_bf16_f32 v105, v100, v107
	v_cvt_pk_bf16_f32 v106, v101, v102
	ds_bpermute_b32 v100, v163, v103
	ds_bpermute_b32 v101, v163, v104
	ds_bpermute_b32 v102, v163, v105
	ds_bpermute_b32 v103, v163, v106
	s_waitcnt lgkmcnt(0)
	global_store_dwordx4 v[150:151], v[100:103], off offset:256
.LBB0_1210:
	s_nop 1
	v_lshlrev_b64 v[100:101], 11, v[152:153]
	v_lshl_add_u64 v[102:103], v[100:101], 0, v[138:139]
	v_lshlrev_b32_e32 v100, 16, v179
	v_add_f32_e32 v96, v96, v100
	v_and_b32_e32 v100, 0xffff0000, v179
	v_add_f32_e32 v100, v97, v100
	v_lshlrev_b32_e32 v97, 16, v178
	v_add_f32_e32 v97, v98, v97
	v_and_b32_e32 v98, 0xffff0000, v178
	v_add_f32_e32 v99, v99, v98
	s_waitcnt lgkmcnt(13)
	v_lshlrev_b32_e32 v98, 16, v177
	v_add_f32_e32 v98, v92, v98
	v_and_b32_e32 v92, 0xffff0000, v177
	v_add_f32_e32 v101, v93, v92
	s_waitcnt lgkmcnt(12)
	v_lshlrev_b32_e32 v92, 16, v176
	v_add_f32_e32 v94, v94, v92
	v_and_b32_e32 v92, 0xffff0000, v176
	v_add_f32_e32 v95, v95, v92
	s_and_b64 vcc, exec, s[40:41]
	v_lshl_add_u64 v[92:93], v[102:103], 2, s[6:7]
	s_cbranch_vccnz .LBB0_1253
	ds_bpermute_b32 v102, v163, v96
	ds_bpermute_b32 v103, v163, v100
	ds_bpermute_b32 v104, v163, v97
	ds_bpermute_b32 v105, v163, v99
	ds_bpermute_b32 v106, v163, v98
	ds_bpermute_b32 v107, v163, v101
	ds_bpermute_b32 v108, v163, v94
	ds_bpermute_b32 v109, v163, v95
	s_waitcnt lgkmcnt(4)
	global_store_dwordx4 v[92:93], v[102:105], off
	s_waitcnt lgkmcnt(0)
	global_store_dwordx4 v[92:93], v[106:109], off offset:16
	s_cbranch_execnz .LBB0_1213
.LBB0_1212:
	v_cvt_pk_bf16_f32 v96, v96, v100
	v_cvt_pk_bf16_f32 v97, v97, v99
	v_cvt_pk_bf16_f32 v98, v98, v101
	v_cvt_pk_bf16_f32 v99, v94, v95
	ds_bpermute_b32 v94, v163, v96
	ds_bpermute_b32 v95, v163, v97
	ds_bpermute_b32 v96, v163, v98
	ds_bpermute_b32 v97, v163, v99
	s_waitcnt lgkmcnt(0)
	global_store_dwordx4 v[146:147], v[94:97], off
.LBB0_1213:
	s_waitcnt lgkmcnt(11)
	s_nop 0
	v_lshlrev_b32_e32 v94, 16, v175
	v_add_f32_e32 v88, v88, v94
	v_and_b32_e32 v94, 0xffff0000, v175
	v_add_f32_e32 v94, v89, v94
	s_waitcnt lgkmcnt(10)
	v_lshlrev_b32_e32 v89, 16, v174
	v_add_f32_e32 v89, v90, v89
	v_and_b32_e32 v90, 0xffff0000, v174
	v_add_f32_e32 v90, v91, v90
	s_waitcnt lgkmcnt(9)
	v_lshlrev_b32_e32 v91, 16, v173
	v_add_f32_e32 v84, v84, v91
	v_and_b32_e32 v91, 0xffff0000, v173
	v_add_f32_e32 v91, v85, v91
	s_waitcnt lgkmcnt(8)
	v_lshlrev_b32_e32 v85, 16, v172
	v_add_f32_e32 v85, v86, v85
	v_and_b32_e32 v86, 0xffff0000, v172
	s_and_b64 vcc, exec, s[40:41]
	v_add_f32_e32 v86, v87, v86
	s_cbranch_vccnz .LBB0_1254
	ds_bpermute_b32 v96, v163, v88
	ds_bpermute_b32 v97, v163, v94
	ds_bpermute_b32 v98, v163, v89
	ds_bpermute_b32 v99, v163, v90
	ds_bpermute_b32 v100, v163, v84
	ds_bpermute_b32 v101, v163, v91
	ds_bpermute_b32 v102, v163, v85
	ds_bpermute_b32 v103, v163, v86
	s_waitcnt lgkmcnt(4)
	global_store_dwordx4 v[92:93], v[96:99], off offset:512
	s_waitcnt lgkmcnt(0)
	global_store_dwordx4 v[92:93], v[100:103], off offset:528
	s_cbranch_execnz .LBB0_1216
.LBB0_1215:
	v_cvt_pk_bf16_f32 v87, v88, v94
	v_cvt_pk_bf16_f32 v88, v89, v90
	v_cvt_pk_bf16_f32 v89, v84, v91
	v_cvt_pk_bf16_f32 v90, v85, v86
	ds_bpermute_b32 v84, v163, v87
	ds_bpermute_b32 v85, v163, v88
	ds_bpermute_b32 v86, v163, v89
	ds_bpermute_b32 v87, v163, v90
	s_waitcnt lgkmcnt(0)
	global_store_dwordx4 v[146:147], v[84:87], off offset:256
.LBB0_1216:
	s_nop 1
	v_lshlrev_b64 v[84:85], 11, v[148:149]
	v_lshl_add_u64 v[86:87], v[84:85], 0, v[138:139]
	s_waitcnt lgkmcnt(7)
	v_lshlrev_b32_e32 v84, 16, v171
	v_add_f32_e32 v80, v80, v84
	v_and_b32_e32 v84, 0xffff0000, v171
	v_add_f32_e32 v84, v81, v84
	s_waitcnt lgkmcnt(6)
	v_lshlrev_b32_e32 v81, 16, v170
	v_add_f32_e32 v81, v82, v81
	v_and_b32_e32 v82, 0xffff0000, v170
	v_add_f32_e32 v83, v83, v82
	s_waitcnt lgkmcnt(5)
	v_lshlrev_b32_e32 v82, 16, v169
	v_add_f32_e32 v82, v76, v82
	v_and_b32_e32 v76, 0xffff0000, v169
	v_add_f32_e32 v85, v77, v76
	s_waitcnt lgkmcnt(4)
	v_lshlrev_b32_e32 v76, 16, v168
	v_add_f32_e32 v78, v78, v76
	v_and_b32_e32 v76, 0xffff0000, v168
	v_add_f32_e32 v79, v79, v76
	s_and_b64 vcc, exec, s[40:41]
	v_lshl_add_u64 v[76:77], v[86:87], 2, s[6:7]
	s_cbranch_vccnz .LBB0_1255
	ds_bpermute_b32 v86, v163, v80
	ds_bpermute_b32 v87, v163, v84
	ds_bpermute_b32 v88, v163, v81
	ds_bpermute_b32 v89, v163, v83
	ds_bpermute_b32 v90, v163, v82
	ds_bpermute_b32 v91, v163, v85
	ds_bpermute_b32 v92, v163, v78
	ds_bpermute_b32 v93, v163, v79
	s_waitcnt lgkmcnt(4)
	global_store_dwordx4 v[76:77], v[86:89], off
	s_waitcnt lgkmcnt(0)
	global_store_dwordx4 v[76:77], v[90:93], off offset:16
	s_cbranch_execnz .LBB0_1219
.LBB0_1218:
	v_cvt_pk_bf16_f32 v80, v80, v84
	v_cvt_pk_bf16_f32 v81, v81, v83
	v_cvt_pk_bf16_f32 v82, v82, v85
	v_cvt_pk_bf16_f32 v83, v78, v79
	ds_bpermute_b32 v78, v163, v80
	ds_bpermute_b32 v79, v163, v81
	ds_bpermute_b32 v80, v163, v82
	ds_bpermute_b32 v81, v163, v83
	s_waitcnt lgkmcnt(0)
	global_store_dwordx4 v[144:145], v[78:81], off
.LBB0_1219:
	s_waitcnt lgkmcnt(3)
	s_nop 0
	v_lshlrev_b32_e32 v78, 16, v167
	v_add_f32_e32 v72, v72, v78
	v_and_b32_e32 v78, 0xffff0000, v167
	v_add_f32_e32 v78, v73, v78
	s_waitcnt lgkmcnt(2)
	v_lshlrev_b32_e32 v73, 16, v166
	v_add_f32_e32 v73, v74, v73
	v_and_b32_e32 v74, 0xffff0000, v166
	v_add_f32_e32 v74, v75, v74
	s_waitcnt lgkmcnt(1)
	v_lshlrev_b32_e32 v75, 16, v165
	v_add_f32_e32 v68, v68, v75
	v_and_b32_e32 v75, 0xffff0000, v165
	v_add_f32_e32 v75, v69, v75
	s_waitcnt lgkmcnt(0)
	v_lshlrev_b32_e32 v69, 16, v141
	v_add_f32_e32 v69, v70, v69
	v_and_b32_e32 v70, 0xffff0000, v141
	s_and_b64 vcc, exec, s[40:41]
	v_add_f32_e32 v70, v71, v70
	s_cbranch_vccnz .LBB0_1256
	ds_bpermute_b32 v80, v163, v72
	ds_bpermute_b32 v81, v163, v78
	ds_bpermute_b32 v82, v163, v73
	ds_bpermute_b32 v83, v163, v74
	ds_bpermute_b32 v84, v163, v68
	ds_bpermute_b32 v85, v163, v75
	ds_bpermute_b32 v86, v163, v69
	ds_bpermute_b32 v87, v163, v70
	s_waitcnt lgkmcnt(4)
	global_store_dwordx4 v[76:77], v[80:83], off offset:512
	s_waitcnt lgkmcnt(0)
	global_store_dwordx4 v[76:77], v[84:87], off offset:528
	s_cbranch_execnz .LBB0_1222
.LBB0_1221:
	v_cvt_pk_bf16_f32 v71, v72, v78
	v_cvt_pk_bf16_f32 v72, v73, v74
	v_cvt_pk_bf16_f32 v73, v68, v75
	v_cvt_pk_bf16_f32 v74, v69, v70
	ds_bpermute_b32 v68, v163, v71
	ds_bpermute_b32 v69, v163, v72
	ds_bpermute_b32 v70, v163, v73
	ds_bpermute_b32 v71, v163, v74
	s_waitcnt lgkmcnt(0)
	global_store_dwordx4 v[144:145], v[68:71], off offset:256
.LBB0_1222:
	s_nop 1
	v_add_u32_e32 v68, 0x80, v140
	v_ashrrev_i32_e32 v69, 31, v68
	v_lshlrev_b64 v[128:129], 11, v[68:69]
	v_lshlrev_b64 v[68:69], 12, v[68:69]
	v_lshl_add_u64 v[78:79], v[142:143], 0, v[68:69]
	global_load_dwordx4 v[82:85], v[78:79], off
	global_load_dwordx4 v[86:89], v[78:79], off offset:256
	v_add_u32_e32 v80, 0x90, v140
	v_ashrrev_i32_e32 v81, 31, v80
	v_add_u32_e32 v76, 0xa0, v140
	v_lshlrev_b64 v[68:69], 12, v[80:81]
	v_ashrrev_i32_e32 v77, 31, v76
	v_lshl_add_u64 v[74:75], v[142:143], 0, v[68:69]
	v_lshlrev_b64 v[68:69], 12, v[76:77]
	v_lshl_add_u64 v[70:71], v[142:143], 0, v[68:69]
	v_add_u32_e32 v72, 0xb0, v140
	global_load_dwordx4 v[90:93], v[74:75], off
	global_load_dwordx4 v[94:97], v[74:75], off offset:256
	global_load_dwordx4 v[112:115], v[70:71], off
	global_load_dwordx4 v[116:119], v[70:71], off offset:256
	v_ashrrev_i32_e32 v73, 31, v72
	v_lshlrev_b64 v[68:69], 12, v[72:73]
	v_lshl_add_u64 v[68:69], v[142:143], 0, v[68:69]
	global_load_dwordx4 v[120:123], v[68:69], off
	global_load_dwordx4 v[124:127], v[68:69], off offset:256
	s_and_b64 vcc, exec, s[40:41]
	s_waitcnt vmcnt(7)
	ds_bpermute_b32 v130, v164, v82
	ds_bpermute_b32 v131, v164, v83
	ds_bpermute_b32 v140, v164, v84
	ds_bpermute_b32 v141, v164, v85
	s_waitcnt vmcnt(6)
	ds_bpermute_b32 v111, v164, v86
	ds_bpermute_b32 v110, v164, v87
	ds_bpermute_b32 v109, v164, v88
	ds_bpermute_b32 v108, v164, v89
	v_lshl_add_u64 v[82:83], v[128:129], 0, v[138:139]
	s_waitcnt vmcnt(5)
	ds_bpermute_b32 v107, v164, v90
	s_waitcnt vmcnt(3)
	ds_bpermute_b32 v99, v164, v112
	s_waitcnt lgkmcnt(9)
	v_lshlrev_b32_e32 v112, 16, v130
	v_add_f32_e32 v64, v64, v112
	v_and_b32_e32 v112, 0xffff0000, v130
	v_add_f32_e32 v112, v65, v112
	s_waitcnt lgkmcnt(8)
	v_lshlrev_b32_e32 v65, 16, v131
	v_add_f32_e32 v65, v66, v65
	v_and_b32_e32 v66, 0xffff0000, v131
	ds_bpermute_b32 v106, v164, v91
	ds_bpermute_b32 v105, v164, v92
	ds_bpermute_b32 v104, v164, v93
	ds_bpermute_b32 v103, v164, v94
	ds_bpermute_b32 v102, v164, v95
	ds_bpermute_b32 v101, v164, v96
	ds_bpermute_b32 v100, v164, v97
	ds_bpermute_b32 v98, v164, v113
	ds_bpermute_b32 v97, v164, v114
	ds_bpermute_b32 v96, v164, v115
	s_waitcnt vmcnt(2)
	ds_bpermute_b32 v95, v164, v116
	ds_bpermute_b32 v94, v164, v117
	ds_bpermute_b32 v93, v164, v118
	ds_bpermute_b32 v92, v164, v119
	s_waitcnt vmcnt(1)
	ds_bpermute_b32 v91, v164, v120
	ds_bpermute_b32 v90, v164, v121
	ds_bpermute_b32 v89, v164, v122
	ds_bpermute_b32 v88, v164, v123
	s_waitcnt vmcnt(0)
	ds_bpermute_b32 v87, v164, v124
	ds_bpermute_b32 v86, v164, v125
	ds_bpermute_b32 v85, v164, v126
	ds_bpermute_b32 v84, v164, v127
	v_add_f32_e32 v67, v67, v66
	s_waitcnt lgkmcnt(14)
	v_lshlrev_b32_e32 v66, 16, v140
	v_add_f32_e32 v66, v60, v66
	v_and_b32_e32 v60, 0xffff0000, v140
	v_add_f32_e32 v113, v61, v60
	v_lshlrev_b32_e32 v60, 16, v141
	v_add_f32_e32 v62, v62, v60
	v_and_b32_e32 v60, 0xffff0000, v141
	v_add_f32_e32 v63, v63, v60
	v_lshl_add_u64 v[60:61], v[82:83], 2, s[6:7]
	s_cbranch_vccnz .LBB0_1257
	ds_bpermute_b32 v114, v163, v64
	ds_bpermute_b32 v115, v163, v112
	ds_bpermute_b32 v116, v163, v65
	ds_bpermute_b32 v117, v163, v67
	ds_bpermute_b32 v118, v163, v66
	ds_bpermute_b32 v119, v163, v113
	ds_bpermute_b32 v120, v163, v62
	ds_bpermute_b32 v121, v163, v63
	s_waitcnt lgkmcnt(4)
	global_store_dwordx4 v[60:61], v[114:117], off
	s_waitcnt lgkmcnt(0)
	global_store_dwordx4 v[60:61], v[118:121], off offset:16
	s_cbranch_execnz .LBB0_1225
.LBB0_1224:
	v_cvt_pk_bf16_f32 v64, v64, v112
	v_cvt_pk_bf16_f32 v65, v65, v67
	v_cvt_pk_bf16_f32 v66, v66, v113
	v_cvt_pk_bf16_f32 v67, v62, v63
	ds_bpermute_b32 v62, v163, v64
	ds_bpermute_b32 v63, v163, v65
	ds_bpermute_b32 v64, v163, v66
	ds_bpermute_b32 v65, v163, v67
	s_waitcnt lgkmcnt(0)
	global_store_dwordx4 v[78:79], v[62:65], off
.LBB0_1225:
	s_nop 1
	v_lshlrev_b32_e32 v62, 16, v111
	v_add_f32_e32 v56, v56, v62
	v_and_b32_e32 v62, 0xffff0000, v111
	v_add_f32_e32 v62, v57, v62
	v_lshlrev_b32_e32 v57, 16, v110
	v_add_f32_e32 v57, v58, v57
	v_and_b32_e32 v58, 0xffff0000, v110
	v_add_f32_e32 v58, v59, v58
	v_lshlrev_b32_e32 v59, 16, v109
	v_add_f32_e32 v52, v52, v59
	v_and_b32_e32 v59, 0xffff0000, v109
	v_add_f32_e32 v59, v53, v59
	v_lshlrev_b32_e32 v53, 16, v108
	v_add_f32_e32 v53, v54, v53
	v_and_b32_e32 v54, 0xffff0000, v108
	s_and_b64 vcc, exec, s[40:41]
	v_add_f32_e32 v54, v55, v54
	s_cbranch_vccnz .LBB0_1258
	ds_bpermute_b32 v64, v163, v56
	ds_bpermute_b32 v65, v163, v62
	ds_bpermute_b32 v66, v163, v57
	ds_bpermute_b32 v67, v163, v58
	ds_bpermute_b32 v108, v163, v52
	ds_bpermute_b32 v109, v163, v59
	ds_bpermute_b32 v110, v163, v53
	ds_bpermute_b32 v111, v163, v54
	s_waitcnt lgkmcnt(4)
	global_store_dwordx4 v[60:61], v[64:67], off offset:512
	s_waitcnt lgkmcnt(0)
	global_store_dwordx4 v[60:61], v[108:111], off offset:528
	s_cbranch_execnz .LBB0_1228
.LBB0_1227:
	v_cvt_pk_bf16_f32 v55, v56, v62
	v_cvt_pk_bf16_f32 v56, v57, v58
	v_cvt_pk_bf16_f32 v57, v52, v59
	v_cvt_pk_bf16_f32 v58, v53, v54
	ds_bpermute_b32 v52, v163, v55
	ds_bpermute_b32 v53, v163, v56
	ds_bpermute_b32 v54, v163, v57
	ds_bpermute_b32 v55, v163, v58
	s_waitcnt lgkmcnt(0)
	global_store_dwordx4 v[78:79], v[52:55], off offset:256
.LBB0_1228:
	s_nop 1
	v_lshlrev_b64 v[52:53], 11, v[80:81]
	v_lshl_add_u64 v[54:55], v[52:53], 0, v[138:139]
	v_lshlrev_b32_e32 v52, 16, v107
	v_add_f32_e32 v48, v48, v52
	v_and_b32_e32 v52, 0xffff0000, v107
	v_add_f32_e32 v52, v49, v52
	v_lshlrev_b32_e32 v49, 16, v106
	v_add_f32_e32 v49, v50, v49
	v_and_b32_e32 v50, 0xffff0000, v106
	v_add_f32_e32 v51, v51, v50
	v_lshlrev_b32_e32 v50, 16, v105
	v_add_f32_e32 v50, v44, v50
	v_and_b32_e32 v44, 0xffff0000, v105
	v_add_f32_e32 v53, v45, v44
	v_lshlrev_b32_e32 v44, 16, v104
	v_add_f32_e32 v46, v46, v44
	v_and_b32_e32 v44, 0xffff0000, v104
	v_add_f32_e32 v47, v47, v44
	s_and_b64 vcc, exec, s[40:41]
	v_lshl_add_u64 v[44:45], v[54:55], 2, s[6:7]
	s_cbranch_vccnz .LBB0_1259
	ds_bpermute_b32 v54, v163, v48
	ds_bpermute_b32 v55, v163, v52
	ds_bpermute_b32 v56, v163, v49
	ds_bpermute_b32 v57, v163, v51
	ds_bpermute_b32 v58, v163, v50
	ds_bpermute_b32 v59, v163, v53
	ds_bpermute_b32 v60, v163, v46
	ds_bpermute_b32 v61, v163, v47
	s_waitcnt lgkmcnt(4)
	global_store_dwordx4 v[44:45], v[54:57], off
	s_waitcnt lgkmcnt(0)
	global_store_dwordx4 v[44:45], v[58:61], off offset:16
	s_cbranch_execnz .LBB0_1231
.LBB0_1230:
	v_cvt_pk_bf16_f32 v48, v48, v52
	v_cvt_pk_bf16_f32 v49, v49, v51
	v_cvt_pk_bf16_f32 v50, v50, v53
	v_cvt_pk_bf16_f32 v51, v46, v47
	ds_bpermute_b32 v46, v163, v48
	ds_bpermute_b32 v47, v163, v49
	ds_bpermute_b32 v48, v163, v50
	ds_bpermute_b32 v49, v163, v51
	s_waitcnt lgkmcnt(0)
	global_store_dwordx4 v[74:75], v[46:49], off
.LBB0_1231:
	s_nop 1
	v_lshlrev_b32_e32 v46, 16, v103
	v_add_f32_e32 v40, v40, v46
	v_and_b32_e32 v46, 0xffff0000, v103
	v_add_f32_e32 v46, v41, v46
	v_lshlrev_b32_e32 v41, 16, v102
	v_add_f32_e32 v41, v42, v41
	v_and_b32_e32 v42, 0xffff0000, v102
	v_add_f32_e32 v42, v43, v42
	v_lshlrev_b32_e32 v43, 16, v101
	v_add_f32_e32 v36, v36, v43
	v_and_b32_e32 v43, 0xffff0000, v101
	v_add_f32_e32 v43, v37, v43
	v_lshlrev_b32_e32 v37, 16, v100
	v_add_f32_e32 v37, v38, v37
	v_and_b32_e32 v38, 0xffff0000, v100
	s_and_b64 vcc, exec, s[40:41]
	v_add_f32_e32 v38, v39, v38
	s_cbranch_vccnz .LBB0_1260
	ds_bpermute_b32 v48, v163, v40
	ds_bpermute_b32 v49, v163, v46
	ds_bpermute_b32 v50, v163, v41
	ds_bpermute_b32 v51, v163, v42
	ds_bpermute_b32 v52, v163, v36
	ds_bpermute_b32 v53, v163, v43
	ds_bpermute_b32 v54, v163, v37
	ds_bpermute_b32 v55, v163, v38
	s_waitcnt lgkmcnt(4)
	global_store_dwordx4 v[44:45], v[48:51], off offset:512
	s_waitcnt lgkmcnt(0)
	global_store_dwordx4 v[44:45], v[52:55], off offset:528
	s_cbranch_execnz .LBB0_1234
.LBB0_1233:
	v_cvt_pk_bf16_f32 v39, v40, v46
	v_cvt_pk_bf16_f32 v40, v41, v42
	v_cvt_pk_bf16_f32 v41, v36, v43
	v_cvt_pk_bf16_f32 v42, v37, v38
	ds_bpermute_b32 v36, v163, v39
	ds_bpermute_b32 v37, v163, v40
	ds_bpermute_b32 v38, v163, v41
	ds_bpermute_b32 v39, v163, v42
	s_waitcnt lgkmcnt(0)
	global_store_dwordx4 v[74:75], v[36:39], off offset:256
.LBB0_1234:
	s_nop 1
	v_lshlrev_b64 v[36:37], 11, v[76:77]
	v_lshl_add_u64 v[38:39], v[36:37], 0, v[138:139]
	v_lshlrev_b32_e32 v36, 16, v99
	v_add_f32_e32 v30, v30, v36
	v_and_b32_e32 v36, 0xffff0000, v99
	v_add_f32_e32 v36, v31, v36
	v_lshlrev_b32_e32 v31, 16, v98
	v_add_f32_e32 v31, v32, v31
	v_and_b32_e32 v32, 0xffff0000, v98
	v_add_f32_e32 v33, v33, v32
	s_waitcnt lgkmcnt(13)
	v_lshlrev_b32_e32 v32, 16, v97
	v_add_f32_e32 v32, v26, v32
	v_and_b32_e32 v26, 0xffff0000, v97
	v_add_f32_e32 v37, v27, v26
	s_waitcnt lgkmcnt(12)
	v_lshlrev_b32_e32 v26, 16, v96
	v_add_f32_e32 v28, v28, v26
	v_and_b32_e32 v26, 0xffff0000, v96
	v_add_f32_e32 v29, v29, v26
	s_and_b64 vcc, exec, s[40:41]
	v_lshl_add_u64 v[26:27], v[38:39], 2, s[6:7]
	s_cbranch_vccnz .LBB0_1261
	ds_bpermute_b32 v38, v163, v30
	ds_bpermute_b32 v39, v163, v36
	ds_bpermute_b32 v40, v163, v31
	ds_bpermute_b32 v41, v163, v33
	ds_bpermute_b32 v42, v163, v32
	ds_bpermute_b32 v43, v163, v37
	ds_bpermute_b32 v44, v163, v28
	ds_bpermute_b32 v45, v163, v29
	s_waitcnt lgkmcnt(4)
	global_store_dwordx4 v[26:27], v[38:41], off
	s_waitcnt lgkmcnt(0)
	global_store_dwordx4 v[26:27], v[42:45], off offset:16
	s_cbranch_execnz .LBB0_1237
.LBB0_1236:
	v_cvt_pk_bf16_f32 v30, v30, v36
	v_cvt_pk_bf16_f32 v31, v31, v33
	v_cvt_pk_bf16_f32 v32, v32, v37
	v_cvt_pk_bf16_f32 v33, v28, v29
	ds_bpermute_b32 v28, v163, v30
	ds_bpermute_b32 v29, v163, v31
	ds_bpermute_b32 v30, v163, v32
	ds_bpermute_b32 v31, v163, v33
	s_waitcnt lgkmcnt(0)
	global_store_dwordx4 v[70:71], v[28:31], off
.LBB0_1237:
	s_waitcnt lgkmcnt(11)
	s_nop 0
	v_lshlrev_b32_e32 v28, 16, v95
	v_add_f32_e32 v22, v22, v28
	v_and_b32_e32 v28, 0xffff0000, v95
	v_add_f32_e32 v28, v23, v28
	s_waitcnt lgkmcnt(10)
	v_lshlrev_b32_e32 v23, 16, v94
	v_add_f32_e32 v23, v24, v23
	v_and_b32_e32 v24, 0xffff0000, v94
	v_add_f32_e32 v24, v25, v24
	s_waitcnt lgkmcnt(9)
	v_lshlrev_b32_e32 v25, 16, v93
	v_add_f32_e32 v18, v18, v25
	v_and_b32_e32 v25, 0xffff0000, v93
	v_add_f32_e32 v25, v19, v25
	s_waitcnt lgkmcnt(8)
	v_lshlrev_b32_e32 v19, 16, v92
	v_add_f32_e32 v19, v20, v19
	v_and_b32_e32 v20, 0xffff0000, v92
	s_and_b64 vcc, exec, s[40:41]
	v_add_f32_e32 v20, v21, v20
	s_cbranch_vccnz .LBB0_1262
	ds_bpermute_b32 v30, v163, v22
	ds_bpermute_b32 v31, v163, v28
	ds_bpermute_b32 v32, v163, v23
	ds_bpermute_b32 v33, v163, v24
	ds_bpermute_b32 v36, v163, v18
	ds_bpermute_b32 v37, v163, v25
	ds_bpermute_b32 v38, v163, v19
	ds_bpermute_b32 v39, v163, v20
	s_waitcnt lgkmcnt(4)
	global_store_dwordx4 v[26:27], v[30:33], off offset:512
	s_waitcnt lgkmcnt(0)
	global_store_dwordx4 v[26:27], v[36:39], off offset:528
	s_cbranch_execnz .LBB0_1240
.LBB0_1239:
	v_cvt_pk_bf16_f32 v21, v22, v28
	v_cvt_pk_bf16_f32 v22, v23, v24
	v_cvt_pk_bf16_f32 v23, v18, v25
	v_cvt_pk_bf16_f32 v24, v19, v20
	ds_bpermute_b32 v18, v163, v21
	ds_bpermute_b32 v19, v163, v22
	ds_bpermute_b32 v20, v163, v23
	ds_bpermute_b32 v21, v163, v24
	s_waitcnt lgkmcnt(0)
	global_store_dwordx4 v[70:71], v[18:21], off offset:256
.LBB0_1240:
	s_nop 1
	v_lshlrev_b64 v[18:19], 11, v[72:73]
	v_lshl_add_u64 v[20:21], v[18:19], 0, v[138:139]
	s_waitcnt lgkmcnt(7)
	v_lshlrev_b32_e32 v18, 16, v91
	v_add_f32_e32 v14, v14, v18
	v_and_b32_e32 v18, 0xffff0000, v91
	v_add_f32_e32 v18, v15, v18
	s_waitcnt lgkmcnt(6)
	v_lshlrev_b32_e32 v15, 16, v90
	v_add_f32_e32 v15, v16, v15
	v_and_b32_e32 v16, 0xffff0000, v90
	v_add_f32_e32 v17, v17, v16
	s_waitcnt lgkmcnt(5)
	v_lshlrev_b32_e32 v16, 16, v89
	v_add_f32_e32 v16, v10, v16
	v_and_b32_e32 v10, 0xffff0000, v89
	v_add_f32_e32 v19, v11, v10
	s_waitcnt lgkmcnt(4)
	v_lshlrev_b32_e32 v10, 16, v88
	v_add_f32_e32 v12, v12, v10
	v_and_b32_e32 v10, 0xffff0000, v88
	v_add_f32_e32 v13, v13, v10
	s_and_b64 vcc, exec, s[40:41]
	v_lshl_add_u64 v[10:11], v[20:21], 2, s[6:7]
	s_cbranch_vccnz .LBB0_1263
	ds_bpermute_b32 v20, v163, v14
	ds_bpermute_b32 v21, v163, v18
	ds_bpermute_b32 v22, v163, v15
	ds_bpermute_b32 v23, v163, v17
	ds_bpermute_b32 v24, v163, v16
	ds_bpermute_b32 v25, v163, v19
	ds_bpermute_b32 v26, v163, v12
	ds_bpermute_b32 v27, v163, v13
	s_waitcnt lgkmcnt(4)
	global_store_dwordx4 v[10:11], v[20:23], off
	s_waitcnt lgkmcnt(0)
	global_store_dwordx4 v[10:11], v[24:27], off offset:16
	s_cbranch_execnz .LBB0_1243
.LBB0_1242:
	v_cvt_pk_bf16_f32 v14, v14, v18
	v_cvt_pk_bf16_f32 v15, v15, v17
	v_cvt_pk_bf16_f32 v16, v16, v19
	v_cvt_pk_bf16_f32 v17, v12, v13
	ds_bpermute_b32 v12, v163, v14
	ds_bpermute_b32 v13, v163, v15
	ds_bpermute_b32 v14, v163, v16
	ds_bpermute_b32 v15, v163, v17
	s_waitcnt lgkmcnt(0)
	global_store_dwordx4 v[68:69], v[12:15], off
.LBB0_1243:
	s_waitcnt lgkmcnt(3)
	s_nop 0
	v_lshlrev_b32_e32 v12, 16, v87
	v_add_f32_e32 v6, v6, v12
	v_and_b32_e32 v12, 0xffff0000, v87
	v_add_f32_e32 v12, v7, v12
	s_waitcnt lgkmcnt(2)
	v_lshlrev_b32_e32 v7, 16, v86
	v_add_f32_e32 v7, v8, v7
	v_and_b32_e32 v8, 0xffff0000, v86
	v_add_f32_e32 v8, v9, v8
	s_waitcnt lgkmcnt(1)
	v_lshlrev_b32_e32 v9, 16, v85
	v_add_f32_e32 v2, v2, v9
	v_and_b32_e32 v9, 0xffff0000, v85
	v_add_f32_e32 v9, v3, v9
	s_waitcnt lgkmcnt(0)
	v_lshlrev_b32_e32 v3, 16, v84
	v_add_f32_e32 v3, v4, v3
	v_and_b32_e32 v4, 0xffff0000, v84
	s_and_b64 vcc, exec, s[40:41]
	v_add_f32_e32 v4, v5, v4
	s_cbranch_vccnz .LBB0_1264
	ds_bpermute_b32 v14, v163, v6
	ds_bpermute_b32 v15, v163, v12
	ds_bpermute_b32 v16, v163, v7
	ds_bpermute_b32 v17, v163, v8
	ds_bpermute_b32 v18, v163, v2
	ds_bpermute_b32 v19, v163, v9
	ds_bpermute_b32 v20, v163, v3
	ds_bpermute_b32 v21, v163, v4
	s_waitcnt lgkmcnt(4)
	global_store_dwordx4 v[10:11], v[14:17], off offset:512
	s_waitcnt lgkmcnt(0)
	global_store_dwordx4 v[10:11], v[18:21], off offset:528
	s_cbranch_execnz .LBB0_1246
.LBB0_1245:
	v_cvt_pk_bf16_f32 v5, v6, v12
	v_cvt_pk_bf16_f32 v6, v7, v8
	v_cvt_pk_bf16_f32 v7, v2, v9
	v_cvt_pk_bf16_f32 v8, v3, v4
	ds_bpermute_b32 v2, v163, v5
	ds_bpermute_b32 v3, v163, v6
	ds_bpermute_b32 v4, v163, v7
	ds_bpermute_b32 v5, v163, v8
	s_waitcnt lgkmcnt(0)
	global_store_dwordx4 v[68:69], v[2:5], off offset:256
